# RMSNorm row sums-of-squares produced by RESID epilogue (16 partials per row via dot2c+DPP) and read back by the next fused-norm GEMM instead of Gram MFMAs
# speedup vs baseline: 1.0179x; 1.0179x over previous
; DI float shx(float v, int mask, int lane) { return __int_as_float(__builtin_amdgcn_ds_bpermute((lane ^ mask) << 2, __float_as_int(v))); }
; DI void gemm_run(const GemmCfg c, char* smem, float* const g_h, u16* const g_hb, float* const g_out, const int final_out) {
;     ...
;   for (int slot = Lb; slot < ntiles; slot += G) {
;     const int sr = slot / srow, idx = slot - sr * srow;
;     const int tm = sr < 8 ? sr * 8 + (idx & 7) : 64;
;     const int tn = sr < 8 ? (idx >> 3) : idx;
;     const u16* Ag = c.A + (size_t)(tm * 256 + lrow) * c.lda + tn * c.a_koff_tn + lch * 8;
;     const u16* Bg = c.Bt + (size_t)(tn * 256 + lrow) * K + lch * 8;
;     const size_t astep = (size_t)64 * c.lda, bstep = (size_t)64 * K;
;     ...
;     if (c.use_rs) {
; #pragma unroll
;       for (int i = 0; i < 4; ++i) {
;         float s_ = ss[i];
;         s_ += shx(s_, 1, lane); s_ += shx(s_, 2, lane); s_ += shx(s_, 4, lane);
;         if (lch == 0) s_rowss[lrow + 64 * i] = s_;
;       }
.LBB0_110:
	s_abs_i32 s1, s48
	s_mul_hi_u32 s4, s1, s69
	s_mul_i32 s5, s4, s30
	s_ashr_i32 s0, s48, 31
	s_sub_i32 s1, s1, s5
	s_xor_b32 s0, s0, s63
	s_add_i32 s5, s4, 1
	s_sub_i32 s6, s1, s30
	s_cmp_ge_u32 s1, s30
	s_cselect_b32 s4, s5, s4
	s_cselect_b32 s1, s6, s1
	s_add_i32 s5, s4, 1
	s_cmp_ge_u32 s1, s30
	s_cselect_b32 s1, s5, s4
	s_xor_b32 s1, s1, s0
	s_sub_i32 s0, s1, s0
	s_mul_i32 s1, s0, s65
	s_sub_i32 s1, s48, s1
	s_lshl_b32 s4, s0, 3
	s_and_b32 s5, s48, 7
	s_or_b32 s4, s4, s5
	s_ashr_i32 s5, s1, 3
	s_cmp_lt_i32 s0, 8
	s_cselect_b32 s78, s4, 64
	s_waitcnt lgkmcnt(0)
	s_cselect_b32 s49, s5, s1
	v_lshrrev_b32_e32 v128, 3, v185
	v_and_b32_e32 v129, 7, v185
	v_xor_b32_e32 v129, v129, v128
	v_lshlrev_b32_e32 v129, 4, v129
	s_lshl_b32 s0, s62, 1
	v_mul_lo_u32 v130, v128, s0
	s_lshl_b32 s1, s62, 4
	v_add_u32_e32 v130, v130, v129
	v_add_u32_e32 v131, s1, v130
	v_add_u32_e32 v132, s1, v131
	v_add_u32_e32 v133, s1, v132
	s_lshl_b32 s0, s60, 1
	v_mul_lo_u32 v134, v128, s0
	s_lshl_b32 s1, s60, 4
	v_add_u32_e32 v134, v134, v129
	v_add_u32_e32 v135, s1, v134
	v_add_u32_e32 v136, s1, v135
	v_add_u32_e32 v137, s1, v136
	s_lshl_b32 s8, s75, 5
	s_add_i32 s8, s8, s86
	s_lshl_b32 s0, s78, 8
	s_add_i32 s0, s0, s8
	s_mul_i32 s0, s0, s62
	s_mul_i32 s1, s49, s2
	s_add_i32 s0, s0, s1
	s_lshl_b32 s0, s0, 1
	s_add_u32 s4, s54, s0
	s_addc_u32 s5, s55, 0
	v_readlane_b32 s6, v255, 5
	v_readlane_b32 s7, v255, 6
	s_lshl_b32 s0, s49, 8
	s_add_i32 s0, s0, s8
	s_mul_i32 s0, s0, s60
	s_lshl_b32 s0, s0, 1
	s_add_u32 s6, s6, s0
	s_addc_u32 s7, s7, 0
	s_lshl_b32 s8, s8, 7
	s_add_i32 s9, s75, 1
	s_and_b32 s9, s9, s88
	s_mov_b32 s1, 0
	s_cmp_eq_u32 s9, 0
	s_cbranch_scc1 .Lgemm_rsp_skip
	s_cmpk_lg_i32 s62, 0x400
	s_cbranch_scc1 .Lgemm_rsp_skip
	s_cmp_gt_u32 s78, 63
	s_cbranch_scc1 .Lgemm_rsp_skip
	v_readlane_b32 s0, v254, 38
	v_readlane_b32 s1, v254, 34
	s_nop 1
	s_add_i32 s1, s1, -1
	s_or_b32 s0, s0, s1
	s_mov_b32 s1, 0
	s_cmp_eq_u32 s0, 0
	s_cbranch_scc1 .Lgemm_rsp_skip
	v_readlane_b32 s0, v255, 3
	v_readlane_b32 s1, v255, 4
	s_nop 1
	s_add_u32 s0, s0, 0x11f69000
	s_addc_u32 s1, s1, 0
	s_lshl_b32 s9, s78, 14
	s_add_u32 s0, s0, s9
	s_addc_u32 s1, s1, 0
	v_lshlrev_b32_e32 v221, 5, v210
	global_load_dwordx4 v[156:159], v221, s[0:1]
	global_load_dwordx2 v[208:209], v221, s[0:1] offset:16
	global_load_dwordx2 v[218:219], v221, s[0:1] offset:24
	s_mov_b32 s9, 0
	s_mov_b32 s1, 1
.Lgemm_rsp_skip:
	s_nop 0
	v_writelane_b32 v255, s1, 50
	s_barrier
	s_cmp_lt_u32 s8, 0x4000
	s_cbranch_scc0 .Lgemm_rz_skip
	s_cmp_eq_u32 s9, 0
	s_cbranch_scc1 .Lgemm_rz_skip
	v_lshlrev_b32_e32 v128, 2, v185
	s_lshr_b32 s1, s8, 4
	s_add_i32 s1, s1, 0x24000
	v_mov_b32_e32 v129, 0
	v_add_u32_e32 v128, s1, v128
	ds_write_b32 v128, v129
; DI void lds_barrier() { asm volatile("s_waitcnt lgkmcnt(0)\n\ts_barrier" ::: "memory"); }
; #define G_LOAD(RA, RB, KT) { size_t as_ = astep, bs_ = bstep; asm volatile("" : "+s"(as_), "+s"(bs_)); \
;       _Pragma("unroll") for (int i = 0; i < 4; ++i) { RA[i] = *(const u32x4*)(Ag + i * as_ + (KT) * 64); RB[i] = *(const u32x4*)(Bg + i * bs_ + (KT) * 64); } }
; DI void gemm_run(const GemmCfg c, char* smem, float* const g_h, u16* const g_hb, float* const g_out, const int final_out) {
;     ...
;     f32x16 acc[2][4];
; #pragma unroll
;     for (int a = 0; a < 2; ++a)
; #pragma unroll
;       for (int b = 0; b < 4; ++b)
; #pragma unroll
;         for (int i = 0; i < 16; ++i) acc[a][b][i] = 0.f;
;     float ss[4] = {0.f, 0.f, 0.f, 0.f};
;     u32x4 ra0[4], rb0[4];
;     ...
;     G_LOAD(ra0, rb0, 0);
;     __syncthreads();
;     G_STORE(ra0, rb0, 0);
;     G_LOAD(ra0, rb0, 1);
;     lds_barrier();
.Lgemm_rz_skip:
	s_add_u32 m0, s8, 0x0
	s_nop 0
	global_load_lds_dwordx4 v130, s[4:5]
	s_add_u32 m0, s8, 0x12000
	s_nop 0
	global_load_lds_dwordx4 v134, s[6:7]
	s_add_u32 m0, s8, 0x400
	s_nop 0
	global_load_lds_dwordx4 v131, s[4:5]
	s_add_u32 m0, s8, 0x12400
	s_nop 0
	global_load_lds_dwordx4 v135, s[6:7]
	s_add_u32 m0, s8, 0x800
	s_nop 0
	global_load_lds_dwordx4 v132, s[4:5]
	s_add_u32 m0, s8, 0x12800
	s_nop 0
	global_load_lds_dwordx4 v136, s[6:7]
	s_add_u32 m0, s8, 0xc00
	s_nop 0
	global_load_lds_dwordx4 v133, s[4:5]
	s_add_u32 m0, s8, 0x12c00
	s_nop 0
	global_load_lds_dwordx4 v137, s[6:7]
	s_add_u32 s4, s4, 0x80
	s_addc_u32 s5, s5, 0
	s_add_u32 s6, s6, 0x80
	s_addc_u32 s7, s7, 0
	s_add_u32 m0, s8, 0x9000
	s_nop 0
	global_load_lds_dwordx4 v130, s[4:5]
	s_add_u32 m0, s8, 0x1b000
	s_nop 0
	global_load_lds_dwordx4 v134, s[6:7]
	s_add_u32 m0, s8, 0x9400
	s_nop 0
	global_load_lds_dwordx4 v131, s[4:5]
	s_add_u32 m0, s8, 0x1b400
	s_nop 0
	global_load_lds_dwordx4 v135, s[6:7]
	s_add_u32 m0, s8, 0x9800
	s_nop 0
	global_load_lds_dwordx4 v132, s[4:5]
	s_add_u32 m0, s8, 0x1b800
	s_nop 0
	global_load_lds_dwordx4 v136, s[6:7]
	s_add_u32 m0, s8, 0x9c00
	s_nop 0
	global_load_lds_dwordx4 v133, s[4:5]
	s_add_u32 m0, s8, 0x1bc00
	s_nop 0
	global_load_lds_dwordx4 v137, s[6:7]
	s_add_u32 s4, s4, 0x80
	s_addc_u32 s5, s5, 0
	s_add_u32 s6, s6, 0x80
	s_addc_u32 s7, s7, 0
	v_mov_b32_e32 v0, 0
	v_mov_b32_e32 v1, 0
	v_mov_b32_e32 v2, 0
	v_mov_b32_e32 v3, 0
	v_mov_b32_e32 v4, 0
	v_mov_b32_e32 v5, 0
	v_mov_b32_e32 v6, 0
	v_mov_b32_e32 v7, 0
	v_mov_b32_e32 v8, 0
	v_mov_b32_e32 v9, 0
	v_mov_b32_e32 v10, 0
	v_mov_b32_e32 v11, 0
	v_mov_b32_e32 v12, 0
	v_mov_b32_e32 v13, 0
	v_mov_b32_e32 v14, 0
	v_mov_b32_e32 v15, 0
	v_mov_b32_e32 v16, 0
	v_mov_b32_e32 v17, 0
	v_mov_b32_e32 v18, 0
	v_mov_b32_e32 v19, 0
	v_mov_b32_e32 v20, 0
	v_mov_b32_e32 v21, 0
	v_mov_b32_e32 v22, 0
	v_mov_b32_e32 v23, 0
	v_mov_b32_e32 v24, 0
	v_mov_b32_e32 v25, 0
	v_mov_b32_e32 v26, 0
	v_mov_b32_e32 v27, 0
	v_mov_b32_e32 v28, 0
	v_mov_b32_e32 v29, 0
	v_mov_b32_e32 v30, 0
	v_mov_b32_e32 v31, 0
	v_mov_b32_e32 v32, 0
	v_mov_b32_e32 v33, 0
	v_mov_b32_e32 v34, 0
	v_mov_b32_e32 v35, 0
	v_mov_b32_e32 v36, 0
	v_mov_b32_e32 v37, 0
	v_mov_b32_e32 v38, 0
	v_mov_b32_e32 v39, 0
	v_mov_b32_e32 v40, 0
	v_mov_b32_e32 v41, 0
	v_mov_b32_e32 v42, 0
	v_mov_b32_e32 v43, 0
	v_mov_b32_e32 v44, 0
	v_mov_b32_e32 v45, 0
	v_mov_b32_e32 v46, 0
	v_mov_b32_e32 v47, 0
	v_mov_b32_e32 v48, 0
	v_mov_b32_e32 v49, 0
	v_mov_b32_e32 v50, 0
	v_mov_b32_e32 v51, 0
	v_mov_b32_e32 v52, 0
	v_mov_b32_e32 v53, 0
	v_mov_b32_e32 v54, 0
	v_mov_b32_e32 v55, 0
	v_mov_b32_e32 v56, 0
	v_mov_b32_e32 v57, 0
	v_mov_b32_e32 v58, 0
	v_mov_b32_e32 v59, 0
	v_mov_b32_e32 v60, 0
	v_mov_b32_e32 v61, 0
	v_mov_b32_e32 v62, 0
	v_mov_b32_e32 v63, 0
	v_mov_b32_e32 v64, 0
	v_mov_b32_e32 v65, 0
	v_mov_b32_e32 v66, 0
	v_mov_b32_e32 v67, 0
	v_mov_b32_e32 v68, 0
	v_mov_b32_e32 v69, 0
	v_mov_b32_e32 v70, 0
	v_mov_b32_e32 v71, 0
	v_mov_b32_e32 v72, 0
	v_mov_b32_e32 v73, 0
	v_mov_b32_e32 v74, 0
	v_mov_b32_e32 v75, 0
	v_mov_b32_e32 v76, 0
	v_mov_b32_e32 v77, 0
	v_mov_b32_e32 v78, 0
	v_mov_b32_e32 v79, 0
	v_mov_b32_e32 v80, 0
	v_mov_b32_e32 v81, 0
	v_mov_b32_e32 v82, 0
	v_mov_b32_e32 v83, 0
	v_mov_b32_e32 v84, 0
	v_mov_b32_e32 v85, 0
	v_mov_b32_e32 v86, 0
	v_mov_b32_e32 v87, 0
	v_mov_b32_e32 v88, 0
	v_mov_b32_e32 v89, 0
	v_mov_b32_e32 v90, 0
	v_mov_b32_e32 v91, 0
	v_mov_b32_e32 v92, 0
	v_mov_b32_e32 v93, 0
	v_mov_b32_e32 v94, 0
	v_mov_b32_e32 v95, 0
	v_mov_b32_e32 v96, 0
	v_mov_b32_e32 v97, 0
	v_mov_b32_e32 v98, 0
	v_mov_b32_e32 v99, 0
	v_mov_b32_e32 v100, 0
	v_mov_b32_e32 v101, 0
	v_mov_b32_e32 v102, 0
	v_mov_b32_e32 v103, 0
	v_mov_b32_e32 v104, 0
	v_mov_b32_e32 v105, 0
	v_mov_b32_e32 v106, 0
	v_mov_b32_e32 v107, 0
	v_mov_b32_e32 v108, 0
	v_mov_b32_e32 v109, 0
	v_mov_b32_e32 v110, 0
	v_mov_b32_e32 v111, 0
	v_mov_b32_e32 v112, 0
	v_mov_b32_e32 v113, 0
	v_mov_b32_e32 v114, 0
	v_mov_b32_e32 v115, 0
	v_mov_b32_e32 v116, 0
	v_mov_b32_e32 v117, 0
	v_mov_b32_e32 v118, 0
	v_mov_b32_e32 v119, 0
	v_mov_b32_e32 v120, 0
	v_mov_b32_e32 v121, 0
	v_mov_b32_e32 v122, 0
	v_mov_b32_e32 v123, 0
	v_mov_b32_e32 v124, 0
	v_mov_b32_e32 v125, 0
	v_mov_b32_e32 v126, 0
	v_mov_b32_e32 v127, 0
	v_mov_b32_e32 v199, 0
	v_mov_b32_e32 v198, 0
	v_mov_b32_e32 v171, 0
	v_mov_b32_e32 v164, 0
	v_mov_b32_e32 v140, 0
	v_mov_b32_e32 v141, 0
	v_mov_b32_e32 v142, 0
	v_mov_b32_e32 v143, 0
	v_mov_b32_e32 v144, 0
	v_mov_b32_e32 v145, 0
	v_mov_b32_e32 v146, 0
	v_mov_b32_e32 v147, 0
	v_mov_b32_e32 v148, 0
	v_mov_b32_e32 v149, 0
	v_mov_b32_e32 v150, 0
	v_mov_b32_e32 v151, 0
	v_mov_b32_e32 v152, 0
	v_mov_b32_e32 v153, 0
	v_mov_b32_e32 v154, 0
	v_mov_b32_e32 v155, 0
	s_waitcnt vmcnt(8)
	s_mov_b32 s1, 0
	s_add_i32 s0, s68, 3
	s_barrier
	ds_read_b128 v[160:163], v194
	ds_read_b128 v[176:179], v194 offset:2048
	ds_read_b128 v[180:183], v194 offset:4096
	ds_read_b128 v[204:207], v195
	ds_read_b128 v[222:225], v195 offset:2048
	ds_read_b128 v[226:229], v195 offset:4096
	ds_read_b128 v[230:233], v195 offset:6144
	ds_read_b128 v[234:237], v195 offset:8192
	ds_read_b128 v[238:241], v195 offset:10240
	ds_read_b128 v[242:245], v195 offset:12288
	ds_read_b128 v[246:249], v195 offset:14336
	ds_read_b128 v[200:203], v194 offset:6144
	s_cmp_ge_u32 s8, 0x4000
	s_cbranch_scc1 .Lgemm_disp_late
	s_cmp_eq_u32 s9, 0
	s_cbranch_scc1 .Lgemm_kloop_n
	s_cmp_eq_u32 s9, 2
	s_cbranch_scc1 .Lgemm_kloop_r1e
	s_branch .LBB0_112

; DI float shx(float v, int mask, int lane) { return __int_as_float(__builtin_amdgcn_ds_bpermute((lane ^ mask) << 2, __float_as_int(v))); }
; DI int crow(int i, int hh) { return (i & 3) + 8 * (i >> 2) + 4 * hh; }
; DI void epi_slab(const GemmCfg c, const f32x16 (&acc)[4], float* sW, const float* rss, const size_t row0, const int g, const int lane,
;                  float* const g_h, u16* const g_hb, float* const g_out, const int final_out) {
;     ...
; #pragma unroll
;   for (int nb = 0; nb < 4; ++nb)
; #pragma unroll
;     for (int i = 0; i < 16; ++i) sW[crow(i, hh) * 132 + nb * 32 + l31] = acc[nb][i];
;   asm volatile("s_waitcnt lgkmcnt(0)" ::: "memory");
; DI void gemm_run(const GemmCfg c, char* smem, float* const g_h, u16* const g_hb, float* const g_out, const int final_out) {
;     ...
;     if (c.use_rs) {
; #pragma unroll
;       for (int i = 0; i < 4; ++i) {
;         float s_ = ss[i];
;         s_ += shx(s_, 1, lane); s_ += shx(s_, 2, lane); s_ += shx(s_, 4, lane);
;         if (lch == 0) s_rowss[lrow + 64 * i] = s_;
;       }
;     }
;     __syncthreads();
; #pragma unroll
;     for (int mb = 0; mb < 2; ++mb) {
;       const size_t row0 = (size_t)tm * 256 + wm * 64 + mb * 32;
;       if (row0 < (size_t)M) epi_slab(c, acc[mb], sW, s_rowss + wm * 64 + mb * 32, row0, tn * 2 + wn, lane, g_h, g_hb, g_out, final_out);
.Lgemm_kdone:
	s_waitcnt lgkmcnt(0)
	v_readlane_b32 s8, v255, 50
	s_nop 1
	s_cmp_eq_u32 s8, 0
	s_cbranch_scc1 .Lgemm_rsp_done
	s_waitcnt vmcnt(0)
	v_add_f32_e32 v156, v156, v157
	v_add_f32_e32 v158, v158, v159
	v_add_f32_e32 v208, v208, v209
	v_add_f32_e32 v218, v218, v219
	v_add_f32_e32 v156, v156, v158
	v_add_f32_e32 v208, v208, v218
	v_add_f32_e32 v156, v156, v208
	v_lshrrev_b32_e32 v221, 1, v210
	s_nop 0
	v_add_f32_dpp v156, v156, v156 quad_perm:[1,0,3,2] row_mask:0xf bank_mask:0xf
	v_lshlrev_b32_e32 v221, 2, v221
	v_add_u32_e32 v221, 0x24000, v221
	ds_write_b32 v221, v156
	s_waitcnt lgkmcnt(0)
.Lgemm_rsp_done:
	s_barrier
	s_lshl_b32 s0, s49, 8
	v_cndmask_b32_e64 v136, 0, 1, s[88:89]
	v_cmp_ne_u32_e64 s[42:43], 1, v136
	s_cmp_lg_u32 s9, 0
	s_cbranch_scc0 .LBB0_124
	v_and_b32_e32 v128, 15, v185
	v_lshrrev_b32_e32 v129, 4, v185
	v_lshrrev_b32_e32 v130, 2, v128
	v_and_b32_e32 v131, 3, v128
	v_cmp_eq_u32_e64 s[4:5], 1, v131
	v_cmp_eq_u32_e64 s[6:7], 2, v131
	v_cmp_eq_u32_e64 s[8:9], 3, v131
	v_cmp_eq_u32_e32 vcc, v129, v130
	s_nop 1
	v_cndmask_b32_e64 v132, v140, v141, s[4:5]
	v_cndmask_b32_e64 v132, v132, v142, s[6:7]
	v_cndmask_b32_e64 v132, v132, v143, s[8:9]
	v_cndmask_b32_e64 v133, v144, v145, s[4:5]
	v_cndmask_b32_e64 v133, v133, v146, s[6:7]
	v_cndmask_b32_e64 v133, v133, v147, s[8:9]
	v_cndmask_b32_e64 v134, v148, v149, s[4:5]
	v_cndmask_b32_e64 v134, v134, v150, s[6:7]
	v_cndmask_b32_e64 v134, v134, v151, s[8:9]
	v_cndmask_b32_e64 v135, v152, v153, s[4:5]
	v_cndmask_b32_e64 v135, v135, v154, s[6:7]
	v_cndmask_b32_e64 v135, v135, v155, s[8:9]
	s_lshl_b32 s1, s86, 2
	s_add_i32 s1, s1, 0x24000
	v_lshl_add_u32 v128, v128, 2, s1
	s_and_saveexec_b64 s[4:5], vcc
	ds_add_f32 v128, v132
	ds_add_f32 v128, v133 offset:64
	ds_add_f32 v128, v134 offset:128
	ds_add_f32 v128, v135 offset:192
	s_or_b64 exec, exec, s[4:5]
.LBB0_124:
	s_ashr_i32 s79, s78, 31
	s_lshl_b64 s[4:5], s[78:79], 8
	s_add_u32 s6, s4, s86
	s_addc_u32 s7, s5, s87
	s_lshl_b32 s1, s49, 1
	s_or_b32 s8, s1, s75
	s_lshl_b32 s64, s8, 7
	s_cmp_gt_i32 s8, 1
	s_cselect_b64 s[84:85], -1, 0
	s_cmp_gt_u32 s1, 3
	s_cselect_b64 s[26:27], -1, 0
	s_cmp_eq_u32 s8, 4
	s_cselect_b64 s[70:71], -1, 0
	s_cmp_lt_i32 s8, s20
	s_cselect_b64 s[72:73], -1, 0
	s_cmp_lt_i32 s8, 8
	s_cselect_b64 vcc, -1, 0
	v_mov_b32_e32 v128, 0x3e38aa3b
	v_cndmask_b32_e32 v130, 1.0, v128, vcc
	s_and_b64 s[8:9], vcc, exec
	s_waitcnt lgkmcnt(0)
	v_mov_b64_e32 v[128:129], 0x4080
	s_cselect_b32 s8, 0, 0x100
	v_cmp_lt_u64_e64 s[44:45], s[6:7], v[128:129]
	v_mov_b64_e32 v[128:129], 0x407f
	s_add_u32 s58, s66, s8
	v_cmp_gt_u64_e32 vcc, s[6:7], v[128:129]
	s_addc_u32 s59, s67, 0
	s_barrier
	s_cbranch_vccnz .LBB0_279
	v_mov_b32_e32 v131, v185
	s_movk_i32 s8, 0x210
	v_ashrrev_i32_e32 v128, 5, v131
	v_and_b32_e32 v132, 31, v131
	v_mul_lo_u32 v133, v128, s8
	v_lshlrev_b32_e32 v129, 2, v132
	v_lshlrev_b32_e32 v134, 2, v133
	v_add3_u32 v129, s53, v129, v134
	v_lshrrev_b32_e32 v242, 4, v131
	v_mul_u32_u24_e32 v242, 0x840, v242
	v_and_b32_e32 v243, 15, v131
	v_lshl_add_u32 v242, v243, 2, v242
	v_add_u32_e32 v234, s53, v242
	v_add_u32_e32 v235, 0x210, v234
	v_add_u32_e32 v236, 0x420, v234
	v_add_u32_e32 v237, 0x630, v234
	v_add_u32_e32 v238, 0x2100, v234
	v_add_u32_e32 v239, 0x2310, v234
	v_add_u32_e32 v240, 0x2520, v234
	v_add_u32_e32 v241, 0x2730, v234
	ds_write2_b32 v234, v64, v68 offset1:16
	ds_write2_b32 v234, v72, v76 offset0:32 offset1:48
	ds_write2_b32 v234, v80, v84 offset0:64 offset1:80
	ds_write2_b32 v234, v88, v92 offset0:96 offset1:112
	ds_write2_b32 v235, v65, v69 offset1:16
	ds_write2_b32 v235, v73, v77 offset0:32 offset1:48
	ds_write2_b32 v235, v81, v85 offset0:64 offset1:80
	ds_write2_b32 v235, v89, v93 offset0:96 offset1:112
	ds_write2_b32 v236, v66, v70 offset1:16
	ds_write2_b32 v236, v74, v78 offset0:32 offset1:48
	ds_write2_b32 v236, v82, v86 offset0:64 offset1:80
	ds_write2_b32 v236, v90, v94 offset0:96 offset1:112
	ds_write2_b32 v237, v67, v71 offset1:16
	ds_write2_b32 v237, v75, v79 offset0:32 offset1:48
	ds_write2_b32 v237, v83, v87 offset0:64 offset1:80
	ds_write2_b32 v237, v91, v95 offset0:96 offset1:112
	ds_write2_b32 v238, v96, v100 offset1:16
	ds_write2_b32 v238, v104, v108 offset0:32 offset1:48
	ds_write2_b32 v238, v112, v116 offset0:64 offset1:80
	ds_write2_b32 v238, v120, v124 offset0:96 offset1:112
	ds_write2_b32 v239, v97, v101 offset1:16
	ds_write2_b32 v239, v105, v109 offset0:32 offset1:48
	ds_write2_b32 v239, v113, v117 offset0:64 offset1:80
	ds_write2_b32 v239, v121, v125 offset0:96 offset1:112
	ds_write2_b32 v240, v98, v102 offset1:16
	ds_write2_b32 v240, v106, v110 offset0:32 offset1:48
	ds_write2_b32 v240, v114, v118 offset0:64 offset1:80
	ds_write2_b32 v240, v122, v126 offset0:96 offset1:112
	ds_write2_b32 v241, v99, v103 offset1:16
	ds_write2_b32 v241, v107, v111 offset0:32 offset1:48
	ds_write2_b32 v241, v115, v119 offset0:64 offset1:80
	ds_write2_b32 v241, v123, v127 offset0:96 offset1:112
	v_add_u32_e32 v64, 0x3800, v129
	v_add_u32_e32 v65, 0x1000, v129
	v_add_u32_e32 v66, 0x1400, v129
	v_add_u32_e32 v67, 0x2000, v129
	v_add_u32_e32 v68, 0x2400, v129
	v_add_u32_e32 v70, 0x3400, v129
	v_add_u32_e32 v69, 0x3000, v129
	v_add_u32_e32 v71, 0x3600, v129
	s_waitcnt lgkmcnt(0)
	s_mov_b64 s[22:23], -1
	s_mov_b64 s[50:51], 0
	s_cmp_lt_i32 s52, 1
	s_mov_b64 s[14:15], 0
	s_cbranch_scc1 .LBB0_272
; DI void epi_slab(const GemmCfg c, const f32x16 (&acc)[4], float* sW, const float* rss, const size_t row0, const int g, const int lane,
;                  float* const g_h, u16* const g_hb, float* const g_out, const int final_out) {
;     ...
; #pragma unroll
;     for (int hb_ = 0; hb_ < 2; ++hb_) {
;       f32x4 hv[8];
; #pragma unroll
;       for (int i8 = 0; i8 < 8; ++i8) hv[i8] = *(const f32x4*)(g_h + (row0 + hh + 2 * (hb_ * 8 + i8)) * D + col);
; #pragma unroll
;       for (int i8 = 0; i8 < 8; ++i8) {
;         const int r = hh + 2 * (hb_ * 8 + i8);
;         const size_t row = row0 + r;
;         f32x4 v = *(const f32x4*)(sW + r * 132 + c4);
;         f32x4 o = hv[i8] + v * sc;
;         *(f32x4*)(g_h + row * D + col) = o;
;         *(u32x2*)(g_hb + row * D + col) = MK2(pack2(o[0], o[1]), pack2(o[2], o[3]));
	s_cmp_eq_u32 s52, 1
	s_mov_b64 s[14:15], -1
	s_cbranch_scc0 .LBB0_192
	v_lshl_or_b32 v98, v132, 2, s64
	v_ashrrev_i32_e32 v129, 31, v128
	v_ashrrev_i32_e32 v99, 31, v98
	v_readlane_b32 s8, v254, 60
	v_lshl_add_u64 v[104:105], s[6:7], 0, v[128:129]
	v_lshlrev_b64 v[106:107], 2, v[98:99]
	v_readlane_b32 s9, v254, 61
	v_lshlrev_b64 v[64:65], 12, v[104:105]
	v_lshl_add_u32 v108, v132, 4, s53
	v_lshl_add_u64 v[96:97], s[8:9], 0, v[106:107]
	v_lshl_add_u64 v[102:103], v[96:97], 0, v[64:65]
	s_movk_i32 s8, 0x2000
	v_add_co_u32_e32 v64, vcc, s8, v102
	s_movk_i32 s8, 0x4000
	s_nop 0
	v_addc_co_u32_e32 v65, vcc, 0, v103, vcc
	global_load_dwordx4 v[92:95], v[102:103], off
	global_load_dwordx4 v[88:91], v[64:65], off
	v_add_co_u32_e32 v64, vcc, s8, v102
	s_movk_i32 s8, 0x6000
	s_nop 0
	v_addc_co_u32_e32 v65, vcc, 0, v103, vcc
	v_add_co_u32_e32 v66, vcc, s8, v102
	s_mov_b32 s8, 0x8000
	s_nop 0
	v_addc_co_u32_e32 v67, vcc, 0, v103, vcc
	global_load_dwordx4 v[84:87], v[64:65], off
	global_load_dwordx4 v[80:83], v[66:67], off
	v_add_co_u32_e32 v64, vcc, s8, v102
	s_mov_b32 s8, 0xa000
	s_nop 0
	v_addc_co_u32_e32 v65, vcc, 0, v103, vcc
	v_add_co_u32_e32 v66, vcc, s8, v102
	s_mov_b32 s8, 0xc000
	s_nop 0
	v_addc_co_u32_e32 v67, vcc, 0, v103, vcc
	global_load_dwordx4 v[76:79], v[64:65], off
	global_load_dwordx4 v[72:75], v[66:67], off
	v_add_co_u32_e32 v64, vcc, s8, v102
	s_mov_b32 s8, 0xe000
	s_nop 0
	v_addc_co_u32_e32 v65, vcc, 0, v103, vcc
	v_add_co_u32_e32 v66, vcc, s8, v102
	v_add_u32_e32 v100, v108, v133
	s_nop 0
	v_addc_co_u32_e32 v67, vcc, 0, v103, vcc
	global_load_dwordx4 v[68:71], v[64:65], off
	s_nop 0
	global_load_dwordx4 v[64:67], v[66:67], off
	v_readlane_b32 s8, v255, 3
	ds_read_b128 v[110:113], v100
	v_readlane_b32 s9, v255, 4
	v_mov_b32_e32 v171, v170
	s_waitcnt vmcnt(7) lgkmcnt(0)
	v_pk_fma_f32 v[94:95], v[170:171], v[112:113], v[94:95]
	v_lshl_add_u64 v[100:101], v[98:99], 1, s[8:9]
	v_mov_b32_e32 v148, 0x11f69000
	v_mov_b32_e32 v149, 0
	v_lshl_add_u64 v[146:147], v[148:149], 0, s[8:9]
	v_lshrrev_b32_e32 v148, 6, v98
	v_lshlrev_b32_e32 v148, 2, v148
	v_lshl_add_u64 v[146:147], v[146:147], 0, v[148:149]
	v_mov_b32_e32 v143, 0
	v_readlane_b32 s8, v252, 47
	v_readlane_b32 s9, v252, 48
	v_readlane_b32 s8, v255, 13
	v_readlane_b32 s9, v255, 14
	v_readlane_b32 s22, v252, 61
	v_readlane_b32 s23, v252, 62
	v_pk_fma_f32 v[92:93], v[172:173], v[110:111], v[92:93]
	v_lshlrev_b64 v[110:111], 11, v[104:105]
	v_cndmask_b32_e64 v109, 0, 1, s[8:9]
	v_lshl_add_u64 v[98:99], s[22:23], 0, v[106:107]
	v_cvt_pk_bf16_f32 v106, v92, v93
	v_cvt_pk_bf16_f32 v107, v94, v95
	v_lshrrev_b32_e32 v142, 5, v110
	v_lshl_add_u64 v[110:111], v[100:101], 0, v[110:111]
	v_cmp_ne_u32_e64 s[46:47], 1, v109
	s_andn2_b64 vcc, exec, s[8:9]
	v_readlane_b32 s10, v252, 49
	v_readlane_b32 s11, v252, 50
	v_readlane_b32 s12, v252, 51
	v_readlane_b32 s13, v252, 52
	v_readlane_b32 s14, v252, 53
	v_readlane_b32 s15, v252, 54
	v_readlane_b32 s16, v252, 55
	v_readlane_b32 s17, v252, 56
	v_readlane_b32 s18, v252, 57
	v_readlane_b32 s19, v252, 58
	v_readlane_b32 s20, v252, 59
	v_readlane_b32 s21, v252, 60
	global_store_dwordx4 v[102:103], v[92:95], off
	global_store_dwordx2 v[110:111], v[106:107], off
	v_mov_b32_e32 v141, 0
	v_dot2c_f32_bf16_e32 v141, v106, v106
	v_dot2c_f32_bf16_e32 v141, v107, v107
	s_nop 4
	v_add_f32_dpp v141, v141, v141 quad_perm:[1,0,3,2] row_mask:0xf bank_mask:0xf
	s_nop 1
	v_add_f32_dpp v141, v141, v141 quad_perm:[2,3,0,1] row_mask:0xf bank_mask:0xf
	s_nop 1
	v_add_f32_dpp v141, v141, v141 row_half_mirror row_mask:0xf bank_mask:0xf
	s_nop 1
	v_add_f32_dpp v141, v141, v141 row_mirror row_mask:0xf bank_mask:0xf
	v_lshl_add_u64 v[144:145], v[142:143], 0, v[146:147]
	global_store_dword v[144:145], v141, off
	s_cbranch_vccnz .LBB0_131
	s_mov_b32 s8, 0xe03f80ff
	v_mul_hi_u32 v164, v104, s8
	v_mad_u64_u32 v[106:107], s[14:15], v105, s8, v[164:165]
	v_mov_b32_e32 v164, v107
	v_mov_b32_e32 v107, v165
	s_mov_b32 s8, 0xfe03f80f
	v_mad_u64_u32 v[106:107], s[14:15], v104, s8, v[106:107]
	v_mov_b32_e32 v106, v107
	v_mov_b32_e32 v107, v165
	v_lshl_add_u64 v[106:107], v[164:165], 0, v[106:107]
	v_mad_u64_u32 v[106:107], s[14:15], v105, s8, v[106:107]
	v_alignbit_b32 v109, v107, v106, 11
	s_movk_i32 s8, 0x810
	v_mad_u64_u32 v[110:111], s[14:15], v109, s8, 0
	v_lshrrev_b32_e32 v109, 11, v107
	v_mad_u32_u24 v109, v109, s8, v111
	v_sub_co_u32_e32 v104, vcc, v104, v110
	s_nop 1
	v_subb_co_u32_e32 v105, vcc, v105, v109, vcc
	v_cmp_lt_u64_e32 vcc, 15, v[104:105]
	s_and_saveexec_b64 s[14:15], vcc
	s_cbranch_execz .LBB0_130
	v_lshrrev_b64 v[106:107], 11, v[106:107]
	v_mov_b32_e32 v110, v165
	v_mov_b32_e32 v111, v106
	v_ashrrev_i64 v[106:107], 21, v[110:111]
	v_add_u32_e32 v164, -16, v104
	v_lshl_add_u64 v[104:105], v[106:107], 0, v[164:165]
	v_lshlrev_b64 v[104:105], 12, v[104:105]
	v_lshl_add_u64 v[104:105], v[98:99], 0, v[104:105]
	global_store_dwordx4 v[104:105], v[92:95], off

; DI void epi_slab(const GemmCfg c, const f32x16 (&acc)[4], float* sW, const float* rss, const size_t row0, const int g, const int lane,
;                  float* const g_h, u16* const g_hb, float* const g_out, const int final_out) {
;     ...
;       for (int i8 = 0; i8 < 8; ++i8) {
;         const int r = hh + 2 * (hb_ * 8 + i8);
;         const size_t row = row0 + r;
;         f32x4 v = *(const f32x4*)(sW + r * 132 + c4);
;         f32x4 o = hv[i8] + v * sc;
;         *(f32x4*)(g_h + row * D + col) = o;
;         *(u32x2*)(g_hb + row * D + col) = MK2(pack2(o[0], o[1]), pack2(o[2], o[3]));
.LBB0_131:
	s_nop 0
	v_add_u32_e32 v94, 2, v128
	v_ashrrev_i32_e32 v95, 31, v94
	s_movk_i32 s8, 0x210
	v_lshl_add_u64 v[92:93], s[6:7], 0, v[94:95]
	v_mul_lo_u32 v94, v94, s8
	v_add_u32_e32 v106, v108, v94
	ds_read_b128 v[108:111], v106
	v_lshlrev_b64 v[94:95], 12, v[92:93]
	v_lshl_add_u64 v[94:95], v[96:97], 0, v[94:95]
	v_lshlrev_b64 v[104:105], 11, v[92:93]
	v_readlane_b32 s12, v254, 28
	s_waitcnt vmcnt(9) lgkmcnt(0)
	v_pk_fma_f32 v[90:91], v[170:171], v[110:111], v[90:91]
	v_pk_fma_f32 v[88:89], v[172:173], v[108:109], v[88:89]
	v_readlane_b32 s16, v255, 43
	global_store_dwordx4 v[94:95], v[88:91], off
	v_cvt_pk_bf16_f32 v94, v88, v89
	v_cvt_pk_bf16_f32 v95, v90, v91
	v_lshrrev_b32_e32 v142, 5, v104
	v_lshl_add_u64 v[104:105], v[100:101], 0, v[104:105]
	s_and_b64 vcc, exec, s[46:47]
	v_readlane_b32 s10, v254, 23
	v_readlane_b32 s13, v254, 29
	s_movk_i32 s11, 0x1600
	v_readlane_b32 s20, v255, 42
	v_readlane_b32 s17, v255, 44
	global_store_dwordx2 v[104:105], v[94:95], off
	v_mov_b32_e32 v141, 0
	v_dot2c_f32_bf16_e32 v141, v94, v94
	v_dot2c_f32_bf16_e32 v141, v95, v95
	s_nop 4
	v_add_f32_dpp v141, v141, v141 quad_perm:[1,0,3,2] row_mask:0xf bank_mask:0xf
	s_nop 1
	v_add_f32_dpp v141, v141, v141 quad_perm:[2,3,0,1] row_mask:0xf bank_mask:0xf
	s_nop 1
	v_add_f32_dpp v141, v141, v141 row_half_mirror row_mask:0xf bank_mask:0xf
	s_nop 1
	v_add_f32_dpp v141, v141, v141 row_mirror row_mask:0xf bank_mask:0xf
	v_lshl_add_u64 v[144:145], v[142:143], 0, v[146:147]
	global_store_dword v[144:145], v141, off
	s_cbranch_vccnz .LBB0_135
	s_mov_b32 s8, 0xe03f80ff
	v_mul_hi_u32 v164, v92, s8
	v_mad_u64_u32 v[94:95], s[14:15], v93, s8, v[164:165]
	v_mov_b32_e32 v164, v95
	v_mov_b32_e32 v95, v165
	s_mov_b32 s8, 0xfe03f80f
	v_mad_u64_u32 v[94:95], s[14:15], v92, s8, v[94:95]
	v_mov_b32_e32 v94, v95
	v_mov_b32_e32 v95, v165
	v_lshl_add_u64 v[94:95], v[164:165], 0, v[94:95]
	v_mad_u64_u32 v[94:95], s[14:15], v93, s8, v[94:95]
	v_alignbit_b32 v104, v95, v94, 11
	s_movk_i32 s8, 0x810
	v_mad_u64_u32 v[104:105], s[14:15], v104, s8, 0
	v_lshrrev_b32_e32 v107, 11, v95
	v_mad_u32_u24 v105, v107, s8, v105
	v_sub_co_u32_e32 v92, vcc, v92, v104
	s_nop 1
	v_subb_co_u32_e32 v93, vcc, v93, v105, vcc
	v_cmp_lt_u64_e32 vcc, 15, v[92:93]
	s_and_saveexec_b64 s[14:15], vcc
	s_cbranch_execz .LBB0_134
	v_lshrrev_b64 v[94:95], 11, v[94:95]
	v_mov_b32_e32 v104, v165
	v_mov_b32_e32 v105, v94
	v_ashrrev_i64 v[94:95], 21, v[104:105]
	v_add_u32_e32 v164, -16, v92
	v_lshl_add_u64 v[92:93], v[94:95], 0, v[164:165]
	v_lshlrev_b64 v[92:93], 12, v[92:93]
	v_lshl_add_u64 v[92:93], v[98:99], 0, v[92:93]
	global_store_dwordx4 v[92:93], v[88:91], off

; DI void epi_slab(const GemmCfg c, const f32x16 (&acc)[4], float* sW, const float* rss, const size_t row0, const int g, const int lane,
;                  float* const g_h, u16* const g_hb, float* const g_out, const int final_out) {
;     ...
;       for (int i8 = 0; i8 < 8; ++i8) {
;         const int r = hh + 2 * (hb_ * 8 + i8);
;         const size_t row = row0 + r;
;         f32x4 v = *(const f32x4*)(sW + r * 132 + c4);
;         f32x4 o = hv[i8] + v * sc;
;         *(f32x4*)(g_h + row * D + col) = o;
;         *(u32x2*)(g_hb + row * D + col) = MK2(pack2(o[0], o[1]), pack2(o[2], o[3]));
.LBB0_135:
	ds_read_b128 v[90:93], v106 offset:1056
	v_add_u32_e32 v88, 4, v128
	v_ashrrev_i32_e32 v89, 31, v88
	v_lshl_add_u64 v[88:89], s[6:7], 0, v[88:89]
	v_mov_b32_e32 v171, v170
	s_waitcnt vmcnt(11) lgkmcnt(0)
	v_pk_fma_f32 v[84:85], v[172:173], v[90:91], v[84:85]
	v_lshlrev_b64 v[90:91], 12, v[88:89]
	v_pk_fma_f32 v[86:87], v[170:171], v[92:93], v[86:87]
	v_lshl_add_u64 v[90:91], v[96:97], 0, v[90:91]
	v_lshlrev_b64 v[92:93], 11, v[88:89]
	global_store_dwordx4 v[90:91], v[84:87], off
	v_cvt_pk_bf16_f32 v90, v84, v85
	v_cvt_pk_bf16_f32 v91, v86, v87
	v_lshrrev_b32_e32 v142, 5, v92
	v_lshl_add_u64 v[92:93], v[100:101], 0, v[92:93]
	s_and_b64 vcc, exec, s[46:47]
	global_store_dwordx2 v[92:93], v[90:91], off
	v_mov_b32_e32 v141, 0
	v_dot2c_f32_bf16_e32 v141, v90, v90
	v_dot2c_f32_bf16_e32 v141, v91, v91
	s_nop 4
	v_add_f32_dpp v141, v141, v141 quad_perm:[1,0,3,2] row_mask:0xf bank_mask:0xf
	s_nop 1
	v_add_f32_dpp v141, v141, v141 quad_perm:[2,3,0,1] row_mask:0xf bank_mask:0xf
	s_nop 1
	v_add_f32_dpp v141, v141, v141 row_half_mirror row_mask:0xf bank_mask:0xf
	s_nop 1
	v_add_f32_dpp v141, v141, v141 row_mirror row_mask:0xf bank_mask:0xf
	v_lshl_add_u64 v[144:145], v[142:143], 0, v[146:147]
	global_store_dword v[144:145], v141, off
	s_cbranch_vccnz .LBB0_139
	s_mov_b32 s8, 0xe03f80ff
	v_mul_hi_u32 v164, v88, s8
	v_mad_u64_u32 v[90:91], s[14:15], v89, s8, v[164:165]
	v_mov_b32_e32 v164, v91
	v_mov_b32_e32 v91, v165
	s_mov_b32 s8, 0xfe03f80f
	v_mad_u64_u32 v[90:91], s[14:15], v88, s8, v[90:91]
	v_mov_b32_e32 v90, v91
	v_mov_b32_e32 v91, v165
	v_lshl_add_u64 v[90:91], v[164:165], 0, v[90:91]
	v_mad_u64_u32 v[90:91], s[14:15], v89, s8, v[90:91]
	v_alignbit_b32 v92, v91, v90, 11
	s_movk_i32 s8, 0x810
	v_mad_u64_u32 v[92:93], s[14:15], v92, s8, 0
	v_lshrrev_b32_e32 v94, 11, v91
	v_mad_u32_u24 v93, v94, s8, v93
	v_sub_co_u32_e32 v88, vcc, v88, v92
	s_nop 1
	v_subb_co_u32_e32 v89, vcc, v89, v93, vcc
	v_cmp_lt_u64_e32 vcc, 15, v[88:89]
	s_and_saveexec_b64 s[14:15], vcc
	s_cbranch_execz .LBB0_138
	v_lshrrev_b64 v[90:91], 11, v[90:91]
	v_mov_b32_e32 v92, v165
	v_mov_b32_e32 v93, v90
	v_ashrrev_i64 v[90:91], 21, v[92:93]
	v_add_u32_e32 v164, -16, v88
	v_lshl_add_u64 v[88:89], v[90:91], 0, v[164:165]
	v_lshlrev_b64 v[88:89], 12, v[88:89]
	v_lshl_add_u64 v[88:89], v[98:99], 0, v[88:89]
	global_store_dwordx4 v[88:89], v[84:87], off

; DI void epi_slab(const GemmCfg c, const f32x16 (&acc)[4], float* sW, const float* rss, const size_t row0, const int g, const int lane,
;                  float* const g_h, u16* const g_hb, float* const g_out, const int final_out) {
;     ...
;       for (int i8 = 0; i8 < 8; ++i8) {
;         const int r = hh + 2 * (hb_ * 8 + i8);
;         const size_t row = row0 + r;
;         f32x4 v = *(const f32x4*)(sW + r * 132 + c4);
;         f32x4 o = hv[i8] + v * sc;
;         *(f32x4*)(g_h + row * D + col) = o;
;         *(u32x2*)(g_hb + row * D + col) = MK2(pack2(o[0], o[1]), pack2(o[2], o[3]));
.LBB0_139:
	ds_read_b128 v[86:89], v106 offset:2112
	v_add_u32_e32 v84, 6, v128
	v_ashrrev_i32_e32 v85, 31, v84
	v_lshl_add_u64 v[84:85], s[6:7], 0, v[84:85]
	s_and_b64 vcc, exec, s[46:47]
	s_waitcnt vmcnt(13) lgkmcnt(0)
	v_pk_fma_f32 v[80:81], v[172:173], v[86:87], v[80:81]
	v_lshlrev_b64 v[86:87], 12, v[84:85]
	v_pk_fma_f32 v[82:83], v[170:171], v[88:89], v[82:83]
	v_lshl_add_u64 v[86:87], v[96:97], 0, v[86:87]
	v_lshlrev_b64 v[88:89], 11, v[84:85]
	global_store_dwordx4 v[86:87], v[80:83], off
	v_cvt_pk_bf16_f32 v86, v80, v81
	v_cvt_pk_bf16_f32 v87, v82, v83
	v_lshrrev_b32_e32 v142, 5, v88
	v_lshl_add_u64 v[88:89], v[100:101], 0, v[88:89]
	global_store_dwordx2 v[88:89], v[86:87], off
	v_mov_b32_e32 v141, 0
	v_dot2c_f32_bf16_e32 v141, v86, v86
	v_dot2c_f32_bf16_e32 v141, v87, v87
	s_nop 4
	v_add_f32_dpp v141, v141, v141 quad_perm:[1,0,3,2] row_mask:0xf bank_mask:0xf
	s_nop 1
	v_add_f32_dpp v141, v141, v141 quad_perm:[2,3,0,1] row_mask:0xf bank_mask:0xf
	s_nop 1
	v_add_f32_dpp v141, v141, v141 row_half_mirror row_mask:0xf bank_mask:0xf
	s_nop 1
	v_add_f32_dpp v141, v141, v141 row_mirror row_mask:0xf bank_mask:0xf
	v_lshl_add_u64 v[144:145], v[142:143], 0, v[146:147]
	global_store_dword v[144:145], v141, off
	s_cbranch_vccnz .LBB0_143
	s_mov_b32 s8, 0xe03f80ff
	v_mul_hi_u32 v164, v84, s8
	v_mad_u64_u32 v[86:87], s[14:15], v85, s8, v[164:165]
	v_mov_b32_e32 v164, v87
	v_mov_b32_e32 v87, v165
	s_mov_b32 s8, 0xfe03f80f
	v_mad_u64_u32 v[86:87], s[14:15], v84, s8, v[86:87]
	v_mov_b32_e32 v86, v87
	v_mov_b32_e32 v87, v165
	v_lshl_add_u64 v[86:87], v[164:165], 0, v[86:87]
	v_mad_u64_u32 v[86:87], s[14:15], v85, s8, v[86:87]
	v_alignbit_b32 v88, v87, v86, 11
	s_movk_i32 s8, 0x810
	v_mad_u64_u32 v[88:89], s[14:15], v88, s8, 0
	v_lshrrev_b32_e32 v90, 11, v87
	v_mad_u32_u24 v89, v90, s8, v89
	v_sub_co_u32_e32 v84, vcc, v84, v88
	s_nop 1
	v_subb_co_u32_e32 v85, vcc, v85, v89, vcc
	v_cmp_lt_u64_e32 vcc, 15, v[84:85]
	s_and_saveexec_b64 s[14:15], vcc
	s_cbranch_execz .LBB0_142
	v_lshrrev_b64 v[86:87], 11, v[86:87]
	v_mov_b32_e32 v88, v165
	v_mov_b32_e32 v89, v86
	v_ashrrev_i64 v[86:87], 21, v[88:89]
	v_add_u32_e32 v164, -16, v84
	v_lshl_add_u64 v[84:85], v[86:87], 0, v[164:165]
	v_lshlrev_b64 v[84:85], 12, v[84:85]
	v_lshl_add_u64 v[84:85], v[98:99], 0, v[84:85]
	global_store_dwordx4 v[84:85], v[80:83], off

; DI void epi_slab(const GemmCfg c, const f32x16 (&acc)[4], float* sW, const float* rss, const size_t row0, const int g, const int lane,
;                  float* const g_h, u16* const g_hb, float* const g_out, const int final_out) {
;     ...
;       for (int i8 = 0; i8 < 8; ++i8) {
;         const int r = hh + 2 * (hb_ * 8 + i8);
;         const size_t row = row0 + r;
;         f32x4 v = *(const f32x4*)(sW + r * 132 + c4);
;         f32x4 o = hv[i8] + v * sc;
;         *(f32x4*)(g_h + row * D + col) = o;
;         *(u32x2*)(g_hb + row * D + col) = MK2(pack2(o[0], o[1]), pack2(o[2], o[3]));
.LBB0_143:
	ds_read_b128 v[82:85], v106 offset:3168
	v_add_u32_e32 v80, 8, v128
	v_ashrrev_i32_e32 v81, 31, v80
	v_lshl_add_u64 v[80:81], s[6:7], 0, v[80:81]
	v_mov_b32_e32 v171, v170
	s_waitcnt vmcnt(15) lgkmcnt(0)
	v_pk_fma_f32 v[76:77], v[172:173], v[82:83], v[76:77]
	v_lshlrev_b64 v[82:83], 12, v[80:81]
	v_pk_fma_f32 v[78:79], v[170:171], v[84:85], v[78:79]
	v_lshl_add_u64 v[82:83], v[96:97], 0, v[82:83]
	v_lshlrev_b64 v[84:85], 11, v[80:81]
	global_store_dwordx4 v[82:83], v[76:79], off
	v_cvt_pk_bf16_f32 v82, v76, v77
	v_cvt_pk_bf16_f32 v83, v78, v79
	v_lshrrev_b32_e32 v142, 5, v84
	v_lshl_add_u64 v[84:85], v[100:101], 0, v[84:85]
	s_and_b64 vcc, exec, s[46:47]
	global_store_dwordx2 v[84:85], v[82:83], off
	v_mov_b32_e32 v141, 0
	v_dot2c_f32_bf16_e32 v141, v82, v82
	v_dot2c_f32_bf16_e32 v141, v83, v83
	s_nop 4
	v_add_f32_dpp v141, v141, v141 quad_perm:[1,0,3,2] row_mask:0xf bank_mask:0xf
	s_nop 1
	v_add_f32_dpp v141, v141, v141 quad_perm:[2,3,0,1] row_mask:0xf bank_mask:0xf
	s_nop 1
	v_add_f32_dpp v141, v141, v141 row_half_mirror row_mask:0xf bank_mask:0xf
	s_nop 1
	v_add_f32_dpp v141, v141, v141 row_mirror row_mask:0xf bank_mask:0xf
	v_lshl_add_u64 v[144:145], v[142:143], 0, v[146:147]
	global_store_dword v[144:145], v141, off
	s_cbranch_vccnz .LBB0_147
	s_mov_b32 s8, 0xe03f80ff
	v_mul_hi_u32 v164, v80, s8
	v_mad_u64_u32 v[82:83], s[14:15], v81, s8, v[164:165]
	v_mov_b32_e32 v164, v83
	v_mov_b32_e32 v83, v165
	s_mov_b32 s8, 0xfe03f80f
	v_mad_u64_u32 v[82:83], s[14:15], v80, s8, v[82:83]
	v_mov_b32_e32 v82, v83
	v_mov_b32_e32 v83, v165
	v_lshl_add_u64 v[82:83], v[164:165], 0, v[82:83]
	v_mad_u64_u32 v[82:83], s[14:15], v81, s8, v[82:83]
	v_alignbit_b32 v84, v83, v82, 11
	s_movk_i32 s8, 0x810
	v_mad_u64_u32 v[84:85], s[14:15], v84, s8, 0
	v_lshrrev_b32_e32 v86, 11, v83
	v_mad_u32_u24 v85, v86, s8, v85
	v_sub_co_u32_e32 v80, vcc, v80, v84
	s_nop 1
	v_subb_co_u32_e32 v81, vcc, v81, v85, vcc
	v_cmp_lt_u64_e32 vcc, 15, v[80:81]
	s_and_saveexec_b64 s[14:15], vcc
	s_cbranch_execz .LBB0_146
	v_lshrrev_b64 v[82:83], 11, v[82:83]
	v_mov_b32_e32 v84, v165
	v_mov_b32_e32 v85, v82
	v_ashrrev_i64 v[82:83], 21, v[84:85]
	v_add_u32_e32 v164, -16, v80
	v_lshl_add_u64 v[80:81], v[82:83], 0, v[164:165]
	v_lshlrev_b64 v[80:81], 12, v[80:81]
	v_lshl_add_u64 v[80:81], v[98:99], 0, v[80:81]
	global_store_dwordx4 v[80:81], v[76:79], off

; DI void epi_slab(const GemmCfg c, const f32x16 (&acc)[4], float* sW, const float* rss, const size_t row0, const int g, const int lane,
;                  float* const g_h, u16* const g_hb, float* const g_out, const int final_out) {
;     ...
;       for (int i8 = 0; i8 < 8; ++i8) {
;         const int r = hh + 2 * (hb_ * 8 + i8);
;         const size_t row = row0 + r;
;         f32x4 v = *(const f32x4*)(sW + r * 132 + c4);
;         f32x4 o = hv[i8] + v * sc;
;         *(f32x4*)(g_h + row * D + col) = o;
;         *(u32x2*)(g_hb + row * D + col) = MK2(pack2(o[0], o[1]), pack2(o[2], o[3]));
.LBB0_147:
	ds_read_b128 v[78:81], v106 offset:4224
	v_add_u32_e32 v76, 10, v128
	v_ashrrev_i32_e32 v77, 31, v76
	v_lshl_add_u64 v[76:77], s[6:7], 0, v[76:77]
	s_and_b64 vcc, exec, s[46:47]
	s_waitcnt vmcnt(17) lgkmcnt(0)
	v_pk_fma_f32 v[72:73], v[172:173], v[78:79], v[72:73]
	v_lshlrev_b64 v[78:79], 12, v[76:77]
	v_pk_fma_f32 v[74:75], v[170:171], v[80:81], v[74:75]
	v_lshl_add_u64 v[78:79], v[96:97], 0, v[78:79]
	v_lshlrev_b64 v[80:81], 11, v[76:77]
	global_store_dwordx4 v[78:79], v[72:75], off
	v_cvt_pk_bf16_f32 v78, v72, v73
	v_cvt_pk_bf16_f32 v79, v74, v75
	v_lshrrev_b32_e32 v142, 5, v80
	v_lshl_add_u64 v[80:81], v[100:101], 0, v[80:81]
	global_store_dwordx2 v[80:81], v[78:79], off
	v_mov_b32_e32 v141, 0
	v_dot2c_f32_bf16_e32 v141, v78, v78
	v_dot2c_f32_bf16_e32 v141, v79, v79
	s_nop 4
	v_add_f32_dpp v141, v141, v141 quad_perm:[1,0,3,2] row_mask:0xf bank_mask:0xf
	s_nop 1
	v_add_f32_dpp v141, v141, v141 quad_perm:[2,3,0,1] row_mask:0xf bank_mask:0xf
	s_nop 1
	v_add_f32_dpp v141, v141, v141 row_half_mirror row_mask:0xf bank_mask:0xf
	s_nop 1
	v_add_f32_dpp v141, v141, v141 row_mirror row_mask:0xf bank_mask:0xf
	v_lshl_add_u64 v[144:145], v[142:143], 0, v[146:147]
	global_store_dword v[144:145], v141, off
	s_cbranch_vccnz .LBB0_151
	s_mov_b32 s8, 0xe03f80ff
	v_mul_hi_u32 v164, v76, s8
	v_mad_u64_u32 v[78:79], s[14:15], v77, s8, v[164:165]
	v_mov_b32_e32 v164, v79
	v_mov_b32_e32 v79, v165
	s_mov_b32 s8, 0xfe03f80f
	v_mad_u64_u32 v[78:79], s[14:15], v76, s8, v[78:79]
	v_mov_b32_e32 v78, v79
	v_mov_b32_e32 v79, v165
	v_lshl_add_u64 v[78:79], v[164:165], 0, v[78:79]
	v_mad_u64_u32 v[78:79], s[14:15], v77, s8, v[78:79]
	v_alignbit_b32 v80, v79, v78, 11
	s_movk_i32 s8, 0x810
	v_mad_u64_u32 v[80:81], s[14:15], v80, s8, 0
	v_lshrrev_b32_e32 v82, 11, v79
	v_mad_u32_u24 v81, v82, s8, v81
	v_sub_co_u32_e32 v76, vcc, v76, v80
	s_nop 1
	v_subb_co_u32_e32 v77, vcc, v77, v81, vcc
	v_cmp_lt_u64_e32 vcc, 15, v[76:77]
	s_and_saveexec_b64 s[14:15], vcc
	s_cbranch_execz .LBB0_150
	v_lshrrev_b64 v[78:79], 11, v[78:79]
	v_mov_b32_e32 v80, v165
	v_mov_b32_e32 v81, v78
	v_ashrrev_i64 v[78:79], 21, v[80:81]
	v_add_u32_e32 v164, -16, v76
	v_lshl_add_u64 v[76:77], v[78:79], 0, v[164:165]
	v_lshlrev_b64 v[76:77], 12, v[76:77]
	v_lshl_add_u64 v[76:77], v[98:99], 0, v[76:77]
	global_store_dwordx4 v[76:77], v[72:75], off

; DI void epi_slab(const GemmCfg c, const f32x16 (&acc)[4], float* sW, const float* rss, const size_t row0, const int g, const int lane,
;                  float* const g_h, u16* const g_hb, float* const g_out, const int final_out) {
;     ...
;     for (int hb_ = 0; hb_ < 2; ++hb_) {
;       f32x4 hv[8];
; #pragma unroll
;       for (int i8 = 0; i8 < 8; ++i8) hv[i8] = *(const f32x4*)(g_h + (row0 + hh + 2 * (hb_ * 8 + i8)) * D + col);
; #pragma unroll
;       for (int i8 = 0; i8 < 8; ++i8) {
;         const int r = hh + 2 * (hb_ * 8 + i8);
;         const size_t row = row0 + r;
;         f32x4 v = *(const f32x4*)(sW + r * 132 + c4);
;         f32x4 o = hv[i8] + v * sc;
;         *(f32x4*)(g_h + row * D + col) = o;
;         *(u32x2*)(g_hb + row * D + col) = MK2(pack2(o[0], o[1]), pack2(o[2], o[3]));
;         if (final_out) {
;           const int b = (int)(row / T), t = (int)(row % T);
;           if (t >= 16) *(f32x4*)(g_out + ((size_t)b * 2048 + (t - 16)) * D + col) = o;
;         }
;       }
.LBB0_151:
	ds_read_b128 v[74:77], v106 offset:5280
	v_add_u32_e32 v72, 12, v128
	v_ashrrev_i32_e32 v73, 31, v72
	v_lshl_add_u64 v[72:73], s[6:7], 0, v[72:73]
	v_mov_b32_e32 v171, v170
	s_waitcnt vmcnt(19) lgkmcnt(0)
	v_pk_fma_f32 v[68:69], v[172:173], v[74:75], v[68:69]
	v_lshlrev_b64 v[74:75], 12, v[72:73]
	v_pk_fma_f32 v[70:71], v[170:171], v[76:77], v[70:71]
	v_lshl_add_u64 v[74:75], v[96:97], 0, v[74:75]
	v_lshlrev_b64 v[76:77], 11, v[72:73]
	global_store_dwordx4 v[74:75], v[68:71], off
	v_cvt_pk_bf16_f32 v74, v68, v69
	v_cvt_pk_bf16_f32 v75, v70, v71
	v_lshrrev_b32_e32 v142, 5, v76
	v_lshl_add_u64 v[76:77], v[100:101], 0, v[76:77]
	s_and_b64 vcc, exec, s[46:47]
	global_store_dwordx2 v[76:77], v[74:75], off
	v_mov_b32_e32 v141, 0
	v_dot2c_f32_bf16_e32 v141, v74, v74
	v_dot2c_f32_bf16_e32 v141, v75, v75
	s_nop 4
	v_add_f32_dpp v141, v141, v141 quad_perm:[1,0,3,2] row_mask:0xf bank_mask:0xf
	s_nop 1
	v_add_f32_dpp v141, v141, v141 quad_perm:[2,3,0,1] row_mask:0xf bank_mask:0xf
	s_nop 1
	v_add_f32_dpp v141, v141, v141 row_half_mirror row_mask:0xf bank_mask:0xf
	s_nop 1
	v_add_f32_dpp v141, v141, v141 row_mirror row_mask:0xf bank_mask:0xf
	v_lshl_add_u64 v[144:145], v[142:143], 0, v[146:147]
	global_store_dword v[144:145], v141, off
	s_cbranch_vccnz .LBB0_155
	s_mov_b32 s8, 0xe03f80ff
	v_mul_hi_u32 v164, v72, s8
	v_mad_u64_u32 v[74:75], s[14:15], v73, s8, v[164:165]
	v_mov_b32_e32 v164, v75
	v_mov_b32_e32 v75, v165
	s_mov_b32 s8, 0xfe03f80f
	v_mad_u64_u32 v[74:75], s[14:15], v72, s8, v[74:75]
	v_mov_b32_e32 v74, v75
	v_mov_b32_e32 v75, v165
	v_lshl_add_u64 v[74:75], v[164:165], 0, v[74:75]
	v_mad_u64_u32 v[74:75], s[14:15], v73, s8, v[74:75]
	v_alignbit_b32 v76, v75, v74, 11
	s_movk_i32 s8, 0x810
	v_mad_u64_u32 v[76:77], s[14:15], v76, s8, 0
	v_lshrrev_b32_e32 v78, 11, v75
	v_mad_u32_u24 v77, v78, s8, v77
	v_sub_co_u32_e32 v72, vcc, v72, v76
	s_nop 1
	v_subb_co_u32_e32 v73, vcc, v73, v77, vcc
	v_cmp_lt_u64_e32 vcc, 15, v[72:73]
	s_and_saveexec_b64 s[14:15], vcc
	s_cbranch_execz .LBB0_154
	v_lshrrev_b64 v[74:75], 11, v[74:75]
	v_mov_b32_e32 v76, v165
	v_mov_b32_e32 v77, v74
	v_ashrrev_i64 v[74:75], 21, v[76:77]
	v_add_u32_e32 v164, -16, v72
	v_lshl_add_u64 v[72:73], v[74:75], 0, v[164:165]
	v_lshlrev_b64 v[72:73], 12, v[72:73]
	v_lshl_add_u64 v[72:73], v[98:99], 0, v[72:73]
	global_store_dwordx4 v[72:73], v[68:71], off

; DI void epi_slab(const GemmCfg c, const f32x16 (&acc)[4], float* sW, const float* rss, const size_t row0, const int g, const int lane,
;                  float* const g_h, u16* const g_hb, float* const g_out, const int final_out) {
;     ...
;     for (int hb_ = 0; hb_ < 2; ++hb_) {
;       f32x4 hv[8];
; #pragma unroll
;       for (int i8 = 0; i8 < 8; ++i8) hv[i8] = *(const f32x4*)(g_h + (row0 + hh + 2 * (hb_ * 8 + i8)) * D + col);
; #pragma unroll
;       for (int i8 = 0; i8 < 8; ++i8) {
;         const int r = hh + 2 * (hb_ * 8 + i8);
;         const size_t row = row0 + r;
;         f32x4 v = *(const f32x4*)(sW + r * 132 + c4);
;         f32x4 o = hv[i8] + v * sc;
;         *(f32x4*)(g_h + row * D + col) = o;
;         *(u32x2*)(g_hb + row * D + col) = MK2(pack2(o[0], o[1]), pack2(o[2], o[3]));
;         if (final_out) {
;           const int b = (int)(row / T), t = (int)(row % T);
;           if (t >= 16) *(f32x4*)(g_out + ((size_t)b * 2048 + (t - 16)) * D + col) = o;
;         }
;       }
.LBB0_155:
	ds_read_b128 v[70:73], v106 offset:6336
	v_add_u32_e32 v68, 14, v128
	v_ashrrev_i32_e32 v69, 31, v68
	v_lshl_add_u64 v[68:69], s[6:7], 0, v[68:69]
	s_and_b64 vcc, exec, s[46:47]
	s_waitcnt vmcnt(21) lgkmcnt(0)
	v_pk_fma_f32 v[64:65], v[172:173], v[70:71], v[64:65]
	v_lshlrev_b64 v[70:71], 12, v[68:69]
	v_pk_fma_f32 v[66:67], v[170:171], v[72:73], v[66:67]
	v_lshl_add_u64 v[70:71], v[96:97], 0, v[70:71]
	v_lshlrev_b64 v[72:73], 11, v[68:69]
	global_store_dwordx4 v[70:71], v[64:67], off
	v_cvt_pk_bf16_f32 v70, v64, v65
	v_cvt_pk_bf16_f32 v71, v66, v67
	v_lshrrev_b32_e32 v142, 5, v72
	v_lshl_add_u64 v[72:73], v[100:101], 0, v[72:73]
	global_store_dwordx2 v[72:73], v[70:71], off
	v_mov_b32_e32 v141, 0
	v_dot2c_f32_bf16_e32 v141, v70, v70
	v_dot2c_f32_bf16_e32 v141, v71, v71
	s_nop 4
	v_add_f32_dpp v141, v141, v141 quad_perm:[1,0,3,2] row_mask:0xf bank_mask:0xf
	s_nop 1
	v_add_f32_dpp v141, v141, v141 quad_perm:[2,3,0,1] row_mask:0xf bank_mask:0xf
	s_nop 1
	v_add_f32_dpp v141, v141, v141 row_half_mirror row_mask:0xf bank_mask:0xf
	s_nop 1
	v_add_f32_dpp v141, v141, v141 row_mirror row_mask:0xf bank_mask:0xf
	v_lshl_add_u64 v[144:145], v[142:143], 0, v[146:147]
	global_store_dword v[144:145], v141, off
	s_cbranch_vccnz .LBB0_159
	s_mov_b32 s8, 0xe03f80ff
	v_mul_hi_u32 v164, v68, s8
	v_mad_u64_u32 v[70:71], s[14:15], v69, s8, v[164:165]
	v_mov_b32_e32 v164, v71
	v_mov_b32_e32 v71, v165
	s_mov_b32 s8, 0xfe03f80f
	v_mad_u64_u32 v[70:71], s[14:15], v68, s8, v[70:71]
	v_mov_b32_e32 v70, v71
	v_mov_b32_e32 v71, v165
	v_lshl_add_u64 v[70:71], v[164:165], 0, v[70:71]
	v_mad_u64_u32 v[70:71], s[14:15], v69, s8, v[70:71]
	v_alignbit_b32 v72, v71, v70, 11
	s_movk_i32 s8, 0x810
	v_mad_u64_u32 v[72:73], s[14:15], v72, s8, 0
	v_lshrrev_b32_e32 v74, 11, v71
	v_mad_u32_u24 v73, v74, s8, v73
	v_sub_co_u32_e32 v68, vcc, v68, v72
	s_nop 1
	v_subb_co_u32_e32 v69, vcc, v69, v73, vcc
	v_cmp_lt_u64_e32 vcc, 15, v[68:69]
	s_and_saveexec_b64 s[14:15], vcc
	s_cbranch_execz .LBB0_158
	v_lshrrev_b64 v[70:71], 11, v[70:71]
	v_mov_b32_e32 v72, v165
	v_mov_b32_e32 v73, v70
	v_ashrrev_i64 v[70:71], 21, v[72:73]
	v_add_u32_e32 v164, -16, v68
	v_lshl_add_u64 v[68:69], v[70:71], 0, v[164:165]
	v_lshlrev_b64 v[68:69], 12, v[68:69]
	v_lshl_add_u64 v[68:69], v[98:99], 0, v[68:69]
	global_store_dwordx4 v[68:69], v[64:67], off

; DI void epi_slab(const GemmCfg c, const f32x16 (&acc)[4], float* sW, const float* rss, const size_t row0, const int g, const int lane,
;                  float* const g_h, u16* const g_hb, float* const g_out, const int final_out) {
;     ...
;     for (int hb_ = 0; hb_ < 2; ++hb_) {
;       f32x4 hv[8];
; #pragma unroll
;       for (int i8 = 0; i8 < 8; ++i8) hv[i8] = *(const f32x4*)(g_h + (row0 + hh + 2 * (hb_ * 8 + i8)) * D + col);
; #pragma unroll
;       for (int i8 = 0; i8 < 8; ++i8) {
;         const int r = hh + 2 * (hb_ * 8 + i8);
;         const size_t row = row0 + r;
;         f32x4 v = *(const f32x4*)(sW + r * 132 + c4);
;         f32x4 o = hv[i8] + v * sc;
;         *(f32x4*)(g_h + row * D + col) = o;
;         *(u32x2*)(g_hb + row * D + col) = MK2(pack2(o[0], o[1]), pack2(o[2], o[3]));
;         if (final_out) {
;           const int b = (int)(row / T), t = (int)(row % T);
;           if (t >= 16) *(f32x4*)(g_out + ((size_t)b * 2048 + (t - 16)) * D + col) = o;
;         }
;       }
.LBB0_159:
	s_nop 0
	v_add_co_u32_e32 v64, vcc, 0x10000, v102
	ds_read_b128 v[108:111], v106 offset:7392
	s_nop 0
	v_addc_co_u32_e32 v65, vcc, 0, v103, vcc
	global_load_dwordx4 v[92:95], v[64:65], off
	v_add_co_u32_e32 v64, vcc, 0x12000, v102
	v_mov_b32_e32 v171, v170
	s_nop 0
	v_addc_co_u32_e32 v65, vcc, 0, v103, vcc
	global_load_dwordx4 v[88:91], v[64:65], off
	v_add_co_u32_e32 v64, vcc, 0x14000, v102
	s_waitcnt vmcnt(1) lgkmcnt(0)
	v_pk_fma_f32 v[94:95], v[170:171], v[110:111], v[94:95]
	v_addc_co_u32_e32 v65, vcc, 0, v103, vcc
	global_load_dwordx4 v[84:87], v[64:65], off
	v_add_co_u32_e32 v64, vcc, 0x16000, v102
	v_pk_fma_f32 v[92:93], v[172:173], v[108:109], v[92:93]
	s_nop 0
	v_addc_co_u32_e32 v65, vcc, 0, v103, vcc
	global_load_dwordx4 v[80:83], v[64:65], off
	v_add_co_u32_e32 v64, vcc, 0x18000, v102
	s_nop 1
	v_addc_co_u32_e32 v65, vcc, 0, v103, vcc
	global_load_dwordx4 v[76:79], v[64:65], off
	v_add_co_u32_e32 v64, vcc, 0x1a000, v102
	s_nop 1
	v_addc_co_u32_e32 v65, vcc, 0, v103, vcc
	global_load_dwordx4 v[72:75], v[64:65], off
	v_add_co_u32_e32 v64, vcc, 0x1c000, v102
	s_nop 1
	v_addc_co_u32_e32 v65, vcc, 0, v103, vcc
	global_load_dwordx4 v[68:71], v[64:65], off
	v_add_co_u32_e32 v64, vcc, 0x1e000, v102
	v_add_u32_e32 v102, 16, v128
	s_nop 0
	v_addc_co_u32_e32 v65, vcc, 0, v103, vcc
	global_load_dwordx4 v[64:67], v[64:65], off
	v_ashrrev_i32_e32 v103, 31, v102
	v_lshl_add_u64 v[102:103], s[6:7], 0, v[102:103]
	v_lshlrev_b64 v[104:105], 12, v[102:103]
	v_lshl_add_u64 v[104:105], v[96:97], 0, v[104:105]
	v_lshlrev_b64 v[108:109], 11, v[102:103]
	global_store_dwordx4 v[104:105], v[92:95], off
	v_cvt_pk_bf16_f32 v104, v92, v93
	v_cvt_pk_bf16_f32 v105, v94, v95
	v_lshrrev_b32_e32 v142, 5, v108
	v_lshl_add_u64 v[108:109], v[100:101], 0, v[108:109]
	s_and_b64 vcc, exec, s[46:47]
	global_store_dwordx2 v[108:109], v[104:105], off
	v_mov_b32_e32 v141, 0
	v_dot2c_f32_bf16_e32 v141, v104, v104
	v_dot2c_f32_bf16_e32 v141, v105, v105
	s_nop 4
	v_add_f32_dpp v141, v141, v141 quad_perm:[1,0,3,2] row_mask:0xf bank_mask:0xf
	s_nop 1
	v_add_f32_dpp v141, v141, v141 quad_perm:[2,3,0,1] row_mask:0xf bank_mask:0xf
	s_nop 1
	v_add_f32_dpp v141, v141, v141 row_half_mirror row_mask:0xf bank_mask:0xf
	s_nop 1
	v_add_f32_dpp v141, v141, v141 row_mirror row_mask:0xf bank_mask:0xf
	v_lshl_add_u64 v[144:145], v[142:143], 0, v[146:147]
	global_store_dword v[144:145], v141, off
	s_cbranch_vccnz .LBB0_163
	s_mov_b32 s8, 0xe03f80ff
	v_mul_hi_u32 v164, v102, s8
	v_mad_u64_u32 v[104:105], s[14:15], v103, s8, v[164:165]
	v_mov_b32_e32 v164, v105
	v_mov_b32_e32 v105, v165
	s_mov_b32 s8, 0xfe03f80f
	v_mad_u64_u32 v[104:105], s[14:15], v102, s8, v[104:105]
	v_mov_b32_e32 v104, v105
	v_mov_b32_e32 v105, v165
	v_lshl_add_u64 v[104:105], v[164:165], 0, v[104:105]
	v_mad_u64_u32 v[104:105], s[14:15], v103, s8, v[104:105]
	v_alignbit_b32 v107, v105, v104, 11
	s_movk_i32 s8, 0x810
	v_mad_u64_u32 v[108:109], s[14:15], v107, s8, 0
	v_lshrrev_b32_e32 v107, 11, v105
	v_mad_u32_u24 v107, v107, s8, v109
	v_sub_co_u32_e32 v102, vcc, v102, v108
	s_nop 1
	v_subb_co_u32_e32 v103, vcc, v103, v107, vcc
	v_cmp_lt_u64_e32 vcc, 15, v[102:103]
	s_and_saveexec_b64 s[14:15], vcc
	s_cbranch_execz .LBB0_162
	v_lshrrev_b64 v[104:105], 11, v[104:105]
	v_mov_b32_e32 v108, v165
	v_mov_b32_e32 v109, v104
	v_ashrrev_i64 v[104:105], 21, v[108:109]
	v_add_u32_e32 v164, -16, v102
	v_lshl_add_u64 v[102:103], v[104:105], 0, v[164:165]
	v_lshlrev_b64 v[102:103], 12, v[102:103]
	v_lshl_add_u64 v[102:103], v[98:99], 0, v[102:103]
	global_store_dwordx4 v[102:103], v[92:95], off

; DI void epi_slab(const GemmCfg c, const f32x16 (&acc)[4], float* sW, const float* rss, const size_t row0, const int g, const int lane,
;                  float* const g_h, u16* const g_hb, float* const g_out, const int final_out) {
;     ...
;     for (int hb_ = 0; hb_ < 2; ++hb_) {
;       f32x4 hv[8];
; #pragma unroll
;       for (int i8 = 0; i8 < 8; ++i8) hv[i8] = *(const f32x4*)(g_h + (row0 + hh + 2 * (hb_ * 8 + i8)) * D + col);
; #pragma unroll
;       for (int i8 = 0; i8 < 8; ++i8) {
;         const int r = hh + 2 * (hb_ * 8 + i8);
;         const size_t row = row0 + r;
;         f32x4 v = *(const f32x4*)(sW + r * 132 + c4);
;         f32x4 o = hv[i8] + v * sc;
;         *(f32x4*)(g_h + row * D + col) = o;
;         *(u32x2*)(g_hb + row * D + col) = MK2(pack2(o[0], o[1]), pack2(o[2], o[3]));
;         if (final_out) {
;           const int b = (int)(row / T), t = (int)(row % T);
;           if (t >= 16) *(f32x4*)(g_out + ((size_t)b * 2048 + (t - 16)) * D + col) = o;
;         }
;       }
.LBB0_163:
	ds_read_b128 v[102:105], v106 offset:8448
	v_add_u32_e32 v92, 18, v128
	v_ashrrev_i32_e32 v93, 31, v92
	v_lshl_add_u64 v[92:93], s[6:7], 0, v[92:93]
	v_lshlrev_b64 v[94:95], 12, v[92:93]
	s_waitcnt vmcnt(9) lgkmcnt(0)
	v_pk_fma_f32 v[90:91], v[170:171], v[104:105], v[90:91]
	v_pk_fma_f32 v[88:89], v[172:173], v[102:103], v[88:89]
	v_lshl_add_u64 v[94:95], v[96:97], 0, v[94:95]
	v_lshlrev_b64 v[102:103], 11, v[92:93]
	global_store_dwordx4 v[94:95], v[88:91], off
	v_cvt_pk_bf16_f32 v94, v88, v89
	v_cvt_pk_bf16_f32 v95, v90, v91
	v_lshrrev_b32_e32 v142, 5, v102
	v_lshl_add_u64 v[102:103], v[100:101], 0, v[102:103]
	s_and_b64 vcc, exec, s[46:47]
	global_store_dwordx2 v[102:103], v[94:95], off
	v_mov_b32_e32 v141, 0
	v_dot2c_f32_bf16_e32 v141, v94, v94
	v_dot2c_f32_bf16_e32 v141, v95, v95
	s_nop 4
	v_add_f32_dpp v141, v141, v141 quad_perm:[1,0,3,2] row_mask:0xf bank_mask:0xf
	s_nop 1
	v_add_f32_dpp v141, v141, v141 quad_perm:[2,3,0,1] row_mask:0xf bank_mask:0xf
	s_nop 1
	v_add_f32_dpp v141, v141, v141 row_half_mirror row_mask:0xf bank_mask:0xf
	s_nop 1
	v_add_f32_dpp v141, v141, v141 row_mirror row_mask:0xf bank_mask:0xf
	v_lshl_add_u64 v[144:145], v[142:143], 0, v[146:147]
	global_store_dword v[144:145], v141, off
	s_cbranch_vccnz .LBB0_167
	s_mov_b32 s8, 0xe03f80ff
	v_mul_hi_u32 v164, v92, s8
	v_mad_u64_u32 v[94:95], s[14:15], v93, s8, v[164:165]
	v_mov_b32_e32 v164, v95
	v_mov_b32_e32 v95, v165
	s_mov_b32 s8, 0xfe03f80f
	v_mad_u64_u32 v[94:95], s[14:15], v92, s8, v[94:95]
	v_mov_b32_e32 v94, v95
	v_mov_b32_e32 v95, v165
	v_lshl_add_u64 v[94:95], v[164:165], 0, v[94:95]
	v_mad_u64_u32 v[94:95], s[14:15], v93, s8, v[94:95]
	v_alignbit_b32 v102, v95, v94, 11
	s_movk_i32 s8, 0x810
	v_mad_u64_u32 v[102:103], s[14:15], v102, s8, 0
	v_lshrrev_b32_e32 v104, 11, v95
	v_mad_u32_u24 v103, v104, s8, v103
	v_sub_co_u32_e32 v92, vcc, v92, v102
	s_nop 1
	v_subb_co_u32_e32 v93, vcc, v93, v103, vcc
	v_cmp_lt_u64_e32 vcc, 15, v[92:93]
	s_and_saveexec_b64 s[14:15], vcc
	s_cbranch_execz .LBB0_166
	v_lshrrev_b64 v[94:95], 11, v[94:95]
	v_mov_b32_e32 v102, v165
	v_mov_b32_e32 v103, v94
	v_ashrrev_i64 v[94:95], 21, v[102:103]
	v_add_u32_e32 v164, -16, v92
	v_lshl_add_u64 v[92:93], v[94:95], 0, v[164:165]
	v_lshlrev_b64 v[92:93], 12, v[92:93]
	v_lshl_add_u64 v[92:93], v[98:99], 0, v[92:93]
	global_store_dwordx4 v[92:93], v[88:91], off

; DI void epi_slab(const GemmCfg c, const f32x16 (&acc)[4], float* sW, const float* rss, const size_t row0, const int g, const int lane,
;                  float* const g_h, u16* const g_hb, float* const g_out, const int final_out) {
;     ...
;     for (int hb_ = 0; hb_ < 2; ++hb_) {
;       f32x4 hv[8];
; #pragma unroll
;       for (int i8 = 0; i8 < 8; ++i8) hv[i8] = *(const f32x4*)(g_h + (row0 + hh + 2 * (hb_ * 8 + i8)) * D + col);
; #pragma unroll
;       for (int i8 = 0; i8 < 8; ++i8) {
;         const int r = hh + 2 * (hb_ * 8 + i8);
;         const size_t row = row0 + r;
;         f32x4 v = *(const f32x4*)(sW + r * 132 + c4);
;         f32x4 o = hv[i8] + v * sc;
;         *(f32x4*)(g_h + row * D + col) = o;
;         *(u32x2*)(g_hb + row * D + col) = MK2(pack2(o[0], o[1]), pack2(o[2], o[3]));
;         if (final_out) {
;           const int b = (int)(row / T), t = (int)(row % T);
;           if (t >= 16) *(f32x4*)(g_out + ((size_t)b * 2048 + (t - 16)) * D + col) = o;
;         }
;       }
.LBB0_167:
	ds_read_b128 v[90:93], v106 offset:9504
	v_add_u32_e32 v88, 20, v128
	v_ashrrev_i32_e32 v89, 31, v88
	v_lshl_add_u64 v[88:89], s[6:7], 0, v[88:89]
	v_mov_b32_e32 v171, v170
	s_waitcnt vmcnt(11) lgkmcnt(0)
	v_pk_fma_f32 v[84:85], v[172:173], v[90:91], v[84:85]
	v_lshlrev_b64 v[90:91], 12, v[88:89]
	v_pk_fma_f32 v[86:87], v[170:171], v[92:93], v[86:87]
	v_lshl_add_u64 v[90:91], v[96:97], 0, v[90:91]
	v_lshlrev_b64 v[92:93], 11, v[88:89]
	global_store_dwordx4 v[90:91], v[84:87], off
	v_cvt_pk_bf16_f32 v90, v84, v85
	v_cvt_pk_bf16_f32 v91, v86, v87
	v_lshrrev_b32_e32 v142, 5, v92
	v_lshl_add_u64 v[92:93], v[100:101], 0, v[92:93]
	s_and_b64 vcc, exec, s[46:47]
	global_store_dwordx2 v[92:93], v[90:91], off
	v_mov_b32_e32 v141, 0
	v_dot2c_f32_bf16_e32 v141, v90, v90
	v_dot2c_f32_bf16_e32 v141, v91, v91
	s_nop 4
	v_add_f32_dpp v141, v141, v141 quad_perm:[1,0,3,2] row_mask:0xf bank_mask:0xf
	s_nop 1
	v_add_f32_dpp v141, v141, v141 quad_perm:[2,3,0,1] row_mask:0xf bank_mask:0xf
	s_nop 1
	v_add_f32_dpp v141, v141, v141 row_half_mirror row_mask:0xf bank_mask:0xf
	s_nop 1
	v_add_f32_dpp v141, v141, v141 row_mirror row_mask:0xf bank_mask:0xf
	v_lshl_add_u64 v[144:145], v[142:143], 0, v[146:147]
	global_store_dword v[144:145], v141, off
	s_cbranch_vccnz .LBB0_171
	s_mov_b32 s8, 0xe03f80ff
	v_mul_hi_u32 v164, v88, s8
	v_mad_u64_u32 v[90:91], s[14:15], v89, s8, v[164:165]
	v_mov_b32_e32 v164, v91
	v_mov_b32_e32 v91, v165
	s_mov_b32 s8, 0xfe03f80f
	v_mad_u64_u32 v[90:91], s[14:15], v88, s8, v[90:91]
	v_mov_b32_e32 v90, v91
	v_mov_b32_e32 v91, v165
	v_lshl_add_u64 v[90:91], v[164:165], 0, v[90:91]
	v_mad_u64_u32 v[90:91], s[14:15], v89, s8, v[90:91]
	v_alignbit_b32 v92, v91, v90, 11
	s_movk_i32 s8, 0x810
	v_mad_u64_u32 v[92:93], s[14:15], v92, s8, 0
	v_lshrrev_b32_e32 v94, 11, v91
	v_mad_u32_u24 v93, v94, s8, v93
	v_sub_co_u32_e32 v88, vcc, v88, v92
	s_nop 1
	v_subb_co_u32_e32 v89, vcc, v89, v93, vcc
	v_cmp_lt_u64_e32 vcc, 15, v[88:89]
	s_and_saveexec_b64 s[14:15], vcc
	s_cbranch_execz .LBB0_170
	v_lshrrev_b64 v[90:91], 11, v[90:91]
	v_mov_b32_e32 v92, v165
	v_mov_b32_e32 v93, v90
	v_ashrrev_i64 v[90:91], 21, v[92:93]
	v_add_u32_e32 v164, -16, v88
	v_lshl_add_u64 v[88:89], v[90:91], 0, v[164:165]
	v_lshlrev_b64 v[88:89], 12, v[88:89]
	v_lshl_add_u64 v[88:89], v[98:99], 0, v[88:89]
	global_store_dwordx4 v[88:89], v[84:87], off

; DI void epi_slab(const GemmCfg c, const f32x16 (&acc)[4], float* sW, const float* rss, const size_t row0, const int g, const int lane,
;                  float* const g_h, u16* const g_hb, float* const g_out, const int final_out) {
;     ...
;     for (int hb_ = 0; hb_ < 2; ++hb_) {
;       f32x4 hv[8];
; #pragma unroll
;       for (int i8 = 0; i8 < 8; ++i8) hv[i8] = *(const f32x4*)(g_h + (row0 + hh + 2 * (hb_ * 8 + i8)) * D + col);
; #pragma unroll
;       for (int i8 = 0; i8 < 8; ++i8) {
;         const int r = hh + 2 * (hb_ * 8 + i8);
;         const size_t row = row0 + r;
;         f32x4 v = *(const f32x4*)(sW + r * 132 + c4);
;         f32x4 o = hv[i8] + v * sc;
;         *(f32x4*)(g_h + row * D + col) = o;
;         *(u32x2*)(g_hb + row * D + col) = MK2(pack2(o[0], o[1]), pack2(o[2], o[3]));
;         if (final_out) {
;           const int b = (int)(row / T), t = (int)(row % T);
;           if (t >= 16) *(f32x4*)(g_out + ((size_t)b * 2048 + (t - 16)) * D + col) = o;
;         }
;       }
.LBB0_171:
	ds_read_b128 v[86:89], v106 offset:10560
	v_add_u32_e32 v84, 22, v128
	v_ashrrev_i32_e32 v85, 31, v84
	v_lshl_add_u64 v[84:85], s[6:7], 0, v[84:85]
	s_and_b64 vcc, exec, s[46:47]
	s_waitcnt vmcnt(13) lgkmcnt(0)
	v_pk_fma_f32 v[80:81], v[172:173], v[86:87], v[80:81]
	v_lshlrev_b64 v[86:87], 12, v[84:85]
	v_pk_fma_f32 v[82:83], v[170:171], v[88:89], v[82:83]
	v_lshl_add_u64 v[86:87], v[96:97], 0, v[86:87]
	v_lshlrev_b64 v[88:89], 11, v[84:85]
	global_store_dwordx4 v[86:87], v[80:83], off
	v_cvt_pk_bf16_f32 v86, v80, v81
	v_cvt_pk_bf16_f32 v87, v82, v83
	v_lshrrev_b32_e32 v142, 5, v88
	v_lshl_add_u64 v[88:89], v[100:101], 0, v[88:89]
	global_store_dwordx2 v[88:89], v[86:87], off
	v_mov_b32_e32 v141, 0
	v_dot2c_f32_bf16_e32 v141, v86, v86
	v_dot2c_f32_bf16_e32 v141, v87, v87
	s_nop 4
	v_add_f32_dpp v141, v141, v141 quad_perm:[1,0,3,2] row_mask:0xf bank_mask:0xf
	s_nop 1
	v_add_f32_dpp v141, v141, v141 quad_perm:[2,3,0,1] row_mask:0xf bank_mask:0xf
	s_nop 1
	v_add_f32_dpp v141, v141, v141 row_half_mirror row_mask:0xf bank_mask:0xf
	s_nop 1
	v_add_f32_dpp v141, v141, v141 row_mirror row_mask:0xf bank_mask:0xf
	v_lshl_add_u64 v[144:145], v[142:143], 0, v[146:147]
	global_store_dword v[144:145], v141, off
	s_cbranch_vccnz .LBB0_175
	s_mov_b32 s8, 0xe03f80ff
	v_mul_hi_u32 v164, v84, s8
	v_mad_u64_u32 v[86:87], s[14:15], v85, s8, v[164:165]
	v_mov_b32_e32 v164, v87
	v_mov_b32_e32 v87, v165
	s_mov_b32 s8, 0xfe03f80f
	v_mad_u64_u32 v[86:87], s[14:15], v84, s8, v[86:87]
	v_mov_b32_e32 v86, v87
	v_mov_b32_e32 v87, v165
	v_lshl_add_u64 v[86:87], v[164:165], 0, v[86:87]
	v_mad_u64_u32 v[86:87], s[14:15], v85, s8, v[86:87]
	v_alignbit_b32 v88, v87, v86, 11
	s_movk_i32 s8, 0x810
	v_mad_u64_u32 v[88:89], s[14:15], v88, s8, 0
	v_lshrrev_b32_e32 v90, 11, v87
	v_mad_u32_u24 v89, v90, s8, v89
	v_sub_co_u32_e32 v84, vcc, v84, v88
	s_nop 1
	v_subb_co_u32_e32 v85, vcc, v85, v89, vcc
	v_cmp_lt_u64_e32 vcc, 15, v[84:85]
	s_and_saveexec_b64 s[14:15], vcc
	s_cbranch_execz .LBB0_174
	v_lshrrev_b64 v[86:87], 11, v[86:87]
	v_mov_b32_e32 v88, v165
	v_mov_b32_e32 v89, v86
	v_ashrrev_i64 v[86:87], 21, v[88:89]
	v_add_u32_e32 v164, -16, v84
	v_lshl_add_u64 v[84:85], v[86:87], 0, v[164:165]
	v_lshlrev_b64 v[84:85], 12, v[84:85]
	v_lshl_add_u64 v[84:85], v[98:99], 0, v[84:85]
	global_store_dwordx4 v[84:85], v[80:83], off

; DI void epi_slab(const GemmCfg c, const f32x16 (&acc)[4], float* sW, const float* rss, const size_t row0, const int g, const int lane,
;                  float* const g_h, u16* const g_hb, float* const g_out, const int final_out) {
;     ...
;     for (int hb_ = 0; hb_ < 2; ++hb_) {
;       f32x4 hv[8];
; #pragma unroll
;       for (int i8 = 0; i8 < 8; ++i8) hv[i8] = *(const f32x4*)(g_h + (row0 + hh + 2 * (hb_ * 8 + i8)) * D + col);
; #pragma unroll
;       for (int i8 = 0; i8 < 8; ++i8) {
;         const int r = hh + 2 * (hb_ * 8 + i8);
;         const size_t row = row0 + r;
;         f32x4 v = *(const f32x4*)(sW + r * 132 + c4);
;         f32x4 o = hv[i8] + v * sc;
;         *(f32x4*)(g_h + row * D + col) = o;
;         *(u32x2*)(g_hb + row * D + col) = MK2(pack2(o[0], o[1]), pack2(o[2], o[3]));
;         if (final_out) {
;           const int b = (int)(row / T), t = (int)(row % T);
;           if (t >= 16) *(f32x4*)(g_out + ((size_t)b * 2048 + (t - 16)) * D + col) = o;
;         }
;       }
.LBB0_175:
	ds_read_b128 v[82:85], v106 offset:11616
	v_add_u32_e32 v80, 24, v128
	v_ashrrev_i32_e32 v81, 31, v80
	v_lshl_add_u64 v[80:81], s[6:7], 0, v[80:81]
	v_mov_b32_e32 v171, v170
	s_waitcnt vmcnt(15) lgkmcnt(0)
	v_pk_fma_f32 v[76:77], v[172:173], v[82:83], v[76:77]
	v_lshlrev_b64 v[82:83], 12, v[80:81]
	v_pk_fma_f32 v[78:79], v[170:171], v[84:85], v[78:79]
	v_lshl_add_u64 v[82:83], v[96:97], 0, v[82:83]
	v_lshlrev_b64 v[84:85], 11, v[80:81]
	global_store_dwordx4 v[82:83], v[76:79], off
	v_cvt_pk_bf16_f32 v82, v76, v77
	v_cvt_pk_bf16_f32 v83, v78, v79
	v_lshrrev_b32_e32 v142, 5, v84
	v_lshl_add_u64 v[84:85], v[100:101], 0, v[84:85]
	s_and_b64 vcc, exec, s[46:47]
	global_store_dwordx2 v[84:85], v[82:83], off
	v_mov_b32_e32 v141, 0
	v_dot2c_f32_bf16_e32 v141, v82, v82
	v_dot2c_f32_bf16_e32 v141, v83, v83
	s_nop 4
	v_add_f32_dpp v141, v141, v141 quad_perm:[1,0,3,2] row_mask:0xf bank_mask:0xf
	s_nop 1
	v_add_f32_dpp v141, v141, v141 quad_perm:[2,3,0,1] row_mask:0xf bank_mask:0xf
	s_nop 1
	v_add_f32_dpp v141, v141, v141 row_half_mirror row_mask:0xf bank_mask:0xf
	s_nop 1
	v_add_f32_dpp v141, v141, v141 row_mirror row_mask:0xf bank_mask:0xf
	v_lshl_add_u64 v[144:145], v[142:143], 0, v[146:147]
	global_store_dword v[144:145], v141, off
	s_cbranch_vccnz .LBB0_179
	s_mov_b32 s8, 0xe03f80ff
	v_mul_hi_u32 v164, v80, s8
	v_mad_u64_u32 v[82:83], s[14:15], v81, s8, v[164:165]
	v_mov_b32_e32 v164, v83
	v_mov_b32_e32 v83, v165
	s_mov_b32 s8, 0xfe03f80f
	v_mad_u64_u32 v[82:83], s[14:15], v80, s8, v[82:83]
	v_mov_b32_e32 v82, v83
	v_mov_b32_e32 v83, v165
	v_lshl_add_u64 v[82:83], v[164:165], 0, v[82:83]
	v_mad_u64_u32 v[82:83], s[14:15], v81, s8, v[82:83]
	v_alignbit_b32 v84, v83, v82, 11
	s_movk_i32 s8, 0x810
	v_mad_u64_u32 v[84:85], s[14:15], v84, s8, 0
	v_lshrrev_b32_e32 v86, 11, v83
	v_mad_u32_u24 v85, v86, s8, v85
	v_sub_co_u32_e32 v80, vcc, v80, v84
	s_nop 1
	v_subb_co_u32_e32 v81, vcc, v81, v85, vcc
	v_cmp_lt_u64_e32 vcc, 15, v[80:81]
	s_and_saveexec_b64 s[14:15], vcc
	s_cbranch_execz .LBB0_178
	v_lshrrev_b64 v[82:83], 11, v[82:83]
	v_mov_b32_e32 v84, v165
	v_mov_b32_e32 v85, v82
	v_ashrrev_i64 v[82:83], 21, v[84:85]
	v_add_u32_e32 v164, -16, v80
	v_lshl_add_u64 v[80:81], v[82:83], 0, v[164:165]
	v_lshlrev_b64 v[80:81], 12, v[80:81]
	v_lshl_add_u64 v[80:81], v[98:99], 0, v[80:81]
	global_store_dwordx4 v[80:81], v[76:79], off

; DI void epi_slab(const GemmCfg c, const f32x16 (&acc)[4], float* sW, const float* rss, const size_t row0, const int g, const int lane,
;                  float* const g_h, u16* const g_hb, float* const g_out, const int final_out) {
;     ...
;     for (int hb_ = 0; hb_ < 2; ++hb_) {
;       f32x4 hv[8];
; #pragma unroll
;       for (int i8 = 0; i8 < 8; ++i8) hv[i8] = *(const f32x4*)(g_h + (row0 + hh + 2 * (hb_ * 8 + i8)) * D + col);
; #pragma unroll
;       for (int i8 = 0; i8 < 8; ++i8) {
;         const int r = hh + 2 * (hb_ * 8 + i8);
;         const size_t row = row0 + r;
;         f32x4 v = *(const f32x4*)(sW + r * 132 + c4);
;         f32x4 o = hv[i8] + v * sc;
;         *(f32x4*)(g_h + row * D + col) = o;
;         *(u32x2*)(g_hb + row * D + col) = MK2(pack2(o[0], o[1]), pack2(o[2], o[3]));
;         if (final_out) {
;           const int b = (int)(row / T), t = (int)(row % T);
;           if (t >= 16) *(f32x4*)(g_out + ((size_t)b * 2048 + (t - 16)) * D + col) = o;
;         }
;       }
.LBB0_179:
	ds_read_b128 v[78:81], v106 offset:12672
	v_add_u32_e32 v76, 26, v128
	v_ashrrev_i32_e32 v77, 31, v76
	v_lshl_add_u64 v[76:77], s[6:7], 0, v[76:77]
	s_and_b64 vcc, exec, s[46:47]
	s_waitcnt vmcnt(17) lgkmcnt(0)
	v_pk_fma_f32 v[72:73], v[172:173], v[78:79], v[72:73]
	v_lshlrev_b64 v[78:79], 12, v[76:77]
	v_pk_fma_f32 v[74:75], v[170:171], v[80:81], v[74:75]
	v_lshl_add_u64 v[78:79], v[96:97], 0, v[78:79]
	v_lshlrev_b64 v[80:81], 11, v[76:77]
	global_store_dwordx4 v[78:79], v[72:75], off
	v_cvt_pk_bf16_f32 v78, v72, v73
	v_cvt_pk_bf16_f32 v79, v74, v75
	v_lshrrev_b32_e32 v142, 5, v80
	v_lshl_add_u64 v[80:81], v[100:101], 0, v[80:81]
	global_store_dwordx2 v[80:81], v[78:79], off
	v_mov_b32_e32 v141, 0
	v_dot2c_f32_bf16_e32 v141, v78, v78
	v_dot2c_f32_bf16_e32 v141, v79, v79
	s_nop 4
	v_add_f32_dpp v141, v141, v141 quad_perm:[1,0,3,2] row_mask:0xf bank_mask:0xf
	s_nop 1
	v_add_f32_dpp v141, v141, v141 quad_perm:[2,3,0,1] row_mask:0xf bank_mask:0xf
	s_nop 1
	v_add_f32_dpp v141, v141, v141 row_half_mirror row_mask:0xf bank_mask:0xf
	s_nop 1
	v_add_f32_dpp v141, v141, v141 row_mirror row_mask:0xf bank_mask:0xf
	v_lshl_add_u64 v[144:145], v[142:143], 0, v[146:147]
	global_store_dword v[144:145], v141, off
	s_cbranch_vccnz .LBB0_183
	s_mov_b32 s8, 0xe03f80ff
	v_mul_hi_u32 v164, v76, s8
	v_mad_u64_u32 v[78:79], s[14:15], v77, s8, v[164:165]
	v_mov_b32_e32 v164, v79
	v_mov_b32_e32 v79, v165
	s_mov_b32 s8, 0xfe03f80f
	v_mad_u64_u32 v[78:79], s[14:15], v76, s8, v[78:79]
	v_mov_b32_e32 v78, v79
	v_mov_b32_e32 v79, v165
	v_lshl_add_u64 v[78:79], v[164:165], 0, v[78:79]
	v_mad_u64_u32 v[78:79], s[14:15], v77, s8, v[78:79]
	v_alignbit_b32 v80, v79, v78, 11
	s_movk_i32 s8, 0x810
	v_mad_u64_u32 v[80:81], s[14:15], v80, s8, 0
	v_lshrrev_b32_e32 v82, 11, v79
	v_mad_u32_u24 v81, v82, s8, v81
	v_sub_co_u32_e32 v76, vcc, v76, v80
	s_nop 1
	v_subb_co_u32_e32 v77, vcc, v77, v81, vcc
	v_cmp_lt_u64_e32 vcc, 15, v[76:77]
	s_and_saveexec_b64 s[14:15], vcc
	s_cbranch_execz .LBB0_182
	v_lshrrev_b64 v[78:79], 11, v[78:79]
	v_mov_b32_e32 v80, v165
	v_mov_b32_e32 v81, v78
	v_ashrrev_i64 v[78:79], 21, v[80:81]
	v_add_u32_e32 v164, -16, v76
	v_lshl_add_u64 v[76:77], v[78:79], 0, v[164:165]
	v_lshlrev_b64 v[76:77], 12, v[76:77]
	v_lshl_add_u64 v[76:77], v[98:99], 0, v[76:77]
	global_store_dwordx4 v[76:77], v[72:75], off

; DI void epi_slab(const GemmCfg c, const f32x16 (&acc)[4], float* sW, const float* rss, const size_t row0, const int g, const int lane,
;                  float* const g_h, u16* const g_hb, float* const g_out, const int final_out) {
;     ...
;     for (int hb_ = 0; hb_ < 2; ++hb_) {
;       f32x4 hv[8];
; #pragma unroll
;       for (int i8 = 0; i8 < 8; ++i8) hv[i8] = *(const f32x4*)(g_h + (row0 + hh + 2 * (hb_ * 8 + i8)) * D + col);
; #pragma unroll
;       for (int i8 = 0; i8 < 8; ++i8) {
;         const int r = hh + 2 * (hb_ * 8 + i8);
;         const size_t row = row0 + r;
;         f32x4 v = *(const f32x4*)(sW + r * 132 + c4);
;         f32x4 o = hv[i8] + v * sc;
;         *(f32x4*)(g_h + row * D + col) = o;
;         *(u32x2*)(g_hb + row * D + col) = MK2(pack2(o[0], o[1]), pack2(o[2], o[3]));
;         if (final_out) {
;           const int b = (int)(row / T), t = (int)(row % T);
;           if (t >= 16) *(f32x4*)(g_out + ((size_t)b * 2048 + (t - 16)) * D + col) = o;
;         }
;       }
.LBB0_183:
	ds_read_b128 v[74:77], v106 offset:13728
	v_add_u32_e32 v72, 28, v128
	v_ashrrev_i32_e32 v73, 31, v72
	v_lshl_add_u64 v[72:73], s[6:7], 0, v[72:73]
	v_mov_b32_e32 v171, v170
	s_waitcnt vmcnt(19) lgkmcnt(0)
	v_pk_fma_f32 v[68:69], v[172:173], v[74:75], v[68:69]
	v_lshlrev_b64 v[74:75], 12, v[72:73]
	v_pk_fma_f32 v[70:71], v[170:171], v[76:77], v[70:71]
	v_lshl_add_u64 v[74:75], v[96:97], 0, v[74:75]
	v_lshlrev_b64 v[76:77], 11, v[72:73]
	global_store_dwordx4 v[74:75], v[68:71], off
	v_cvt_pk_bf16_f32 v74, v68, v69
	v_cvt_pk_bf16_f32 v75, v70, v71
	v_lshrrev_b32_e32 v142, 5, v76
	v_lshl_add_u64 v[76:77], v[100:101], 0, v[76:77]
	s_and_b64 vcc, exec, s[46:47]
	global_store_dwordx2 v[76:77], v[74:75], off
	v_mov_b32_e32 v141, 0
	v_dot2c_f32_bf16_e32 v141, v74, v74
	v_dot2c_f32_bf16_e32 v141, v75, v75
	s_nop 4
	v_add_f32_dpp v141, v141, v141 quad_perm:[1,0,3,2] row_mask:0xf bank_mask:0xf
	s_nop 1
	v_add_f32_dpp v141, v141, v141 quad_perm:[2,3,0,1] row_mask:0xf bank_mask:0xf
	s_nop 1
	v_add_f32_dpp v141, v141, v141 row_half_mirror row_mask:0xf bank_mask:0xf
	s_nop 1
	v_add_f32_dpp v141, v141, v141 row_mirror row_mask:0xf bank_mask:0xf
	v_lshl_add_u64 v[144:145], v[142:143], 0, v[146:147]
	global_store_dword v[144:145], v141, off
	s_cbranch_vccnz .LBB0_187
	s_mov_b32 s8, 0xe03f80ff
	v_mul_hi_u32 v164, v72, s8
	v_mad_u64_u32 v[74:75], s[14:15], v73, s8, v[164:165]
	v_mov_b32_e32 v164, v75
	v_mov_b32_e32 v75, v165
	s_mov_b32 s8, 0xfe03f80f
	v_mad_u64_u32 v[74:75], s[14:15], v72, s8, v[74:75]
	v_mov_b32_e32 v74, v75
	v_mov_b32_e32 v75, v165
	v_lshl_add_u64 v[74:75], v[164:165], 0, v[74:75]
	v_mad_u64_u32 v[74:75], s[14:15], v73, s8, v[74:75]
	v_alignbit_b32 v76, v75, v74, 11
	s_movk_i32 s8, 0x810
	v_mad_u64_u32 v[76:77], s[14:15], v76, s8, 0
	v_lshrrev_b32_e32 v78, 11, v75
	v_mad_u32_u24 v77, v78, s8, v77
	v_sub_co_u32_e32 v72, vcc, v72, v76
	s_nop 1
	v_subb_co_u32_e32 v73, vcc, v73, v77, vcc
	v_cmp_lt_u64_e32 vcc, 15, v[72:73]
	s_and_saveexec_b64 s[14:15], vcc
	s_cbranch_execz .LBB0_186
	v_lshrrev_b64 v[74:75], 11, v[74:75]
	v_mov_b32_e32 v76, v165
	v_mov_b32_e32 v77, v74
	v_ashrrev_i64 v[74:75], 21, v[76:77]
	v_add_u32_e32 v164, -16, v72
	v_lshl_add_u64 v[72:73], v[74:75], 0, v[164:165]
	v_lshlrev_b64 v[72:73], 12, v[72:73]
	v_lshl_add_u64 v[72:73], v[98:99], 0, v[72:73]
	global_store_dwordx4 v[72:73], v[68:71], off

; DI void epi_slab(const GemmCfg c, const f32x16 (&acc)[4], float* sW, const float* rss, const size_t row0, const int g, const int lane,
;                  float* const g_h, u16* const g_hb, float* const g_out, const int final_out) {
;     ...
;     for (int hb_ = 0; hb_ < 2; ++hb_) {
;       f32x4 hv[8];
; #pragma unroll
;       for (int i8 = 0; i8 < 8; ++i8) hv[i8] = *(const f32x4*)(g_h + (row0 + hh + 2 * (hb_ * 8 + i8)) * D + col);
; #pragma unroll
;       for (int i8 = 0; i8 < 8; ++i8) {
;         const int r = hh + 2 * (hb_ * 8 + i8);
;         const size_t row = row0 + r;
;         f32x4 v = *(const f32x4*)(sW + r * 132 + c4);
;         f32x4 o = hv[i8] + v * sc;
;         *(f32x4*)(g_h + row * D + col) = o;
;         *(u32x2*)(g_hb + row * D + col) = MK2(pack2(o[0], o[1]), pack2(o[2], o[3]));
;         if (final_out) {
;           const int b = (int)(row / T), t = (int)(row % T);
;           if (t >= 16) *(f32x4*)(g_out + ((size_t)b * 2048 + (t - 16)) * D + col) = o;
;         }
;       }
.LBB0_187:
	ds_read_b128 v[70:73], v106 offset:14784
	v_add_u32_e32 v68, 30, v128
	v_ashrrev_i32_e32 v69, 31, v68
	v_lshl_add_u64 v[68:69], s[6:7], 0, v[68:69]
	s_and_b64 vcc, exec, s[46:47]
	s_waitcnt vmcnt(21) lgkmcnt(0)
	v_pk_fma_f32 v[64:65], v[172:173], v[70:71], v[64:65]
	v_lshlrev_b64 v[70:71], 12, v[68:69]
	v_pk_fma_f32 v[66:67], v[170:171], v[72:73], v[66:67]
	v_lshl_add_u64 v[70:71], v[96:97], 0, v[70:71]
	v_lshlrev_b64 v[72:73], 11, v[68:69]
	global_store_dwordx4 v[70:71], v[64:67], off
	v_cvt_pk_bf16_f32 v70, v64, v65
	v_cvt_pk_bf16_f32 v71, v66, v67
	v_lshrrev_b32_e32 v142, 5, v72
	v_lshl_add_u64 v[72:73], v[100:101], 0, v[72:73]
	global_store_dwordx2 v[72:73], v[70:71], off
	v_mov_b32_e32 v141, 0
	v_dot2c_f32_bf16_e32 v141, v70, v70
	v_dot2c_f32_bf16_e32 v141, v71, v71
	s_nop 4
	v_add_f32_dpp v141, v141, v141 quad_perm:[1,0,3,2] row_mask:0xf bank_mask:0xf
	s_nop 1
	v_add_f32_dpp v141, v141, v141 quad_perm:[2,3,0,1] row_mask:0xf bank_mask:0xf
	s_nop 1
	v_add_f32_dpp v141, v141, v141 row_half_mirror row_mask:0xf bank_mask:0xf
	s_nop 1
	v_add_f32_dpp v141, v141, v141 row_mirror row_mask:0xf bank_mask:0xf
	v_lshl_add_u64 v[144:145], v[142:143], 0, v[146:147]
	global_store_dword v[144:145], v141, off
	s_cbranch_vccnz .LBB0_191
	s_mov_b32 s8, 0xe03f80ff
	v_mul_hi_u32 v164, v68, s8
	v_mad_u64_u32 v[70:71], s[14:15], v69, s8, v[164:165]
	v_mov_b32_e32 v164, v71
	v_mov_b32_e32 v71, v165
	s_mov_b32 s8, 0xfe03f80f
	v_mad_u64_u32 v[70:71], s[14:15], v68, s8, v[70:71]
	v_mov_b32_e32 v70, v71
	v_mov_b32_e32 v71, v165
	v_lshl_add_u64 v[70:71], v[164:165], 0, v[70:71]
	v_mad_u64_u32 v[70:71], s[14:15], v69, s8, v[70:71]
	v_alignbit_b32 v72, v71, v70, 11
	s_movk_i32 s8, 0x810
	v_mad_u64_u32 v[72:73], s[14:15], v72, s8, 0
	v_lshrrev_b32_e32 v74, 11, v71
	v_mad_u32_u24 v73, v74, s8, v73
	v_sub_co_u32_e32 v68, vcc, v68, v72
	s_nop 1
	v_subb_co_u32_e32 v69, vcc, v69, v73, vcc
	v_cmp_lt_u64_e32 vcc, 15, v[68:69]
	s_and_saveexec_b64 s[14:15], vcc
	s_cbranch_execz .LBB0_190
	v_lshrrev_b64 v[70:71], 11, v[70:71]
	v_mov_b32_e32 v72, v165
	v_mov_b32_e32 v73, v70
	v_ashrrev_i64 v[70:71], 21, v[72:73]
	v_add_u32_e32 v164, -16, v68
	v_lshl_add_u64 v[68:69], v[70:71], 0, v[164:165]
	v_lshlrev_b64 v[68:69], 12, v[68:69]
	v_lshl_add_u64 v[68:69], v[98:99], 0, v[68:69]
	global_store_dwordx4 v[68:69], v[64:67], off

; DI int crow(int i, int hh) { return (i & 3) + 8 * (i >> 2) + 4 * hh; }
; DI void epi_slab(const GemmCfg c, const f32x16 (&acc)[4], float* sW, const float* rss, const size_t row0, const int g, const int lane,
;                  float* const g_h, u16* const g_hb, float* const g_out, const int final_out) {
;   int ln_ = lane;
;   asm volatile("" : "+v"(ln_));
;   const int l31 = ln_ & 31, hh = ln_ >> 5;
; #pragma unroll
;   for (int nb = 0; nb < 4; ++nb)
; #pragma unroll
;     for (int i = 0; i < 16; ++i) sW[crow(i, hh) * 132 + nb * 32 + l31] = acc[nb][i];
;   asm volatile("s_waitcnt lgkmcnt(0)" ::: "memory");
;   const int K = c.K;
;   const float invK = 1.0f / (float)K;
;   if (c.epi == EPI_SWIGLU) {
.LBB0_279:
	s_andn2_b64 vcc, exec, s[44:45]
	s_cbranch_vccnz .LBB0_109
	s_waitcnt lgkmcnt(0)
	v_mov_b32_e32 v66, v185
	s_movk_i32 s8, 0x210
	v_ashrrev_i32_e32 v64, 5, v66
	v_and_b32_e32 v67, 31, v66
	v_mul_lo_u32 v68, v64, s8
	v_lshlrev_b32_e32 v65, 2, v67
	v_lshlrev_b32_e32 v69, 2, v68
	v_add3_u32 v65, s53, v65, v69
	v_lshrrev_b32_e32 v242, 4, v66
	v_mul_u32_u24_e32 v242, 0x840, v242
	v_and_b32_e32 v243, 15, v66
	v_lshl_add_u32 v242, v243, 2, v242
	v_add_u32_e32 v234, s53, v242
	v_add_u32_e32 v235, 0x210, v234
	v_add_u32_e32 v236, 0x420, v234
	v_add_u32_e32 v237, 0x630, v234
	v_add_u32_e32 v238, 0x2100, v234
	v_add_u32_e32 v239, 0x2310, v234
	v_add_u32_e32 v240, 0x2520, v234
	v_add_u32_e32 v241, 0x2730, v234
	ds_write2_b32 v234, v0, v4 offset1:16
	ds_write2_b32 v234, v8, v12 offset0:32 offset1:48
	ds_write2_b32 v234, v16, v20 offset0:64 offset1:80
	ds_write2_b32 v234, v24, v28 offset0:96 offset1:112
	ds_write2_b32 v235, v1, v5 offset1:16
	ds_write2_b32 v235, v9, v13 offset0:32 offset1:48
	ds_write2_b32 v235, v17, v21 offset0:64 offset1:80
	ds_write2_b32 v235, v25, v29 offset0:96 offset1:112
	ds_write2_b32 v236, v2, v6 offset1:16
	ds_write2_b32 v236, v10, v14 offset0:32 offset1:48
	ds_write2_b32 v236, v18, v22 offset0:64 offset1:80
	ds_write2_b32 v236, v26, v30 offset0:96 offset1:112
	ds_write2_b32 v237, v3, v7 offset1:16
	ds_write2_b32 v237, v11, v15 offset0:32 offset1:48
	ds_write2_b32 v237, v19, v23 offset0:64 offset1:80
	ds_write2_b32 v237, v27, v31 offset0:96 offset1:112
	ds_write2_b32 v238, v32, v36 offset1:16
	ds_write2_b32 v238, v40, v44 offset0:32 offset1:48
	ds_write2_b32 v238, v48, v52 offset0:64 offset1:80
	ds_write2_b32 v238, v56, v60 offset0:96 offset1:112
	ds_write2_b32 v239, v33, v37 offset1:16
	ds_write2_b32 v239, v41, v45 offset0:32 offset1:48
	ds_write2_b32 v239, v49, v53 offset0:64 offset1:80
	ds_write2_b32 v239, v57, v61 offset0:96 offset1:112
	ds_write2_b32 v240, v34, v38 offset1:16
	ds_write2_b32 v240, v42, v46 offset0:32 offset1:48
	ds_write2_b32 v240, v50, v54 offset0:64 offset1:80
	ds_write2_b32 v240, v58, v62 offset0:96 offset1:112
	ds_write2_b32 v241, v35, v39 offset1:16
	ds_write2_b32 v241, v43, v47 offset0:32 offset1:48
	ds_write2_b32 v241, v51, v55 offset0:64 offset1:80
	ds_write2_b32 v241, v59, v63 offset0:96 offset1:112
	v_add_u32_e32 v32, 0x400, v65
	v_add_u32_e32 v33, 0x1000, v65
	v_add_u32_e32 v34, 0x1400, v65
	v_add_u32_e32 v35, 0x2000, v65
	v_add_u32_e32 v36, 0x2400, v65
	v_add_u32_e32 v38, 0x3400, v65
	v_add_u32_e32 v37, 0x3000, v65
	v_add_u32_e32 v39, 0x3600, v65
	v_add_u32_e32 v0, 0x3800, v65
	s_waitcnt lgkmcnt(0)
	s_mov_b64 s[14:15], -1
	s_mov_b64 s[46:47], 0
	s_cmp_lt_i32 s52, 1
	s_mov_b64 s[8:9], 0
	s_cbranch_scc1 .LBB0_427
	s_cmp_eq_u32 s52, 1
	s_mov_b64 s[8:9], -1
	s_cbranch_scc0 .LBB0_347
; DI void epi_slab(const GemmCfg c, const f32x16 (&acc)[4], float* sW, const float* rss, const size_t row0, const int g, const int lane,
;                  float* const g_h, u16* const g_hb, float* const g_out, const int final_out) {
;     ...
;     const int c4 = l31 * 4;
;     const int col = g * 128 + c4;
;     const float sc = (K == DFF ? 0.5f : 1.f);
; #pragma unroll
;     for (int hb_ = 0; hb_ < 2; ++hb_) {
;       f32x4 hv[8];
; #pragma unroll
;       for (int i8 = 0; i8 < 8; ++i8) hv[i8] = *(const f32x4*)(g_h + (row0 + hh + 2 * (hb_ * 8 + i8)) * D + col);
; #pragma unroll
;       for (int i8 = 0; i8 < 8; ++i8) {
;         const int r = hh + 2 * (hb_ * 8 + i8);
;         const size_t row = row0 + r;
;         f32x4 v = *(const f32x4*)(sW + r * 132 + c4);
;         f32x4 o = hv[i8] + v * sc;
;         *(f32x4*)(g_h + row * D + col) = o;
;         *(u32x2*)(g_hb + row * D + col) = MK2(pack2(o[0], o[1]), pack2(o[2], o[3]));
;         if (final_out) {
;           const int b = (int)(row / T), t = (int)(row % T);
;           if (t >= 16) *(f32x4*)(g_out + ((size_t)b * 2048 + (t - 16)) * D + col) = o;
;         }
;       }
	v_lshl_or_b32 v34, v67, 2, s64
	s_or_b32 s6, s6, 32
	v_ashrrev_i32_e32 v65, 31, v64
	v_ashrrev_i32_e32 v35, 31, v34
	v_readlane_b32 s8, v254, 60
	v_lshl_add_u64 v[40:41], s[6:7], 0, v[64:65]
	v_lshlrev_b64 v[42:43], 2, v[34:35]
	v_readlane_b32 s9, v254, 61
	v_lshlrev_b64 v[0:1], 12, v[40:41]
	v_lshl_add_u32 v44, v67, 4, s53
	v_lshl_add_u64 v[32:33], s[8:9], 0, v[42:43]
	v_lshl_add_u64 v[38:39], v[32:33], 0, v[0:1]
	s_movk_i32 s8, 0x2000
	v_add_co_u32_e32 v0, vcc, s8, v38
	s_movk_i32 s8, 0x4000
	s_nop 0
	v_addc_co_u32_e32 v1, vcc, 0, v39, vcc
	global_load_dwordx4 v[28:31], v[38:39], off
	global_load_dwordx4 v[24:27], v[0:1], off
	v_add_co_u32_e32 v0, vcc, s8, v38
	s_movk_i32 s8, 0x6000
	s_nop 0
	v_addc_co_u32_e32 v1, vcc, 0, v39, vcc
	v_add_co_u32_e32 v2, vcc, s8, v38
	s_mov_b32 s8, 0x8000
	s_nop 0
	v_addc_co_u32_e32 v3, vcc, 0, v39, vcc
	global_load_dwordx4 v[20:23], v[0:1], off
	global_load_dwordx4 v[16:19], v[2:3], off
	v_add_co_u32_e32 v0, vcc, s8, v38
	s_mov_b32 s8, 0xa000
	s_nop 0
	v_addc_co_u32_e32 v1, vcc, 0, v39, vcc
	v_add_co_u32_e32 v2, vcc, s8, v38
	s_mov_b32 s8, 0xc000
	s_nop 0
	v_addc_co_u32_e32 v3, vcc, 0, v39, vcc
	global_load_dwordx4 v[12:15], v[0:1], off
	global_load_dwordx4 v[8:11], v[2:3], off
	v_add_co_u32_e32 v0, vcc, s8, v38
	s_mov_b32 s8, 0xe000
	s_nop 0
	v_addc_co_u32_e32 v1, vcc, 0, v39, vcc
	v_add_co_u32_e32 v2, vcc, s8, v38
	v_add_u32_e32 v36, v44, v68
	s_nop 0
	v_addc_co_u32_e32 v3, vcc, 0, v39, vcc
	global_load_dwordx4 v[4:7], v[0:1], off
	s_nop 0
	global_load_dwordx4 v[0:3], v[2:3], off
	v_readlane_b32 s8, v255, 3
	ds_read_b128 v[46:49], v36
	v_readlane_b32 s9, v255, 4
	v_mov_b32_e32 v171, v170
	s_waitcnt vmcnt(7) lgkmcnt(0)
	v_pk_fma_f32 v[30:31], v[170:171], v[48:49], v[30:31]
	v_lshl_add_u64 v[36:37], v[34:35], 1, s[8:9]
	v_mov_b32_e32 v148, 0x11f69000
	v_mov_b32_e32 v149, 0
	v_lshl_add_u64 v[146:147], v[148:149], 0, s[8:9]
	v_lshrrev_b32_e32 v148, 6, v34
	v_lshlrev_b32_e32 v148, 2, v148
	v_lshl_add_u64 v[146:147], v[146:147], 0, v[148:149]
	v_mov_b32_e32 v143, 0
	v_readlane_b32 s8, v252, 47
	v_readlane_b32 s9, v252, 48
	v_readlane_b32 s8, v255, 13
	v_readlane_b32 s9, v255, 14
	v_readlane_b32 s22, v252, 61
	v_readlane_b32 s23, v252, 62
	v_pk_fma_f32 v[28:29], v[172:173], v[46:47], v[28:29]
	v_lshlrev_b64 v[46:47], 11, v[40:41]
	v_cndmask_b32_e64 v45, 0, 1, s[8:9]
	v_lshl_add_u64 v[34:35], s[22:23], 0, v[42:43]
	v_cvt_pk_bf16_f32 v42, v28, v29
	v_cvt_pk_bf16_f32 v43, v30, v31
	v_lshrrev_b32_e32 v142, 5, v46
	v_lshl_add_u64 v[46:47], v[36:37], 0, v[46:47]
	v_cmp_ne_u32_e64 s[44:45], 1, v45
	s_andn2_b64 vcc, exec, s[8:9]
	v_readlane_b32 s10, v252, 49
	v_readlane_b32 s11, v252, 50
	v_readlane_b32 s12, v252, 51
	v_readlane_b32 s13, v252, 52
	v_readlane_b32 s14, v252, 53
	v_readlane_b32 s15, v252, 54
	v_readlane_b32 s16, v252, 55
	v_readlane_b32 s17, v252, 56
	v_readlane_b32 s18, v252, 57
	v_readlane_b32 s19, v252, 58
	v_readlane_b32 s20, v252, 59
	v_readlane_b32 s21, v252, 60
	global_store_dwordx4 v[38:39], v[28:31], off
	global_store_dwordx2 v[46:47], v[42:43], off
	v_mov_b32_e32 v141, 0
	v_dot2c_f32_bf16_e32 v141, v42, v42
	v_dot2c_f32_bf16_e32 v141, v43, v43
	s_nop 4
	v_add_f32_dpp v141, v141, v141 quad_perm:[1,0,3,2] row_mask:0xf bank_mask:0xf
	s_nop 1
	v_add_f32_dpp v141, v141, v141 quad_perm:[2,3,0,1] row_mask:0xf bank_mask:0xf
	s_nop 1
	v_add_f32_dpp v141, v141, v141 row_half_mirror row_mask:0xf bank_mask:0xf
	s_nop 1
	v_add_f32_dpp v141, v141, v141 row_mirror row_mask:0xf bank_mask:0xf
	v_lshl_add_u64 v[144:145], v[142:143], 0, v[146:147]
	global_store_dword v[144:145], v141, off
	s_cbranch_vccnz .LBB0_286
	s_mov_b32 s8, 0xe03f80ff
	v_mul_hi_u32 v164, v40, s8
	v_mad_u64_u32 v[42:43], s[8:9], v41, s8, v[164:165]
	v_mov_b32_e32 v164, v43
	v_mov_b32_e32 v43, v165
	s_mov_b32 s10, 0xfe03f80f
	v_mad_u64_u32 v[42:43], s[8:9], v40, s10, v[42:43]
	v_mov_b32_e32 v42, v43
	v_mov_b32_e32 v43, v165
	v_lshl_add_u64 v[42:43], v[164:165], 0, v[42:43]
	v_mad_u64_u32 v[42:43], s[8:9], v41, s10, v[42:43]
	v_alignbit_b32 v45, v43, v42, 11
	s_movk_i32 s10, 0x810
	v_mad_u64_u32 v[46:47], s[8:9], v45, s10, 0
	v_lshrrev_b32_e32 v45, 11, v43
	v_mad_u32_u24 v45, v45, s10, v47
	v_sub_co_u32_e32 v40, vcc, v40, v46
	s_nop 1
	v_subb_co_u32_e32 v41, vcc, v41, v45, vcc
	v_cmp_lt_u64_e32 vcc, 15, v[40:41]
	s_and_saveexec_b64 s[8:9], vcc
	s_cbranch_execz .LBB0_285
	v_lshrrev_b64 v[42:43], 11, v[42:43]
	v_mov_b32_e32 v46, v165
	v_mov_b32_e32 v47, v42
	v_ashrrev_i64 v[42:43], 21, v[46:47]
	v_add_u32_e32 v164, -16, v40
	v_lshl_add_u64 v[40:41], v[42:43], 0, v[164:165]
	v_lshlrev_b64 v[40:41], 12, v[40:41]
	v_lshl_add_u64 v[40:41], v[34:35], 0, v[40:41]
	global_store_dwordx4 v[40:41], v[28:31], off

; DI void epi_slab(const GemmCfg c, const f32x16 (&acc)[4], float* sW, const float* rss, const size_t row0, const int g, const int lane,
;                  float* const g_h, u16* const g_hb, float* const g_out, const int final_out) {
;     ...
;       for (int i8 = 0; i8 < 8; ++i8) {
;         const int r = hh + 2 * (hb_ * 8 + i8);
;         const size_t row = row0 + r;
;         f32x4 v = *(const f32x4*)(sW + r * 132 + c4);
;         f32x4 o = hv[i8] + v * sc;
;         *(f32x4*)(g_h + row * D + col) = o;
;         *(u32x2*)(g_hb + row * D + col) = MK2(pack2(o[0], o[1]), pack2(o[2], o[3]));
;         if (final_out) {
;           const int b = (int)(row / T), t = (int)(row % T);
;           if (t >= 16) *(f32x4*)(g_out + ((size_t)b * 2048 + (t - 16)) * D + col) = o;
;         }
;       }
.LBB0_286:
	s_nop 0
	v_add_u32_e32 v30, 2, v64
	v_ashrrev_i32_e32 v31, 31, v30
	s_movk_i32 s8, 0x210
	v_lshl_add_u64 v[28:29], s[6:7], 0, v[30:31]
	v_mul_lo_u32 v30, v30, s8
	v_add_u32_e32 v42, v44, v30
	ds_read_b128 v[44:47], v42
	v_lshlrev_b64 v[30:31], 12, v[28:29]
	v_lshl_add_u64 v[30:31], v[32:33], 0, v[30:31]
	v_lshlrev_b64 v[40:41], 11, v[28:29]
	v_readlane_b32 s12, v254, 28
	s_waitcnt vmcnt(9) lgkmcnt(0)
	v_pk_fma_f32 v[26:27], v[170:171], v[46:47], v[26:27]
	v_pk_fma_f32 v[24:25], v[172:173], v[44:45], v[24:25]
	v_readlane_b32 s16, v255, 43
	global_store_dwordx4 v[30:31], v[24:27], off
	v_cvt_pk_bf16_f32 v30, v24, v25
	v_cvt_pk_bf16_f32 v31, v26, v27
	v_lshrrev_b32_e32 v142, 5, v40
	v_lshl_add_u64 v[40:41], v[36:37], 0, v[40:41]
	s_and_b64 vcc, exec, s[44:45]
	v_readlane_b32 s10, v254, 23
	v_readlane_b32 s13, v254, 29
	s_movk_i32 s11, 0x1600
	v_readlane_b32 s20, v255, 42
	v_readlane_b32 s17, v255, 44
	global_store_dwordx2 v[40:41], v[30:31], off
	v_mov_b32_e32 v141, 0
	v_dot2c_f32_bf16_e32 v141, v30, v30
	v_dot2c_f32_bf16_e32 v141, v31, v31
	s_nop 4
	v_add_f32_dpp v141, v141, v141 quad_perm:[1,0,3,2] row_mask:0xf bank_mask:0xf
	s_nop 1
	v_add_f32_dpp v141, v141, v141 quad_perm:[2,3,0,1] row_mask:0xf bank_mask:0xf
	s_nop 1
	v_add_f32_dpp v141, v141, v141 row_half_mirror row_mask:0xf bank_mask:0xf
	s_nop 1
	v_add_f32_dpp v141, v141, v141 row_mirror row_mask:0xf bank_mask:0xf
	v_lshl_add_u64 v[144:145], v[142:143], 0, v[146:147]
	global_store_dword v[144:145], v141, off
	s_cbranch_vccnz .LBB0_290
	s_mov_b32 s8, 0xe03f80ff
	v_mul_hi_u32 v164, v28, s8
	v_mad_u64_u32 v[30:31], s[8:9], v29, s8, v[164:165]
	v_mov_b32_e32 v164, v31
	v_mov_b32_e32 v31, v165
	s_mov_b32 s14, 0xfe03f80f
	v_mad_u64_u32 v[30:31], s[8:9], v28, s14, v[30:31]
	v_mov_b32_e32 v30, v31
	v_mov_b32_e32 v31, v165
	v_lshl_add_u64 v[30:31], v[164:165], 0, v[30:31]
	v_mad_u64_u32 v[30:31], s[8:9], v29, s14, v[30:31]
	v_alignbit_b32 v40, v31, v30, 11
	s_movk_i32 s14, 0x810
	v_mad_u64_u32 v[40:41], s[8:9], v40, s14, 0
	v_lshrrev_b32_e32 v43, 11, v31
	v_mad_u32_u24 v41, v43, s14, v41
	v_sub_co_u32_e32 v28, vcc, v28, v40
	s_nop 1
	v_subb_co_u32_e32 v29, vcc, v29, v41, vcc
	v_cmp_lt_u64_e32 vcc, 15, v[28:29]
	s_and_saveexec_b64 s[8:9], vcc
	s_cbranch_execz .LBB0_289
	v_lshrrev_b64 v[30:31], 11, v[30:31]
	v_mov_b32_e32 v40, v165
	v_mov_b32_e32 v41, v30
	v_ashrrev_i64 v[30:31], 21, v[40:41]
	v_add_u32_e32 v164, -16, v28
	v_lshl_add_u64 v[28:29], v[30:31], 0, v[164:165]
	v_lshlrev_b64 v[28:29], 12, v[28:29]
	v_lshl_add_u64 v[28:29], v[34:35], 0, v[28:29]
	global_store_dwordx4 v[28:29], v[24:27], off

; DI void epi_slab(const GemmCfg c, const f32x16 (&acc)[4], float* sW, const float* rss, const size_t row0, const int g, const int lane,
;                  float* const g_h, u16* const g_hb, float* const g_out, const int final_out) {
;     ...
;       for (int i8 = 0; i8 < 8; ++i8) {
;         const int r = hh + 2 * (hb_ * 8 + i8);
;         const size_t row = row0 + r;
;         f32x4 v = *(const f32x4*)(sW + r * 132 + c4);
;         f32x4 o = hv[i8] + v * sc;
;         *(f32x4*)(g_h + row * D + col) = o;
;         *(u32x2*)(g_hb + row * D + col) = MK2(pack2(o[0], o[1]), pack2(o[2], o[3]));
;         if (final_out) {
;           const int b = (int)(row / T), t = (int)(row % T);
;           if (t >= 16) *(f32x4*)(g_out + ((size_t)b * 2048 + (t - 16)) * D + col) = o;
;         }
;       }
.LBB0_290:
	ds_read_b128 v[26:29], v42 offset:1056
	v_add_u32_e32 v24, 4, v64
	v_ashrrev_i32_e32 v25, 31, v24
	v_lshl_add_u64 v[24:25], s[6:7], 0, v[24:25]
	v_mov_b32_e32 v171, v170
	s_waitcnt vmcnt(11) lgkmcnt(0)
	v_pk_fma_f32 v[20:21], v[172:173], v[26:27], v[20:21]
	v_lshlrev_b64 v[26:27], 12, v[24:25]
	v_pk_fma_f32 v[22:23], v[170:171], v[28:29], v[22:23]
	v_lshl_add_u64 v[26:27], v[32:33], 0, v[26:27]
	v_lshlrev_b64 v[28:29], 11, v[24:25]
	global_store_dwordx4 v[26:27], v[20:23], off
	v_cvt_pk_bf16_f32 v26, v20, v21
	v_cvt_pk_bf16_f32 v27, v22, v23
	v_lshrrev_b32_e32 v142, 5, v28
	v_lshl_add_u64 v[28:29], v[36:37], 0, v[28:29]
	s_and_b64 vcc, exec, s[44:45]
	global_store_dwordx2 v[28:29], v[26:27], off
	v_mov_b32_e32 v141, 0
	v_dot2c_f32_bf16_e32 v141, v26, v26
	v_dot2c_f32_bf16_e32 v141, v27, v27
	s_nop 4
	v_add_f32_dpp v141, v141, v141 quad_perm:[1,0,3,2] row_mask:0xf bank_mask:0xf
	s_nop 1
	v_add_f32_dpp v141, v141, v141 quad_perm:[2,3,0,1] row_mask:0xf bank_mask:0xf
	s_nop 1
	v_add_f32_dpp v141, v141, v141 row_half_mirror row_mask:0xf bank_mask:0xf
	s_nop 1
	v_add_f32_dpp v141, v141, v141 row_mirror row_mask:0xf bank_mask:0xf
	v_lshl_add_u64 v[144:145], v[142:143], 0, v[146:147]
	global_store_dword v[144:145], v141, off
	s_cbranch_vccnz .LBB0_294
	s_mov_b32 s8, 0xe03f80ff
	v_mul_hi_u32 v164, v24, s8
	v_mad_u64_u32 v[26:27], s[8:9], v25, s8, v[164:165]
	v_mov_b32_e32 v164, v27
	v_mov_b32_e32 v27, v165
	s_mov_b32 s14, 0xfe03f80f
	v_mad_u64_u32 v[26:27], s[8:9], v24, s14, v[26:27]
	v_mov_b32_e32 v26, v27
	v_mov_b32_e32 v27, v165
	v_lshl_add_u64 v[26:27], v[164:165], 0, v[26:27]
	v_mad_u64_u32 v[26:27], s[8:9], v25, s14, v[26:27]
	v_alignbit_b32 v28, v27, v26, 11
	s_movk_i32 s14, 0x810
	v_mad_u64_u32 v[28:29], s[8:9], v28, s14, 0
	v_lshrrev_b32_e32 v30, 11, v27
	v_mad_u32_u24 v29, v30, s14, v29
	v_sub_co_u32_e32 v24, vcc, v24, v28
	s_nop 1
	v_subb_co_u32_e32 v25, vcc, v25, v29, vcc
	v_cmp_lt_u64_e32 vcc, 15, v[24:25]
	s_and_saveexec_b64 s[8:9], vcc
	s_cbranch_execz .LBB0_293
	v_lshrrev_b64 v[26:27], 11, v[26:27]
	v_mov_b32_e32 v28, v165
	v_mov_b32_e32 v29, v26
	v_ashrrev_i64 v[26:27], 21, v[28:29]
	v_add_u32_e32 v164, -16, v24
	v_lshl_add_u64 v[24:25], v[26:27], 0, v[164:165]
	v_lshlrev_b64 v[24:25], 12, v[24:25]
	v_lshl_add_u64 v[24:25], v[34:35], 0, v[24:25]
	global_store_dwordx4 v[24:25], v[20:23], off

; DI void epi_slab(const GemmCfg c, const f32x16 (&acc)[4], float* sW, const float* rss, const size_t row0, const int g, const int lane,
;                  float* const g_h, u16* const g_hb, float* const g_out, const int final_out) {
;     ...
;       for (int i8 = 0; i8 < 8; ++i8) {
;         const int r = hh + 2 * (hb_ * 8 + i8);
;         const size_t row = row0 + r;
;         f32x4 v = *(const f32x4*)(sW + r * 132 + c4);
;         f32x4 o = hv[i8] + v * sc;
;         *(f32x4*)(g_h + row * D + col) = o;
;         *(u32x2*)(g_hb + row * D + col) = MK2(pack2(o[0], o[1]), pack2(o[2], o[3]));
;         if (final_out) {
;           const int b = (int)(row / T), t = (int)(row % T);
;           if (t >= 16) *(f32x4*)(g_out + ((size_t)b * 2048 + (t - 16)) * D + col) = o;
;         }
;       }
.LBB0_294:
	ds_read_b128 v[22:25], v42 offset:2112
	v_add_u32_e32 v20, 6, v64
	v_ashrrev_i32_e32 v21, 31, v20
	v_lshl_add_u64 v[20:21], s[6:7], 0, v[20:21]
	s_and_b64 vcc, exec, s[44:45]
	s_waitcnt vmcnt(13) lgkmcnt(0)
	v_pk_fma_f32 v[16:17], v[172:173], v[22:23], v[16:17]
	v_lshlrev_b64 v[22:23], 12, v[20:21]
	v_pk_fma_f32 v[18:19], v[170:171], v[24:25], v[18:19]
	v_lshl_add_u64 v[22:23], v[32:33], 0, v[22:23]
	v_lshlrev_b64 v[24:25], 11, v[20:21]
	global_store_dwordx4 v[22:23], v[16:19], off
	v_cvt_pk_bf16_f32 v22, v16, v17
	v_cvt_pk_bf16_f32 v23, v18, v19
	v_lshrrev_b32_e32 v142, 5, v24
	v_lshl_add_u64 v[24:25], v[36:37], 0, v[24:25]
	global_store_dwordx2 v[24:25], v[22:23], off
	v_mov_b32_e32 v141, 0
	v_dot2c_f32_bf16_e32 v141, v22, v22
	v_dot2c_f32_bf16_e32 v141, v23, v23
	s_nop 4
	v_add_f32_dpp v141, v141, v141 quad_perm:[1,0,3,2] row_mask:0xf bank_mask:0xf
	s_nop 1
	v_add_f32_dpp v141, v141, v141 quad_perm:[2,3,0,1] row_mask:0xf bank_mask:0xf
	s_nop 1
	v_add_f32_dpp v141, v141, v141 row_half_mirror row_mask:0xf bank_mask:0xf
	s_nop 1
	v_add_f32_dpp v141, v141, v141 row_mirror row_mask:0xf bank_mask:0xf
	v_lshl_add_u64 v[144:145], v[142:143], 0, v[146:147]
	global_store_dword v[144:145], v141, off
	s_cbranch_vccnz .LBB0_298
	s_mov_b32 s8, 0xe03f80ff
	v_mul_hi_u32 v164, v20, s8
	v_mad_u64_u32 v[22:23], s[8:9], v21, s8, v[164:165]
	v_mov_b32_e32 v164, v23
	v_mov_b32_e32 v23, v165
	s_mov_b32 s14, 0xfe03f80f
	v_mad_u64_u32 v[22:23], s[8:9], v20, s14, v[22:23]
	v_mov_b32_e32 v22, v23
	v_mov_b32_e32 v23, v165
	v_lshl_add_u64 v[22:23], v[164:165], 0, v[22:23]
	v_mad_u64_u32 v[22:23], s[8:9], v21, s14, v[22:23]
	v_alignbit_b32 v24, v23, v22, 11
	s_movk_i32 s14, 0x810
	v_mad_u64_u32 v[24:25], s[8:9], v24, s14, 0
	v_lshrrev_b32_e32 v26, 11, v23
	v_mad_u32_u24 v25, v26, s14, v25
	v_sub_co_u32_e32 v20, vcc, v20, v24
	s_nop 1
	v_subb_co_u32_e32 v21, vcc, v21, v25, vcc
	v_cmp_lt_u64_e32 vcc, 15, v[20:21]
	s_and_saveexec_b64 s[8:9], vcc
	s_cbranch_execz .LBB0_297
	v_lshrrev_b64 v[22:23], 11, v[22:23]
	v_mov_b32_e32 v24, v165
	v_mov_b32_e32 v25, v22
	v_ashrrev_i64 v[22:23], 21, v[24:25]
	v_add_u32_e32 v164, -16, v20
	v_lshl_add_u64 v[20:21], v[22:23], 0, v[164:165]
	v_lshlrev_b64 v[20:21], 12, v[20:21]
	v_lshl_add_u64 v[20:21], v[34:35], 0, v[20:21]
	global_store_dwordx4 v[20:21], v[16:19], off

; DI void epi_slab(const GemmCfg c, const f32x16 (&acc)[4], float* sW, const float* rss, const size_t row0, const int g, const int lane,
;                  float* const g_h, u16* const g_hb, float* const g_out, const int final_out) {
;     ...
;       for (int i8 = 0; i8 < 8; ++i8) {
;         const int r = hh + 2 * (hb_ * 8 + i8);
;         const size_t row = row0 + r;
;         f32x4 v = *(const f32x4*)(sW + r * 132 + c4);
;         f32x4 o = hv[i8] + v * sc;
;         *(f32x4*)(g_h + row * D + col) = o;
;         *(u32x2*)(g_hb + row * D + col) = MK2(pack2(o[0], o[1]), pack2(o[2], o[3]));
;         if (final_out) {
;           const int b = (int)(row / T), t = (int)(row % T);
;           if (t >= 16) *(f32x4*)(g_out + ((size_t)b * 2048 + (t - 16)) * D + col) = o;
;         }
;       }
.LBB0_298:
	ds_read_b128 v[18:21], v42 offset:3168
	v_add_u32_e32 v16, 8, v64
	v_ashrrev_i32_e32 v17, 31, v16
	v_lshl_add_u64 v[16:17], s[6:7], 0, v[16:17]
	v_mov_b32_e32 v171, v170
	s_waitcnt vmcnt(15) lgkmcnt(0)
	v_pk_fma_f32 v[12:13], v[172:173], v[18:19], v[12:13]
	v_lshlrev_b64 v[18:19], 12, v[16:17]
	v_pk_fma_f32 v[14:15], v[170:171], v[20:21], v[14:15]
	v_lshl_add_u64 v[18:19], v[32:33], 0, v[18:19]
	v_lshlrev_b64 v[20:21], 11, v[16:17]
	global_store_dwordx4 v[18:19], v[12:15], off
	v_cvt_pk_bf16_f32 v18, v12, v13
	v_cvt_pk_bf16_f32 v19, v14, v15
	v_lshrrev_b32_e32 v142, 5, v20
	v_lshl_add_u64 v[20:21], v[36:37], 0, v[20:21]
	s_and_b64 vcc, exec, s[44:45]
	global_store_dwordx2 v[20:21], v[18:19], off
	v_mov_b32_e32 v141, 0
	v_dot2c_f32_bf16_e32 v141, v18, v18
	v_dot2c_f32_bf16_e32 v141, v19, v19
	s_nop 4
	v_add_f32_dpp v141, v141, v141 quad_perm:[1,0,3,2] row_mask:0xf bank_mask:0xf
	s_nop 1
	v_add_f32_dpp v141, v141, v141 quad_perm:[2,3,0,1] row_mask:0xf bank_mask:0xf
	s_nop 1
	v_add_f32_dpp v141, v141, v141 row_half_mirror row_mask:0xf bank_mask:0xf
	s_nop 1
	v_add_f32_dpp v141, v141, v141 row_mirror row_mask:0xf bank_mask:0xf
	v_lshl_add_u64 v[144:145], v[142:143], 0, v[146:147]
	global_store_dword v[144:145], v141, off
	s_cbranch_vccnz .LBB0_302
	s_mov_b32 s8, 0xe03f80ff
	v_mul_hi_u32 v164, v16, s8
	v_mad_u64_u32 v[18:19], s[8:9], v17, s8, v[164:165]
	v_mov_b32_e32 v164, v19
	v_mov_b32_e32 v19, v165
	s_mov_b32 s14, 0xfe03f80f
	v_mad_u64_u32 v[18:19], s[8:9], v16, s14, v[18:19]
	v_mov_b32_e32 v18, v19
	v_mov_b32_e32 v19, v165
	v_lshl_add_u64 v[18:19], v[164:165], 0, v[18:19]
	v_mad_u64_u32 v[18:19], s[8:9], v17, s14, v[18:19]
	v_alignbit_b32 v20, v19, v18, 11
	s_movk_i32 s14, 0x810
	v_mad_u64_u32 v[20:21], s[8:9], v20, s14, 0
	v_lshrrev_b32_e32 v22, 11, v19
	v_mad_u32_u24 v21, v22, s14, v21
	v_sub_co_u32_e32 v16, vcc, v16, v20
	s_nop 1
	v_subb_co_u32_e32 v17, vcc, v17, v21, vcc
	v_cmp_lt_u64_e32 vcc, 15, v[16:17]
	s_and_saveexec_b64 s[8:9], vcc
	s_cbranch_execz .LBB0_301
	v_lshrrev_b64 v[18:19], 11, v[18:19]
	v_mov_b32_e32 v20, v165
	v_mov_b32_e32 v21, v18
	v_ashrrev_i64 v[18:19], 21, v[20:21]
	v_add_u32_e32 v164, -16, v16
	v_lshl_add_u64 v[16:17], v[18:19], 0, v[164:165]
	v_lshlrev_b64 v[16:17], 12, v[16:17]
	v_lshl_add_u64 v[16:17], v[34:35], 0, v[16:17]
	global_store_dwordx4 v[16:17], v[12:15], off

; DI void epi_slab(const GemmCfg c, const f32x16 (&acc)[4], float* sW, const float* rss, const size_t row0, const int g, const int lane,
;                  float* const g_h, u16* const g_hb, float* const g_out, const int final_out) {
;     ...
;       for (int i8 = 0; i8 < 8; ++i8) {
;         const int r = hh + 2 * (hb_ * 8 + i8);
;         const size_t row = row0 + r;
;         f32x4 v = *(const f32x4*)(sW + r * 132 + c4);
;         f32x4 o = hv[i8] + v * sc;
;         *(f32x4*)(g_h + row * D + col) = o;
;         *(u32x2*)(g_hb + row * D + col) = MK2(pack2(o[0], o[1]), pack2(o[2], o[3]));
;         if (final_out) {
;           const int b = (int)(row / T), t = (int)(row % T);
;           if (t >= 16) *(f32x4*)(g_out + ((size_t)b * 2048 + (t - 16)) * D + col) = o;
;         }
;       }
.LBB0_302:
	ds_read_b128 v[14:17], v42 offset:4224
	v_add_u32_e32 v12, 10, v64
	v_ashrrev_i32_e32 v13, 31, v12
	v_lshl_add_u64 v[12:13], s[6:7], 0, v[12:13]
	s_and_b64 vcc, exec, s[44:45]
	s_waitcnt vmcnt(17) lgkmcnt(0)
	v_pk_fma_f32 v[8:9], v[172:173], v[14:15], v[8:9]
	v_lshlrev_b64 v[14:15], 12, v[12:13]
	v_pk_fma_f32 v[10:11], v[170:171], v[16:17], v[10:11]
	v_lshl_add_u64 v[14:15], v[32:33], 0, v[14:15]
	v_lshlrev_b64 v[16:17], 11, v[12:13]
	global_store_dwordx4 v[14:15], v[8:11], off
	v_cvt_pk_bf16_f32 v14, v8, v9
	v_cvt_pk_bf16_f32 v15, v10, v11
	v_lshrrev_b32_e32 v142, 5, v16
	v_lshl_add_u64 v[16:17], v[36:37], 0, v[16:17]
	global_store_dwordx2 v[16:17], v[14:15], off
	v_mov_b32_e32 v141, 0
	v_dot2c_f32_bf16_e32 v141, v14, v14
	v_dot2c_f32_bf16_e32 v141, v15, v15
	s_nop 4
	v_add_f32_dpp v141, v141, v141 quad_perm:[1,0,3,2] row_mask:0xf bank_mask:0xf
	s_nop 1
	v_add_f32_dpp v141, v141, v141 quad_perm:[2,3,0,1] row_mask:0xf bank_mask:0xf
	s_nop 1
	v_add_f32_dpp v141, v141, v141 row_half_mirror row_mask:0xf bank_mask:0xf
	s_nop 1
	v_add_f32_dpp v141, v141, v141 row_mirror row_mask:0xf bank_mask:0xf
	v_lshl_add_u64 v[144:145], v[142:143], 0, v[146:147]
	global_store_dword v[144:145], v141, off
	s_cbranch_vccnz .LBB0_306
	s_mov_b32 s8, 0xe03f80ff
	v_mul_hi_u32 v164, v12, s8
	v_mad_u64_u32 v[14:15], s[8:9], v13, s8, v[164:165]
	v_mov_b32_e32 v164, v15
	v_mov_b32_e32 v15, v165
	s_mov_b32 s14, 0xfe03f80f
	v_mad_u64_u32 v[14:15], s[8:9], v12, s14, v[14:15]
	v_mov_b32_e32 v14, v15
	v_mov_b32_e32 v15, v165
	v_lshl_add_u64 v[14:15], v[164:165], 0, v[14:15]
	v_mad_u64_u32 v[14:15], s[8:9], v13, s14, v[14:15]
	v_alignbit_b32 v16, v15, v14, 11
	s_movk_i32 s14, 0x810
	v_mad_u64_u32 v[16:17], s[8:9], v16, s14, 0
	v_lshrrev_b32_e32 v18, 11, v15
	v_mad_u32_u24 v17, v18, s14, v17
	v_sub_co_u32_e32 v12, vcc, v12, v16
	s_nop 1
	v_subb_co_u32_e32 v13, vcc, v13, v17, vcc
	v_cmp_lt_u64_e32 vcc, 15, v[12:13]
	s_and_saveexec_b64 s[8:9], vcc
	s_cbranch_execz .LBB0_305
	v_lshrrev_b64 v[14:15], 11, v[14:15]
	v_mov_b32_e32 v16, v165
	v_mov_b32_e32 v17, v14
	v_ashrrev_i64 v[14:15], 21, v[16:17]
	v_add_u32_e32 v164, -16, v12
	v_lshl_add_u64 v[12:13], v[14:15], 0, v[164:165]
	v_lshlrev_b64 v[12:13], 12, v[12:13]
	v_lshl_add_u64 v[12:13], v[34:35], 0, v[12:13]
	global_store_dwordx4 v[12:13], v[8:11], off

; DI void epi_slab(const GemmCfg c, const f32x16 (&acc)[4], float* sW, const float* rss, const size_t row0, const int g, const int lane,
;                  float* const g_h, u16* const g_hb, float* const g_out, const int final_out) {
;     ...
;       for (int i8 = 0; i8 < 8; ++i8) {
;         const int r = hh + 2 * (hb_ * 8 + i8);
;         const size_t row = row0 + r;
;         f32x4 v = *(const f32x4*)(sW + r * 132 + c4);
;         f32x4 o = hv[i8] + v * sc;
;         *(f32x4*)(g_h + row * D + col) = o;
;         *(u32x2*)(g_hb + row * D + col) = MK2(pack2(o[0], o[1]), pack2(o[2], o[3]));
;         if (final_out) {
;           const int b = (int)(row / T), t = (int)(row % T);
;           if (t >= 16) *(f32x4*)(g_out + ((size_t)b * 2048 + (t - 16)) * D + col) = o;
;         }
;       }
.LBB0_306:
	ds_read_b128 v[10:13], v42 offset:5280
	v_add_u32_e32 v8, 12, v64
	v_ashrrev_i32_e32 v9, 31, v8
	v_lshl_add_u64 v[8:9], s[6:7], 0, v[8:9]
	v_mov_b32_e32 v171, v170
	s_waitcnt vmcnt(19) lgkmcnt(0)
	v_pk_fma_f32 v[4:5], v[172:173], v[10:11], v[4:5]
	v_lshlrev_b64 v[10:11], 12, v[8:9]
	v_pk_fma_f32 v[6:7], v[170:171], v[12:13], v[6:7]
	v_lshl_add_u64 v[10:11], v[32:33], 0, v[10:11]
	v_lshlrev_b64 v[12:13], 11, v[8:9]
	global_store_dwordx4 v[10:11], v[4:7], off
	v_cvt_pk_bf16_f32 v10, v4, v5
	v_cvt_pk_bf16_f32 v11, v6, v7
	v_lshrrev_b32_e32 v142, 5, v12
	v_lshl_add_u64 v[12:13], v[36:37], 0, v[12:13]
	s_and_b64 vcc, exec, s[44:45]
	global_store_dwordx2 v[12:13], v[10:11], off
	v_mov_b32_e32 v141, 0
	v_dot2c_f32_bf16_e32 v141, v10, v10
	v_dot2c_f32_bf16_e32 v141, v11, v11
	s_nop 4
	v_add_f32_dpp v141, v141, v141 quad_perm:[1,0,3,2] row_mask:0xf bank_mask:0xf
	s_nop 1
	v_add_f32_dpp v141, v141, v141 quad_perm:[2,3,0,1] row_mask:0xf bank_mask:0xf
	s_nop 1
	v_add_f32_dpp v141, v141, v141 row_half_mirror row_mask:0xf bank_mask:0xf
	s_nop 1
	v_add_f32_dpp v141, v141, v141 row_mirror row_mask:0xf bank_mask:0xf
	v_lshl_add_u64 v[144:145], v[142:143], 0, v[146:147]
	global_store_dword v[144:145], v141, off
	s_cbranch_vccnz .LBB0_310
	s_mov_b32 s8, 0xe03f80ff
	v_mul_hi_u32 v164, v8, s8
	v_mad_u64_u32 v[10:11], s[8:9], v9, s8, v[164:165]
	v_mov_b32_e32 v164, v11
	v_mov_b32_e32 v11, v165
	s_mov_b32 s14, 0xfe03f80f
	v_mad_u64_u32 v[10:11], s[8:9], v8, s14, v[10:11]
	v_mov_b32_e32 v10, v11
	v_mov_b32_e32 v11, v165
	v_lshl_add_u64 v[10:11], v[164:165], 0, v[10:11]
	v_mad_u64_u32 v[10:11], s[8:9], v9, s14, v[10:11]
	v_alignbit_b32 v12, v11, v10, 11
	s_movk_i32 s14, 0x810
	v_mad_u64_u32 v[12:13], s[8:9], v12, s14, 0
	v_lshrrev_b32_e32 v14, 11, v11
	v_mad_u32_u24 v13, v14, s14, v13
	v_sub_co_u32_e32 v8, vcc, v8, v12
	s_nop 1
	v_subb_co_u32_e32 v9, vcc, v9, v13, vcc
	v_cmp_lt_u64_e32 vcc, 15, v[8:9]
	s_and_saveexec_b64 s[8:9], vcc
	s_cbranch_execz .LBB0_309
	v_lshrrev_b64 v[10:11], 11, v[10:11]
	v_mov_b32_e32 v12, v165
	v_mov_b32_e32 v13, v10
	v_ashrrev_i64 v[10:11], 21, v[12:13]
	v_add_u32_e32 v164, -16, v8
	v_lshl_add_u64 v[8:9], v[10:11], 0, v[164:165]
	v_lshlrev_b64 v[8:9], 12, v[8:9]
	v_lshl_add_u64 v[8:9], v[34:35], 0, v[8:9]
	global_store_dwordx4 v[8:9], v[4:7], off

; DI void epi_slab(const GemmCfg c, const f32x16 (&acc)[4], float* sW, const float* rss, const size_t row0, const int g, const int lane,
;                  float* const g_h, u16* const g_hb, float* const g_out, const int final_out) {
;     ...
;       for (int i8 = 0; i8 < 8; ++i8) {
;         const int r = hh + 2 * (hb_ * 8 + i8);
;         const size_t row = row0 + r;
;         f32x4 v = *(const f32x4*)(sW + r * 132 + c4);
;         f32x4 o = hv[i8] + v * sc;
;         *(f32x4*)(g_h + row * D + col) = o;
;         *(u32x2*)(g_hb + row * D + col) = MK2(pack2(o[0], o[1]), pack2(o[2], o[3]));
;         if (final_out) {
;           const int b = (int)(row / T), t = (int)(row % T);
;           if (t >= 16) *(f32x4*)(g_out + ((size_t)b * 2048 + (t - 16)) * D + col) = o;
;         }
;       }
.LBB0_310:
	ds_read_b128 v[6:9], v42 offset:6336
	v_add_u32_e32 v4, 14, v64
	v_ashrrev_i32_e32 v5, 31, v4
	v_lshl_add_u64 v[4:5], s[6:7], 0, v[4:5]
	s_and_b64 vcc, exec, s[44:45]
	s_waitcnt vmcnt(21) lgkmcnt(0)
	v_pk_fma_f32 v[0:1], v[172:173], v[6:7], v[0:1]
	v_lshlrev_b64 v[6:7], 12, v[4:5]
	v_pk_fma_f32 v[2:3], v[170:171], v[8:9], v[2:3]
	v_lshl_add_u64 v[6:7], v[32:33], 0, v[6:7]
	v_lshlrev_b64 v[8:9], 11, v[4:5]
	global_store_dwordx4 v[6:7], v[0:3], off
	v_cvt_pk_bf16_f32 v6, v0, v1
	v_cvt_pk_bf16_f32 v7, v2, v3
	v_lshrrev_b32_e32 v142, 5, v8
	v_lshl_add_u64 v[8:9], v[36:37], 0, v[8:9]
	global_store_dwordx2 v[8:9], v[6:7], off
	v_mov_b32_e32 v141, 0
	v_dot2c_f32_bf16_e32 v141, v6, v6
	v_dot2c_f32_bf16_e32 v141, v7, v7
	s_nop 4
	v_add_f32_dpp v141, v141, v141 quad_perm:[1,0,3,2] row_mask:0xf bank_mask:0xf
	s_nop 1
	v_add_f32_dpp v141, v141, v141 quad_perm:[2,3,0,1] row_mask:0xf bank_mask:0xf
	s_nop 1
	v_add_f32_dpp v141, v141, v141 row_half_mirror row_mask:0xf bank_mask:0xf
	s_nop 1
	v_add_f32_dpp v141, v141, v141 row_mirror row_mask:0xf bank_mask:0xf
	v_lshl_add_u64 v[144:145], v[142:143], 0, v[146:147]
	global_store_dword v[144:145], v141, off
	s_cbranch_vccnz .LBB0_314
	s_mov_b32 s8, 0xe03f80ff
	v_mul_hi_u32 v164, v4, s8
	v_mad_u64_u32 v[6:7], s[8:9], v5, s8, v[164:165]
	v_mov_b32_e32 v164, v7
	v_mov_b32_e32 v7, v165
	s_mov_b32 s14, 0xfe03f80f
	v_mad_u64_u32 v[6:7], s[8:9], v4, s14, v[6:7]
	v_mov_b32_e32 v6, v7
	v_mov_b32_e32 v7, v165
	v_lshl_add_u64 v[6:7], v[164:165], 0, v[6:7]
	v_mad_u64_u32 v[6:7], s[8:9], v5, s14, v[6:7]
	v_alignbit_b32 v8, v7, v6, 11
	s_movk_i32 s14, 0x810
	v_mad_u64_u32 v[8:9], s[8:9], v8, s14, 0
	v_lshrrev_b32_e32 v10, 11, v7
	v_mad_u32_u24 v9, v10, s14, v9
	v_sub_co_u32_e32 v4, vcc, v4, v8
	s_nop 1
	v_subb_co_u32_e32 v5, vcc, v5, v9, vcc
	v_cmp_lt_u64_e32 vcc, 15, v[4:5]
	s_and_saveexec_b64 s[8:9], vcc
	s_cbranch_execz .LBB0_313
	v_lshrrev_b64 v[6:7], 11, v[6:7]
	v_mov_b32_e32 v8, v165
	v_mov_b32_e32 v9, v6
	v_ashrrev_i64 v[6:7], 21, v[8:9]
	v_add_u32_e32 v164, -16, v4
	v_lshl_add_u64 v[4:5], v[6:7], 0, v[164:165]
	v_lshlrev_b64 v[4:5], 12, v[4:5]
	v_lshl_add_u64 v[4:5], v[34:35], 0, v[4:5]
	global_store_dwordx4 v[4:5], v[0:3], off

; DI void epi_slab(const GemmCfg c, const f32x16 (&acc)[4], float* sW, const float* rss, const size_t row0, const int g, const int lane,
;                  float* const g_h, u16* const g_hb, float* const g_out, const int final_out) {
;     ...
;     for (int hb_ = 0; hb_ < 2; ++hb_) {
;       f32x4 hv[8];
; #pragma unroll
;       for (int i8 = 0; i8 < 8; ++i8) hv[i8] = *(const f32x4*)(g_h + (row0 + hh + 2 * (hb_ * 8 + i8)) * D + col);
; #pragma unroll
;       for (int i8 = 0; i8 < 8; ++i8) {
;         const int r = hh + 2 * (hb_ * 8 + i8);
;         const size_t row = row0 + r;
;         f32x4 v = *(const f32x4*)(sW + r * 132 + c4);
;         f32x4 o = hv[i8] + v * sc;
;         *(f32x4*)(g_h + row * D + col) = o;
;         *(u32x2*)(g_hb + row * D + col) = MK2(pack2(o[0], o[1]), pack2(o[2], o[3]));
;         if (final_out) {
;           const int b = (int)(row / T), t = (int)(row % T);
;           if (t >= 16) *(f32x4*)(g_out + ((size_t)b * 2048 + (t - 16)) * D + col) = o;
;         }
;       }
.LBB0_314:
	s_nop 0
	v_add_co_u32_e32 v0, vcc, 0x10000, v38
	ds_read_b128 v[44:47], v42 offset:7392
	s_nop 0
	v_addc_co_u32_e32 v1, vcc, 0, v39, vcc
	global_load_dwordx4 v[28:31], v[0:1], off
	v_add_co_u32_e32 v0, vcc, 0x12000, v38
	v_mov_b32_e32 v171, v170
	s_nop 0
	v_addc_co_u32_e32 v1, vcc, 0, v39, vcc
	global_load_dwordx4 v[24:27], v[0:1], off
	v_add_co_u32_e32 v0, vcc, 0x14000, v38
	s_waitcnt vmcnt(1) lgkmcnt(0)
	v_pk_fma_f32 v[30:31], v[170:171], v[46:47], v[30:31]
	v_addc_co_u32_e32 v1, vcc, 0, v39, vcc
	global_load_dwordx4 v[20:23], v[0:1], off
	v_add_co_u32_e32 v0, vcc, 0x16000, v38
	v_pk_fma_f32 v[28:29], v[172:173], v[44:45], v[28:29]
	s_nop 0
	v_addc_co_u32_e32 v1, vcc, 0, v39, vcc
	global_load_dwordx4 v[16:19], v[0:1], off
	v_add_co_u32_e32 v0, vcc, 0x18000, v38
	s_nop 1
	v_addc_co_u32_e32 v1, vcc, 0, v39, vcc
	global_load_dwordx4 v[12:15], v[0:1], off
	v_add_co_u32_e32 v0, vcc, 0x1a000, v38
	s_nop 1
	v_addc_co_u32_e32 v1, vcc, 0, v39, vcc
	global_load_dwordx4 v[8:11], v[0:1], off
	v_add_co_u32_e32 v0, vcc, 0x1c000, v38
	s_nop 1
	v_addc_co_u32_e32 v1, vcc, 0, v39, vcc
	global_load_dwordx4 v[4:7], v[0:1], off
	v_add_co_u32_e32 v0, vcc, 0x1e000, v38
	v_add_u32_e32 v38, 16, v64
	s_nop 0
	v_addc_co_u32_e32 v1, vcc, 0, v39, vcc
	global_load_dwordx4 v[0:3], v[0:1], off
	v_ashrrev_i32_e32 v39, 31, v38
	v_lshl_add_u64 v[38:39], s[6:7], 0, v[38:39]
	v_lshlrev_b64 v[40:41], 12, v[38:39]
	v_lshl_add_u64 v[40:41], v[32:33], 0, v[40:41]
	v_lshlrev_b64 v[44:45], 11, v[38:39]
	global_store_dwordx4 v[40:41], v[28:31], off
	v_cvt_pk_bf16_f32 v40, v28, v29
	v_cvt_pk_bf16_f32 v41, v30, v31
	v_lshrrev_b32_e32 v142, 5, v44
	v_lshl_add_u64 v[44:45], v[36:37], 0, v[44:45]
	s_and_b64 vcc, exec, s[44:45]
	global_store_dwordx2 v[44:45], v[40:41], off
	v_mov_b32_e32 v141, 0
	v_dot2c_f32_bf16_e32 v141, v40, v40
	v_dot2c_f32_bf16_e32 v141, v41, v41
	s_nop 4
	v_add_f32_dpp v141, v141, v141 quad_perm:[1,0,3,2] row_mask:0xf bank_mask:0xf
	s_nop 1
	v_add_f32_dpp v141, v141, v141 quad_perm:[2,3,0,1] row_mask:0xf bank_mask:0xf
	s_nop 1
	v_add_f32_dpp v141, v141, v141 row_half_mirror row_mask:0xf bank_mask:0xf
	s_nop 1
	v_add_f32_dpp v141, v141, v141 row_mirror row_mask:0xf bank_mask:0xf
	v_lshl_add_u64 v[144:145], v[142:143], 0, v[146:147]
	global_store_dword v[144:145], v141, off
	s_cbranch_vccnz .LBB0_318
	s_mov_b32 s8, 0xe03f80ff
	v_mul_hi_u32 v164, v38, s8
	v_mad_u64_u32 v[40:41], s[8:9], v39, s8, v[164:165]
	v_mov_b32_e32 v164, v41
	v_mov_b32_e32 v41, v165
	s_mov_b32 s14, 0xfe03f80f
	v_mad_u64_u32 v[40:41], s[8:9], v38, s14, v[40:41]
	v_mov_b32_e32 v40, v41
	v_mov_b32_e32 v41, v165
	v_lshl_add_u64 v[40:41], v[164:165], 0, v[40:41]
	v_mad_u64_u32 v[40:41], s[8:9], v39, s14, v[40:41]
	v_alignbit_b32 v43, v41, v40, 11
	s_movk_i32 s14, 0x810
	v_mad_u64_u32 v[44:45], s[8:9], v43, s14, 0
	v_lshrrev_b32_e32 v43, 11, v41
	v_mad_u32_u24 v43, v43, s14, v45
	v_sub_co_u32_e32 v38, vcc, v38, v44
	s_nop 1
	v_subb_co_u32_e32 v39, vcc, v39, v43, vcc
	v_cmp_lt_u64_e32 vcc, 15, v[38:39]
	s_and_saveexec_b64 s[8:9], vcc
	s_cbranch_execz .LBB0_317
	v_lshrrev_b64 v[40:41], 11, v[40:41]
	v_mov_b32_e32 v44, v165
	v_mov_b32_e32 v45, v40
	v_ashrrev_i64 v[40:41], 21, v[44:45]
	v_add_u32_e32 v164, -16, v38
	v_lshl_add_u64 v[38:39], v[40:41], 0, v[164:165]
	v_lshlrev_b64 v[38:39], 12, v[38:39]
	v_lshl_add_u64 v[38:39], v[34:35], 0, v[38:39]
	global_store_dwordx4 v[38:39], v[28:31], off

; DI void epi_slab(const GemmCfg c, const f32x16 (&acc)[4], float* sW, const float* rss, const size_t row0, const int g, const int lane,
;                  float* const g_h, u16* const g_hb, float* const g_out, const int final_out) {
;     ...
;       for (int i8 = 0; i8 < 8; ++i8) {
;         const int r = hh + 2 * (hb_ * 8 + i8);
;         const size_t row = row0 + r;
;         f32x4 v = *(const f32x4*)(sW + r * 132 + c4);
;         f32x4 o = hv[i8] + v * sc;
;         *(f32x4*)(g_h + row * D + col) = o;
;         *(u32x2*)(g_hb + row * D + col) = MK2(pack2(o[0], o[1]), pack2(o[2], o[3]));
;         if (final_out) {
;           const int b = (int)(row / T), t = (int)(row % T);
;           if (t >= 16) *(f32x4*)(g_out + ((size_t)b * 2048 + (t - 16)) * D + col) = o;
;         }
;       }
.LBB0_318:
	ds_read_b128 v[38:41], v42 offset:8448
	v_add_u32_e32 v28, 18, v64
	v_ashrrev_i32_e32 v29, 31, v28
	v_lshl_add_u64 v[28:29], s[6:7], 0, v[28:29]
	v_lshlrev_b64 v[30:31], 12, v[28:29]
	s_waitcnt vmcnt(9) lgkmcnt(0)
	v_pk_fma_f32 v[26:27], v[170:171], v[40:41], v[26:27]
	v_pk_fma_f32 v[24:25], v[172:173], v[38:39], v[24:25]
	v_lshl_add_u64 v[30:31], v[32:33], 0, v[30:31]
	v_lshlrev_b64 v[38:39], 11, v[28:29]
	global_store_dwordx4 v[30:31], v[24:27], off
	v_cvt_pk_bf16_f32 v30, v24, v25
	v_cvt_pk_bf16_f32 v31, v26, v27
	v_lshrrev_b32_e32 v142, 5, v38
	v_lshl_add_u64 v[38:39], v[36:37], 0, v[38:39]
	s_and_b64 vcc, exec, s[44:45]
	global_store_dwordx2 v[38:39], v[30:31], off
	v_mov_b32_e32 v141, 0
	v_dot2c_f32_bf16_e32 v141, v30, v30
	v_dot2c_f32_bf16_e32 v141, v31, v31
	s_nop 4
	v_add_f32_dpp v141, v141, v141 quad_perm:[1,0,3,2] row_mask:0xf bank_mask:0xf
	s_nop 1
	v_add_f32_dpp v141, v141, v141 quad_perm:[2,3,0,1] row_mask:0xf bank_mask:0xf
	s_nop 1
	v_add_f32_dpp v141, v141, v141 row_half_mirror row_mask:0xf bank_mask:0xf
	s_nop 1
	v_add_f32_dpp v141, v141, v141 row_mirror row_mask:0xf bank_mask:0xf
	v_lshl_add_u64 v[144:145], v[142:143], 0, v[146:147]
	global_store_dword v[144:145], v141, off
	s_cbranch_vccnz .LBB0_322
	s_mov_b32 s8, 0xe03f80ff
	v_mul_hi_u32 v164, v28, s8
	v_mad_u64_u32 v[30:31], s[8:9], v29, s8, v[164:165]
	v_mov_b32_e32 v164, v31
	v_mov_b32_e32 v31, v165
	s_mov_b32 s14, 0xfe03f80f
	v_mad_u64_u32 v[30:31], s[8:9], v28, s14, v[30:31]
	v_mov_b32_e32 v30, v31
	v_mov_b32_e32 v31, v165
	v_lshl_add_u64 v[30:31], v[164:165], 0, v[30:31]
	v_mad_u64_u32 v[30:31], s[8:9], v29, s14, v[30:31]
	v_alignbit_b32 v38, v31, v30, 11
	s_movk_i32 s14, 0x810
	v_mad_u64_u32 v[38:39], s[8:9], v38, s14, 0
	v_lshrrev_b32_e32 v40, 11, v31
	v_mad_u32_u24 v39, v40, s14, v39
	v_sub_co_u32_e32 v28, vcc, v28, v38
	s_nop 1
	v_subb_co_u32_e32 v29, vcc, v29, v39, vcc
	v_cmp_lt_u64_e32 vcc, 15, v[28:29]
	s_and_saveexec_b64 s[8:9], vcc
	s_cbranch_execz .LBB0_321
	v_lshrrev_b64 v[30:31], 11, v[30:31]
	v_mov_b32_e32 v38, v165
	v_mov_b32_e32 v39, v30
	v_ashrrev_i64 v[30:31], 21, v[38:39]
	v_add_u32_e32 v164, -16, v28
	v_lshl_add_u64 v[28:29], v[30:31], 0, v[164:165]
	v_lshlrev_b64 v[28:29], 12, v[28:29]
	v_lshl_add_u64 v[28:29], v[34:35], 0, v[28:29]
	global_store_dwordx4 v[28:29], v[24:27], off

; DI void epi_slab(const GemmCfg c, const f32x16 (&acc)[4], float* sW, const float* rss, const size_t row0, const int g, const int lane,
;                  float* const g_h, u16* const g_hb, float* const g_out, const int final_out) {
;     ...
;       for (int i8 = 0; i8 < 8; ++i8) {
;         const int r = hh + 2 * (hb_ * 8 + i8);
;         const size_t row = row0 + r;
;         f32x4 v = *(const f32x4*)(sW + r * 132 + c4);
;         f32x4 o = hv[i8] + v * sc;
;         *(f32x4*)(g_h + row * D + col) = o;
;         *(u32x2*)(g_hb + row * D + col) = MK2(pack2(o[0], o[1]), pack2(o[2], o[3]));
;         if (final_out) {
;           const int b = (int)(row / T), t = (int)(row % T);
;           if (t >= 16) *(f32x4*)(g_out + ((size_t)b * 2048 + (t - 16)) * D + col) = o;
;         }
;       }
.LBB0_322:
	ds_read_b128 v[26:29], v42 offset:9504
	v_add_u32_e32 v24, 20, v64
	v_ashrrev_i32_e32 v25, 31, v24
	v_lshl_add_u64 v[24:25], s[6:7], 0, v[24:25]
	v_mov_b32_e32 v171, v170
	s_waitcnt vmcnt(11) lgkmcnt(0)
	v_pk_fma_f32 v[20:21], v[172:173], v[26:27], v[20:21]
	v_lshlrev_b64 v[26:27], 12, v[24:25]
	v_pk_fma_f32 v[22:23], v[170:171], v[28:29], v[22:23]
	v_lshl_add_u64 v[26:27], v[32:33], 0, v[26:27]
	v_lshlrev_b64 v[28:29], 11, v[24:25]
	global_store_dwordx4 v[26:27], v[20:23], off
	v_cvt_pk_bf16_f32 v26, v20, v21
	v_cvt_pk_bf16_f32 v27, v22, v23
	v_lshrrev_b32_e32 v142, 5, v28
	v_lshl_add_u64 v[28:29], v[36:37], 0, v[28:29]
	s_and_b64 vcc, exec, s[44:45]
	global_store_dwordx2 v[28:29], v[26:27], off
	v_mov_b32_e32 v141, 0
	v_dot2c_f32_bf16_e32 v141, v26, v26
	v_dot2c_f32_bf16_e32 v141, v27, v27
	s_nop 4
	v_add_f32_dpp v141, v141, v141 quad_perm:[1,0,3,2] row_mask:0xf bank_mask:0xf
	s_nop 1
	v_add_f32_dpp v141, v141, v141 quad_perm:[2,3,0,1] row_mask:0xf bank_mask:0xf
	s_nop 1
	v_add_f32_dpp v141, v141, v141 row_half_mirror row_mask:0xf bank_mask:0xf
	s_nop 1
	v_add_f32_dpp v141, v141, v141 row_mirror row_mask:0xf bank_mask:0xf
	v_lshl_add_u64 v[144:145], v[142:143], 0, v[146:147]
	global_store_dword v[144:145], v141, off
	s_cbranch_vccnz .LBB0_326
	s_mov_b32 s8, 0xe03f80ff
	v_mul_hi_u32 v164, v24, s8
	v_mad_u64_u32 v[26:27], s[8:9], v25, s8, v[164:165]
	v_mov_b32_e32 v164, v27
	v_mov_b32_e32 v27, v165
	s_mov_b32 s14, 0xfe03f80f
	v_mad_u64_u32 v[26:27], s[8:9], v24, s14, v[26:27]
	v_mov_b32_e32 v26, v27
	v_mov_b32_e32 v27, v165
	v_lshl_add_u64 v[26:27], v[164:165], 0, v[26:27]
	v_mad_u64_u32 v[26:27], s[8:9], v25, s14, v[26:27]
	v_alignbit_b32 v28, v27, v26, 11
	s_movk_i32 s14, 0x810
	v_mad_u64_u32 v[28:29], s[8:9], v28, s14, 0
	v_lshrrev_b32_e32 v30, 11, v27
	v_mad_u32_u24 v29, v30, s14, v29
	v_sub_co_u32_e32 v24, vcc, v24, v28
	s_nop 1
	v_subb_co_u32_e32 v25, vcc, v25, v29, vcc
	v_cmp_lt_u64_e32 vcc, 15, v[24:25]
	s_and_saveexec_b64 s[8:9], vcc
	s_cbranch_execz .LBB0_325
	v_lshrrev_b64 v[26:27], 11, v[26:27]
	v_mov_b32_e32 v28, v165
	v_mov_b32_e32 v29, v26
	v_ashrrev_i64 v[26:27], 21, v[28:29]
	v_add_u32_e32 v164, -16, v24
	v_lshl_add_u64 v[24:25], v[26:27], 0, v[164:165]
	v_lshlrev_b64 v[24:25], 12, v[24:25]
	v_lshl_add_u64 v[24:25], v[34:35], 0, v[24:25]
	global_store_dwordx4 v[24:25], v[20:23], off

; DI void epi_slab(const GemmCfg c, const f32x16 (&acc)[4], float* sW, const float* rss, const size_t row0, const int g, const int lane,
;                  float* const g_h, u16* const g_hb, float* const g_out, const int final_out) {
;     ...
;       for (int i8 = 0; i8 < 8; ++i8) {
;         const int r = hh + 2 * (hb_ * 8 + i8);
;         const size_t row = row0 + r;
;         f32x4 v = *(const f32x4*)(sW + r * 132 + c4);
;         f32x4 o = hv[i8] + v * sc;
;         *(f32x4*)(g_h + row * D + col) = o;
;         *(u32x2*)(g_hb + row * D + col) = MK2(pack2(o[0], o[1]), pack2(o[2], o[3]));
;         if (final_out) {
;           const int b = (int)(row / T), t = (int)(row % T);
;           if (t >= 16) *(f32x4*)(g_out + ((size_t)b * 2048 + (t - 16)) * D + col) = o;
;         }
;       }
.LBB0_326:
	ds_read_b128 v[22:25], v42 offset:10560
	v_add_u32_e32 v20, 22, v64
	v_ashrrev_i32_e32 v21, 31, v20
	v_lshl_add_u64 v[20:21], s[6:7], 0, v[20:21]
	s_and_b64 vcc, exec, s[44:45]
	s_waitcnt vmcnt(13) lgkmcnt(0)
	v_pk_fma_f32 v[16:17], v[172:173], v[22:23], v[16:17]
	v_lshlrev_b64 v[22:23], 12, v[20:21]
	v_pk_fma_f32 v[18:19], v[170:171], v[24:25], v[18:19]
	v_lshl_add_u64 v[22:23], v[32:33], 0, v[22:23]
	v_lshlrev_b64 v[24:25], 11, v[20:21]
	global_store_dwordx4 v[22:23], v[16:19], off
	v_cvt_pk_bf16_f32 v22, v16, v17
	v_cvt_pk_bf16_f32 v23, v18, v19
	v_lshrrev_b32_e32 v142, 5, v24
	v_lshl_add_u64 v[24:25], v[36:37], 0, v[24:25]
	global_store_dwordx2 v[24:25], v[22:23], off
	v_mov_b32_e32 v141, 0
	v_dot2c_f32_bf16_e32 v141, v22, v22
	v_dot2c_f32_bf16_e32 v141, v23, v23
	s_nop 4
	v_add_f32_dpp v141, v141, v141 quad_perm:[1,0,3,2] row_mask:0xf bank_mask:0xf
	s_nop 1
	v_add_f32_dpp v141, v141, v141 quad_perm:[2,3,0,1] row_mask:0xf bank_mask:0xf
	s_nop 1
	v_add_f32_dpp v141, v141, v141 row_half_mirror row_mask:0xf bank_mask:0xf
	s_nop 1
	v_add_f32_dpp v141, v141, v141 row_mirror row_mask:0xf bank_mask:0xf
	v_lshl_add_u64 v[144:145], v[142:143], 0, v[146:147]
	global_store_dword v[144:145], v141, off
	s_cbranch_vccnz .LBB0_330
	s_mov_b32 s8, 0xe03f80ff
	v_mul_hi_u32 v164, v20, s8
	v_mad_u64_u32 v[22:23], s[8:9], v21, s8, v[164:165]
	v_mov_b32_e32 v164, v23
	v_mov_b32_e32 v23, v165
	s_mov_b32 s14, 0xfe03f80f
	v_mad_u64_u32 v[22:23], s[8:9], v20, s14, v[22:23]
	v_mov_b32_e32 v22, v23
	v_mov_b32_e32 v23, v165
	v_lshl_add_u64 v[22:23], v[164:165], 0, v[22:23]
	v_mad_u64_u32 v[22:23], s[8:9], v21, s14, v[22:23]
	v_alignbit_b32 v24, v23, v22, 11
	s_movk_i32 s14, 0x810
	v_mad_u64_u32 v[24:25], s[8:9], v24, s14, 0
	v_lshrrev_b32_e32 v26, 11, v23
	v_mad_u32_u24 v25, v26, s14, v25
	v_sub_co_u32_e32 v20, vcc, v20, v24
	s_nop 1
	v_subb_co_u32_e32 v21, vcc, v21, v25, vcc
	v_cmp_lt_u64_e32 vcc, 15, v[20:21]
	s_and_saveexec_b64 s[8:9], vcc
	s_cbranch_execz .LBB0_329
	v_lshrrev_b64 v[22:23], 11, v[22:23]
	v_mov_b32_e32 v24, v165
	v_mov_b32_e32 v25, v22
	v_ashrrev_i64 v[22:23], 21, v[24:25]
	v_add_u32_e32 v164, -16, v20
	v_lshl_add_u64 v[20:21], v[22:23], 0, v[164:165]
	v_lshlrev_b64 v[20:21], 12, v[20:21]
	v_lshl_add_u64 v[20:21], v[34:35], 0, v[20:21]
	global_store_dwordx4 v[20:21], v[16:19], off

; DI void epi_slab(const GemmCfg c, const f32x16 (&acc)[4], float* sW, const float* rss, const size_t row0, const int g, const int lane,
;                  float* const g_h, u16* const g_hb, float* const g_out, const int final_out) {
;     ...
;       for (int i8 = 0; i8 < 8; ++i8) {
;         const int r = hh + 2 * (hb_ * 8 + i8);
;         const size_t row = row0 + r;
;         f32x4 v = *(const f32x4*)(sW + r * 132 + c4);
;         f32x4 o = hv[i8] + v * sc;
;         *(f32x4*)(g_h + row * D + col) = o;
;         *(u32x2*)(g_hb + row * D + col) = MK2(pack2(o[0], o[1]), pack2(o[2], o[3]));
;         if (final_out) {
;           const int b = (int)(row / T), t = (int)(row % T);
;           if (t >= 16) *(f32x4*)(g_out + ((size_t)b * 2048 + (t - 16)) * D + col) = o;
;         }
;       }
.LBB0_330:
	ds_read_b128 v[18:21], v42 offset:11616
	v_add_u32_e32 v16, 24, v64
	v_ashrrev_i32_e32 v17, 31, v16
	v_lshl_add_u64 v[16:17], s[6:7], 0, v[16:17]
	v_mov_b32_e32 v171, v170
	s_waitcnt vmcnt(15) lgkmcnt(0)
	v_pk_fma_f32 v[12:13], v[172:173], v[18:19], v[12:13]
	v_lshlrev_b64 v[18:19], 12, v[16:17]
	v_pk_fma_f32 v[14:15], v[170:171], v[20:21], v[14:15]
	v_lshl_add_u64 v[18:19], v[32:33], 0, v[18:19]
	v_lshlrev_b64 v[20:21], 11, v[16:17]
	global_store_dwordx4 v[18:19], v[12:15], off
	v_cvt_pk_bf16_f32 v18, v12, v13
	v_cvt_pk_bf16_f32 v19, v14, v15
	v_lshrrev_b32_e32 v142, 5, v20
	v_lshl_add_u64 v[20:21], v[36:37], 0, v[20:21]
	s_and_b64 vcc, exec, s[44:45]
	global_store_dwordx2 v[20:21], v[18:19], off
	v_mov_b32_e32 v141, 0
	v_dot2c_f32_bf16_e32 v141, v18, v18
	v_dot2c_f32_bf16_e32 v141, v19, v19
	s_nop 4
	v_add_f32_dpp v141, v141, v141 quad_perm:[1,0,3,2] row_mask:0xf bank_mask:0xf
	s_nop 1
	v_add_f32_dpp v141, v141, v141 quad_perm:[2,3,0,1] row_mask:0xf bank_mask:0xf
	s_nop 1
	v_add_f32_dpp v141, v141, v141 row_half_mirror row_mask:0xf bank_mask:0xf
	s_nop 1
	v_add_f32_dpp v141, v141, v141 row_mirror row_mask:0xf bank_mask:0xf
	v_lshl_add_u64 v[144:145], v[142:143], 0, v[146:147]
	global_store_dword v[144:145], v141, off
	s_cbranch_vccnz .LBB0_334
	s_mov_b32 s8, 0xe03f80ff
	v_mul_hi_u32 v164, v16, s8
	v_mad_u64_u32 v[18:19], s[8:9], v17, s8, v[164:165]
	v_mov_b32_e32 v164, v19
	v_mov_b32_e32 v19, v165
	s_mov_b32 s14, 0xfe03f80f
	v_mad_u64_u32 v[18:19], s[8:9], v16, s14, v[18:19]
	v_mov_b32_e32 v18, v19
	v_mov_b32_e32 v19, v165
	v_lshl_add_u64 v[18:19], v[164:165], 0, v[18:19]
	v_mad_u64_u32 v[18:19], s[8:9], v17, s14, v[18:19]
	v_alignbit_b32 v20, v19, v18, 11
	s_movk_i32 s14, 0x810
	v_mad_u64_u32 v[20:21], s[8:9], v20, s14, 0
	v_lshrrev_b32_e32 v22, 11, v19
	v_mad_u32_u24 v21, v22, s14, v21
	v_sub_co_u32_e32 v16, vcc, v16, v20
	s_nop 1
	v_subb_co_u32_e32 v17, vcc, v17, v21, vcc
	v_cmp_lt_u64_e32 vcc, 15, v[16:17]
	s_and_saveexec_b64 s[8:9], vcc
	s_cbranch_execz .LBB0_333
	v_lshrrev_b64 v[18:19], 11, v[18:19]
	v_mov_b32_e32 v20, v165
	v_mov_b32_e32 v21, v18
	v_ashrrev_i64 v[18:19], 21, v[20:21]
	v_add_u32_e32 v164, -16, v16
	v_lshl_add_u64 v[16:17], v[18:19], 0, v[164:165]
	v_lshlrev_b64 v[16:17], 12, v[16:17]
	v_lshl_add_u64 v[16:17], v[34:35], 0, v[16:17]
	global_store_dwordx4 v[16:17], v[12:15], off

; DI void epi_slab(const GemmCfg c, const f32x16 (&acc)[4], float* sW, const float* rss, const size_t row0, const int g, const int lane,
;                  float* const g_h, u16* const g_hb, float* const g_out, const int final_out) {
;     ...
;       for (int i8 = 0; i8 < 8; ++i8) {
;         const int r = hh + 2 * (hb_ * 8 + i8);
;         const size_t row = row0 + r;
;         f32x4 v = *(const f32x4*)(sW + r * 132 + c4);
;         f32x4 o = hv[i8] + v * sc;
;         *(f32x4*)(g_h + row * D + col) = o;
;         *(u32x2*)(g_hb + row * D + col) = MK2(pack2(o[0], o[1]), pack2(o[2], o[3]));
;         if (final_out) {
;           const int b = (int)(row / T), t = (int)(row % T);
;           if (t >= 16) *(f32x4*)(g_out + ((size_t)b * 2048 + (t - 16)) * D + col) = o;
;         }
;       }
.LBB0_334:
	ds_read_b128 v[14:17], v42 offset:12672
	v_add_u32_e32 v12, 26, v64
	v_ashrrev_i32_e32 v13, 31, v12
	v_lshl_add_u64 v[12:13], s[6:7], 0, v[12:13]
	s_and_b64 vcc, exec, s[44:45]
	s_waitcnt vmcnt(17) lgkmcnt(0)
	v_pk_fma_f32 v[8:9], v[172:173], v[14:15], v[8:9]
	v_lshlrev_b64 v[14:15], 12, v[12:13]
	v_pk_fma_f32 v[10:11], v[170:171], v[16:17], v[10:11]
	v_lshl_add_u64 v[14:15], v[32:33], 0, v[14:15]
	v_lshlrev_b64 v[16:17], 11, v[12:13]
	global_store_dwordx4 v[14:15], v[8:11], off
	v_cvt_pk_bf16_f32 v14, v8, v9
	v_cvt_pk_bf16_f32 v15, v10, v11
	v_lshrrev_b32_e32 v142, 5, v16
	v_lshl_add_u64 v[16:17], v[36:37], 0, v[16:17]
	global_store_dwordx2 v[16:17], v[14:15], off
	v_mov_b32_e32 v141, 0
	v_dot2c_f32_bf16_e32 v141, v14, v14
	v_dot2c_f32_bf16_e32 v141, v15, v15
	s_nop 4
	v_add_f32_dpp v141, v141, v141 quad_perm:[1,0,3,2] row_mask:0xf bank_mask:0xf
	s_nop 1
	v_add_f32_dpp v141, v141, v141 quad_perm:[2,3,0,1] row_mask:0xf bank_mask:0xf
	s_nop 1
	v_add_f32_dpp v141, v141, v141 row_half_mirror row_mask:0xf bank_mask:0xf
	s_nop 1
	v_add_f32_dpp v141, v141, v141 row_mirror row_mask:0xf bank_mask:0xf
	v_lshl_add_u64 v[144:145], v[142:143], 0, v[146:147]
	global_store_dword v[144:145], v141, off
	s_cbranch_vccnz .LBB0_338
	s_mov_b32 s8, 0xe03f80ff
	v_mul_hi_u32 v164, v12, s8
	v_mad_u64_u32 v[14:15], s[8:9], v13, s8, v[164:165]
	v_mov_b32_e32 v164, v15
	v_mov_b32_e32 v15, v165
	s_mov_b32 s14, 0xfe03f80f
	v_mad_u64_u32 v[14:15], s[8:9], v12, s14, v[14:15]
	v_mov_b32_e32 v14, v15
	v_mov_b32_e32 v15, v165
	v_lshl_add_u64 v[14:15], v[164:165], 0, v[14:15]
	v_mad_u64_u32 v[14:15], s[8:9], v13, s14, v[14:15]
	v_alignbit_b32 v16, v15, v14, 11
	s_movk_i32 s14, 0x810
	v_mad_u64_u32 v[16:17], s[8:9], v16, s14, 0
	v_lshrrev_b32_e32 v18, 11, v15
	v_mad_u32_u24 v17, v18, s14, v17
	v_sub_co_u32_e32 v12, vcc, v12, v16
	s_nop 1
	v_subb_co_u32_e32 v13, vcc, v13, v17, vcc
	v_cmp_lt_u64_e32 vcc, 15, v[12:13]
	s_and_saveexec_b64 s[8:9], vcc
	s_cbranch_execz .LBB0_337
	v_lshrrev_b64 v[14:15], 11, v[14:15]
	v_mov_b32_e32 v16, v165
	v_mov_b32_e32 v17, v14
	v_ashrrev_i64 v[14:15], 21, v[16:17]
	v_add_u32_e32 v164, -16, v12
	v_lshl_add_u64 v[12:13], v[14:15], 0, v[164:165]
	v_lshlrev_b64 v[12:13], 12, v[12:13]
	v_lshl_add_u64 v[12:13], v[34:35], 0, v[12:13]
	global_store_dwordx4 v[12:13], v[8:11], off

; DI void epi_slab(const GemmCfg c, const f32x16 (&acc)[4], float* sW, const float* rss, const size_t row0, const int g, const int lane,
;                  float* const g_h, u16* const g_hb, float* const g_out, const int final_out) {
;     ...
;       for (int i8 = 0; i8 < 8; ++i8) {
;         const int r = hh + 2 * (hb_ * 8 + i8);
;         const size_t row = row0 + r;
;         f32x4 v = *(const f32x4*)(sW + r * 132 + c4);
;         f32x4 o = hv[i8] + v * sc;
;         *(f32x4*)(g_h + row * D + col) = o;
;         *(u32x2*)(g_hb + row * D + col) = MK2(pack2(o[0], o[1]), pack2(o[2], o[3]));
;         if (final_out) {
;           const int b = (int)(row / T), t = (int)(row % T);
;           if (t >= 16) *(f32x4*)(g_out + ((size_t)b * 2048 + (t - 16)) * D + col) = o;
;         }
;       }
.LBB0_338:
	ds_read_b128 v[10:13], v42 offset:13728
	v_add_u32_e32 v8, 28, v64
	v_ashrrev_i32_e32 v9, 31, v8
	v_lshl_add_u64 v[8:9], s[6:7], 0, v[8:9]
	v_mov_b32_e32 v171, v170
	s_waitcnt vmcnt(19) lgkmcnt(0)
	v_pk_fma_f32 v[4:5], v[172:173], v[10:11], v[4:5]
	v_lshlrev_b64 v[10:11], 12, v[8:9]
	v_pk_fma_f32 v[6:7], v[170:171], v[12:13], v[6:7]
	v_lshl_add_u64 v[10:11], v[32:33], 0, v[10:11]
	v_lshlrev_b64 v[12:13], 11, v[8:9]
	global_store_dwordx4 v[10:11], v[4:7], off
	v_cvt_pk_bf16_f32 v10, v4, v5
	v_cvt_pk_bf16_f32 v11, v6, v7
	v_lshrrev_b32_e32 v142, 5, v12
	v_lshl_add_u64 v[12:13], v[36:37], 0, v[12:13]
	s_and_b64 vcc, exec, s[44:45]
	global_store_dwordx2 v[12:13], v[10:11], off
	v_mov_b32_e32 v141, 0
	v_dot2c_f32_bf16_e32 v141, v10, v10
	v_dot2c_f32_bf16_e32 v141, v11, v11
	s_nop 4
	v_add_f32_dpp v141, v141, v141 quad_perm:[1,0,3,2] row_mask:0xf bank_mask:0xf
	s_nop 1
	v_add_f32_dpp v141, v141, v141 quad_perm:[2,3,0,1] row_mask:0xf bank_mask:0xf
	s_nop 1
	v_add_f32_dpp v141, v141, v141 row_half_mirror row_mask:0xf bank_mask:0xf
	s_nop 1
	v_add_f32_dpp v141, v141, v141 row_mirror row_mask:0xf bank_mask:0xf
	v_lshl_add_u64 v[144:145], v[142:143], 0, v[146:147]
	global_store_dword v[144:145], v141, off
	s_cbranch_vccnz .LBB0_342
	s_mov_b32 s8, 0xe03f80ff
	v_mul_hi_u32 v164, v8, s8
	v_mad_u64_u32 v[10:11], s[8:9], v9, s8, v[164:165]
	v_mov_b32_e32 v164, v11
	v_mov_b32_e32 v11, v165
	s_mov_b32 s14, 0xfe03f80f
	v_mad_u64_u32 v[10:11], s[8:9], v8, s14, v[10:11]
	v_mov_b32_e32 v10, v11
	v_mov_b32_e32 v11, v165
	v_lshl_add_u64 v[10:11], v[164:165], 0, v[10:11]
	v_mad_u64_u32 v[10:11], s[8:9], v9, s14, v[10:11]
	v_alignbit_b32 v12, v11, v10, 11
	s_movk_i32 s14, 0x810
	v_mad_u64_u32 v[12:13], s[8:9], v12, s14, 0
	v_lshrrev_b32_e32 v14, 11, v11
	v_mad_u32_u24 v13, v14, s14, v13
	v_sub_co_u32_e32 v8, vcc, v8, v12
	s_nop 1
	v_subb_co_u32_e32 v9, vcc, v9, v13, vcc
	v_cmp_lt_u64_e32 vcc, 15, v[8:9]
	s_and_saveexec_b64 s[8:9], vcc
	s_cbranch_execz .LBB0_341
	v_lshrrev_b64 v[10:11], 11, v[10:11]
	v_mov_b32_e32 v12, v165
	v_mov_b32_e32 v13, v10
	v_ashrrev_i64 v[10:11], 21, v[12:13]
	v_add_u32_e32 v164, -16, v8
	v_lshl_add_u64 v[8:9], v[10:11], 0, v[164:165]
	v_lshlrev_b64 v[8:9], 12, v[8:9]
	v_lshl_add_u64 v[8:9], v[34:35], 0, v[8:9]
	global_store_dwordx4 v[8:9], v[4:7], off

; DI void epi_slab(const GemmCfg c, const f32x16 (&acc)[4], float* sW, const float* rss, const size_t row0, const int g, const int lane,
;                  float* const g_h, u16* const g_hb, float* const g_out, const int final_out) {
;     ...
;       for (int i8 = 0; i8 < 8; ++i8) {
;         const int r = hh + 2 * (hb_ * 8 + i8);
;         const size_t row = row0 + r;
;         f32x4 v = *(const f32x4*)(sW + r * 132 + c4);
;         f32x4 o = hv[i8] + v * sc;
;         *(f32x4*)(g_h + row * D + col) = o;
;         *(u32x2*)(g_hb + row * D + col) = MK2(pack2(o[0], o[1]), pack2(o[2], o[3]));
;         if (final_out) {
;           const int b = (int)(row / T), t = (int)(row % T);
;           if (t >= 16) *(f32x4*)(g_out + ((size_t)b * 2048 + (t - 16)) * D + col) = o;
;         }
;       }
.LBB0_342:
	ds_read_b128 v[6:9], v42 offset:14784
	v_add_u32_e32 v4, 30, v64
	v_ashrrev_i32_e32 v5, 31, v4
	v_lshl_add_u64 v[4:5], s[6:7], 0, v[4:5]
	s_and_b64 vcc, exec, s[44:45]
	s_waitcnt vmcnt(21) lgkmcnt(0)
	v_pk_fma_f32 v[0:1], v[172:173], v[6:7], v[0:1]
	v_lshlrev_b64 v[6:7], 12, v[4:5]
	v_pk_fma_f32 v[2:3], v[170:171], v[8:9], v[2:3]
	v_lshl_add_u64 v[6:7], v[32:33], 0, v[6:7]
	v_lshlrev_b64 v[8:9], 11, v[4:5]
	global_store_dwordx4 v[6:7], v[0:3], off
	v_cvt_pk_bf16_f32 v6, v0, v1
	v_cvt_pk_bf16_f32 v7, v2, v3
	v_lshrrev_b32_e32 v142, 5, v8
	v_lshl_add_u64 v[8:9], v[36:37], 0, v[8:9]
	global_store_dwordx2 v[8:9], v[6:7], off
	v_mov_b32_e32 v141, 0
	v_dot2c_f32_bf16_e32 v141, v6, v6
	v_dot2c_f32_bf16_e32 v141, v7, v7
	s_nop 4
	v_add_f32_dpp v141, v141, v141 quad_perm:[1,0,3,2] row_mask:0xf bank_mask:0xf
	s_nop 1
	v_add_f32_dpp v141, v141, v141 quad_perm:[2,3,0,1] row_mask:0xf bank_mask:0xf
	s_nop 1
	v_add_f32_dpp v141, v141, v141 row_half_mirror row_mask:0xf bank_mask:0xf
	s_nop 1
	v_add_f32_dpp v141, v141, v141 row_mirror row_mask:0xf bank_mask:0xf
	v_lshl_add_u64 v[144:145], v[142:143], 0, v[146:147]
	global_store_dword v[144:145], v141, off
	s_cbranch_vccnz .LBB0_346
	s_mov_b32 s6, 0xe03f80ff
	v_mul_hi_u32 v164, v4, s6
	v_mad_u64_u32 v[6:7], s[6:7], v5, s6, v[164:165]
	v_mov_b32_e32 v164, v7
	v_mov_b32_e32 v7, v165
	s_mov_b32 s8, 0xfe03f80f
	v_mad_u64_u32 v[6:7], s[6:7], v4, s8, v[6:7]
	v_mov_b32_e32 v6, v7
	v_mov_b32_e32 v7, v165
	v_lshl_add_u64 v[6:7], v[164:165], 0, v[6:7]
	v_mad_u64_u32 v[6:7], s[6:7], v5, s8, v[6:7]
	v_alignbit_b32 v8, v7, v6, 11
	s_movk_i32 s8, 0x810
	v_mad_u64_u32 v[8:9], s[6:7], v8, s8, 0
	v_lshrrev_b32_e32 v10, 11, v7
	v_mad_u32_u24 v9, v10, s8, v9
	v_sub_co_u32_e32 v4, vcc, v4, v8
	s_nop 1
	v_subb_co_u32_e32 v5, vcc, v5, v9, vcc
	v_cmp_lt_u64_e32 vcc, 15, v[4:5]
	s_and_saveexec_b64 s[6:7], vcc
	s_cbranch_execz .LBB0_345
	v_lshrrev_b64 v[6:7], 11, v[6:7]
	v_mov_b32_e32 v8, v165
	v_mov_b32_e32 v9, v6
	v_ashrrev_i64 v[6:7], 21, v[8:9]
	v_add_u32_e32 v164, -16, v4
	v_lshl_add_u64 v[4:5], v[6:7], 0, v[164:165]
	v_lshlrev_b64 v[4:5], 12, v[4:5]
	v_lshl_add_u64 v[4:5], v[34:35], 0, v[4:5]
	global_store_dwordx4 v[4:5], v[0:3], off
